# K-loops: independent MFMAs of each 8-group issued in snake order (consecutive MFMAs share one source operand)
# baseline (speedup 1.0000x reference)
; #define PG8_STAGE(bufoff, gbase, voff) do { _Pragma("unroll") for (int _i = 0; _i < 2; ++_i) \
;         __builtin_amdgcn_global_load_lds((const unsigned*)((const char*)(gbase) + (voff)[_i]), (LAS unsigned*)(lds + (bufoff) + ldsw + _i * 8192), 16, 0, 0); } while (0)
; #define PG8_LDA(dst, b, h) do { _Pragma("unroll") for (int m = 0; m < 4; ++m) _Pragma("unroll") for (int k = 0; k < 2; ++k) dst[m][k] = *(const LAS bf16x8*)(lds + PG8_SA(b, h) + aoff + m * 2048 + k * 1024); } while (0)
; #define PG8_LDB(dst, b, h) do { _Pragma("unroll") for (int n = 0; n < 2; ++n) _Pragma("unroll") for (int k = 0; k < 2; ++k) dst[n][k] = *(const LAS bf16x8*)(lds + PG8_SB(b, h) + boff + n * 2048 + k * 1024); } while (0)
; #define PG8_MMA(ai, bj, At, Bt) do { __builtin_amdgcn_s_setprio(1); _Pragma("unroll") for (int m = 0; m < 4; ++m) _Pragma("unroll") for (int n = 0; n < 2; ++n) _Pragma("unroll") for (int k = 0; k < 2; ++k) \
;         acc[ai][bj][m][n] = __builtin_amdgcn_mfma_f32_16x16x32_bf16(Bt[n][k], At[m][k], acc[ai][bj][m][n], 0, 0, 0); __builtin_amdgcn_s_setprio(0); } while (0)
; #define PG8_WAIT_V(n) asm volatile("s_waitcnt vmcnt(" #n ")" ::: "memory")
; #define PG8_WAIT_L(n) asm volatile("s_waitcnt lgkmcnt(" #n ")" ::: "memory")
; #define PG8_BAR __builtin_amdgcn_s_barrier()
; #define PG8_SCHED __builtin_amdgcn_sched_barrier(0)
; template <class Epi, class Sched, bool ALIGN_EPI>
; __device__ __forceinline__ void gemm_phase(LAS unsigned char* lds, const int wid, const int lda_, const int ldb_, const int K_, const Sched& S, const Epi& E) {
;     ...
;             const char* a1 = cA + (size_t)(t + 1) * kstep;
;             const char* a2 = last ? nA : cA + (size_t)(t + 2) * kstep; const char* b2 = last ? nB : cB + (size_t)(t + 2) * kstep;
;             const char* a3 = a2 + kstep; const char* b3 = b2 + kstep;
;             PG8_LDB(B0, 0, 0); PG8_LDB(B1, 0, 1); PG8_SCHED; PG8_LDA(At, 0, 0); PG8_STAGE(PG8_SA(1, 1), a1 + hstepA, voffA);
;             PG8_WAIT_V(8); PG8_WAIT_L(0); PG8_BAR; PG8_MMA(0, 0, At, B0); PG8_MMA(0, 1, At, B1); PG8_BAR; PG8_SCHED;
;             PG8_LDA(At, 0, 1); PG8_STAGE(PG8_SB(0, 0), b2, voffB); PG8_STAGE(PG8_SB(0, 1), b2 + hstepB, voffB); PG8_STAGE(PG8_SA(0, 0), a2, voffA);
;             PG8_WAIT_V(8); PG8_WAIT_L(0); PG8_BAR; PG8_MMA(1, 0, At, B0); PG8_MMA(1, 1, At, B1); PG8_BAR; PG8_SCHED;
.LBB0_299:
	s_add_u32 s17, s46, s48
	s_addc_u32 s27, s47, s49
	s_add_u32 s17, s17, 0x100
	s_addc_u32 s27, s27, 0
	s_add_u32 s77, s35, s48
	s_addc_u32 s78, s45, s49
	s_add_i32 s80, 0, 0x10000
	s_cmpk_eq_i32 s48, 0xf00
	s_cselect_b32 s51, s31, s27
	s_cselect_b32 s50, s37, s17
	v_add_u32_e32 v141, s80, v135
	s_cselect_b32 s79, s4, s78
	s_cselect_b32 s78, s5, s77
	s_add_i32 s17, 0, 0x14000
	ds_read_b128 v[160:163], v141
	ds_read_b128 v[164:167], v141 offset:1024
	ds_read_b128 v[168:171], v141 offset:2048
	ds_read_b128 v[172:175], v141 offset:3072
	v_add_u32_e32 v141, s17, v135
	ds_read_b128 v[180:183], v141
	ds_read_b128 v[184:187], v141 offset:1024
	ds_read_b128 v[188:191], v141 offset:2048
	ds_read_b128 v[192:195], v141 offset:3072
	v_lshl_add_u64 v[228:229], v[158:159], 0, s[48:49]
	s_add_i32 m0, s16, 0xc000
	ds_read_b128 v[196:199], v139
	ds_read_b128 v[200:203], v139 offset:1024
	ds_read_b128 v[204:207], v139 offset:2048
	ds_read_b128 v[208:211], v139 offset:3072
	ds_read_b128 v[212:215], v139 offset:4096
	ds_read_b128 v[216:219], v139 offset:5120
	ds_read_b128 v[220:223], v139 offset:6144
	ds_read_b128 v[224:227], v139 offset:7168
	global_load_lds_dwordx4 v[228:229], off
	v_lshl_add_u64 v[228:229], v[156:157], 0, s[48:49]
	s_add_i32 m0, s16, 0xe000
	s_nop 0
	global_load_lds_dwordx4 v[228:229], off
	s_waitcnt vmcnt(8)
	s_waitcnt lgkmcnt(0)
	s_barrier
	s_setprio 1
	s_waitcnt lgkmcnt(0)
	v_mfma_f32_16x16x32_bf16 v[124:127], v[160:163], v[196:199], v[124:127]
	v_mfma_f32_16x16x32_bf16 v[120:123], v[168:171], v[196:199], v[120:123]
	v_mfma_f32_16x16x32_bf16 v[112:115], v[168:171], v[204:207], v[112:115]
	v_mfma_f32_16x16x32_bf16 v[116:119], v[160:163], v[204:207], v[116:119]
	v_mfma_f32_16x16x32_bf16 v[100:103], v[160:163], v[212:215], v[100:103]
	v_mfma_f32_16x16x32_bf16 v[96:99], v[168:171], v[212:215], v[96:99]
	v_mfma_f32_16x16x32_bf16 v[80:83], v[168:171], v[220:223], v[80:83]
	v_mfma_f32_16x16x32_bf16 v[84:87], v[160:163], v[220:223], v[84:87]
	v_mfma_f32_16x16x32_bf16 v[124:127], v[164:167], v[200:203], v[124:127]
	v_mfma_f32_16x16x32_bf16 v[120:123], v[172:175], v[200:203], v[120:123]
	v_mfma_f32_16x16x32_bf16 v[112:115], v[172:175], v[208:211], v[112:115]
	v_mfma_f32_16x16x32_bf16 v[116:119], v[164:167], v[208:211], v[116:119]
	v_mfma_f32_16x16x32_bf16 v[100:103], v[164:167], v[216:219], v[100:103]
	v_mfma_f32_16x16x32_bf16 v[96:99], v[172:175], v[216:219], v[96:99]
	v_mfma_f32_16x16x32_bf16 v[80:83], v[172:175], v[224:227], v[80:83]
	v_mfma_f32_16x16x32_bf16 v[84:87], v[164:167], v[224:227], v[84:87]
	s_setprio 0
	s_setprio 1
	v_mfma_f32_16x16x32_bf16 v[108:111], v[180:183], v[196:199], v[108:111]
	v_mfma_f32_16x16x32_bf16 v[104:107], v[188:191], v[196:199], v[104:107]
	v_mfma_f32_16x16x32_bf16 v[88:91], v[188:191], v[204:207], v[88:91]
	v_mfma_f32_16x16x32_bf16 v[92:95], v[180:183], v[204:207], v[92:95]
	v_mfma_f32_16x16x32_bf16 v[76:79], v[180:183], v[212:215], v[76:79]
	v_mfma_f32_16x16x32_bf16 v[72:75], v[188:191], v[212:215], v[72:75]
	v_mfma_f32_16x16x32_bf16 v[64:67], v[188:191], v[220:223], v[64:67]
	v_mfma_f32_16x16x32_bf16 v[68:71], v[180:183], v[220:223], v[68:71]
	v_mfma_f32_16x16x32_bf16 v[108:111], v[184:187], v[200:203], v[108:111]
	v_mfma_f32_16x16x32_bf16 v[104:107], v[192:195], v[200:203], v[104:107]
	v_mfma_f32_16x16x32_bf16 v[88:91], v[192:195], v[208:211], v[88:91]
	v_mfma_f32_16x16x32_bf16 v[92:95], v[184:187], v[208:211], v[92:95]
	v_mfma_f32_16x16x32_bf16 v[76:79], v[184:187], v[216:219], v[76:79]
	v_mfma_f32_16x16x32_bf16 v[72:75], v[192:195], v[216:219], v[72:75]
	v_mfma_f32_16x16x32_bf16 v[64:67], v[192:195], v[224:227], v[64:67]
	v_mfma_f32_16x16x32_bf16 v[68:71], v[184:187], v[224:227], v[68:71]
	s_setprio 0
	s_barrier
	s_add_i32 s27, s80, s3
	v_lshl_add_u64 v[228:229], s[78:79], 0, v[176:177]
	s_mov_b32 m0, s27
	ds_read_b128 v[196:199], v139 offset:16384
	ds_read_b128 v[200:203], v139 offset:17408
	ds_read_b128 v[204:207], v139 offset:18432
	ds_read_b128 v[208:211], v139 offset:19456
	ds_read_b128 v[212:215], v139 offset:20480
	ds_read_b128 v[216:219], v139 offset:21504
	ds_read_b128 v[220:223], v139 offset:22528
	ds_read_b128 v[224:227], v139 offset:23552
	global_load_lds_dwordx4 v[228:229], off
	s_add_i32 m0, s27, 0x2000
	v_lshl_add_u64 v[230:231], s[78:79], 0, v[128:129]
	s_add_u32 s78, s78, s10
	s_addc_u32 s79, s79, s11
	s_add_i32 s17, s17, s3
	global_load_lds_dwordx4 v[230:231], off
	v_lshl_add_u64 v[232:233], s[78:79], 0, v[176:177]
	s_mov_b32 m0, s17
	v_lshl_add_u64 v[234:235], s[78:79], 0, v[128:129]
	global_load_lds_dwordx4 v[232:233], off
	s_add_i32 m0, s17, 0x2000
	v_lshl_add_u64 v[236:237], s[50:51], 0, v[132:133]
	global_load_lds_dwordx4 v[234:235], off
	s_mov_b32 m0, s16
	v_lshl_add_u64 v[246:247], s[50:51], 0, v[130:131]
	global_load_lds_dwordx4 v[236:237], off
	s_mov_b32 m0, s15
	s_nop 0
	global_load_lds_dwordx4 v[246:247], off
	s_waitcnt vmcnt(8)
	s_waitcnt lgkmcnt(0)
	s_barrier
; #define PG8_STAGE(bufoff, gbase, voff) do { _Pragma("unroll") for (int _i = 0; _i < 2; ++_i) \
;         __builtin_amdgcn_global_load_lds((const unsigned*)((const char*)(gbase) + (voff)[_i]), (LAS unsigned*)(lds + (bufoff) + ldsw + _i * 8192), 16, 0, 0); } while (0)
; #define PG8_LDA(dst, b, h) do { _Pragma("unroll") for (int m = 0; m < 4; ++m) _Pragma("unroll") for (int k = 0; k < 2; ++k) dst[m][k] = *(const LAS bf16x8*)(lds + PG8_SA(b, h) + aoff + m * 2048 + k * 1024); } while (0)
; #define PG8_LDB(dst, b, h) do { _Pragma("unroll") for (int n = 0; n < 2; ++n) _Pragma("unroll") for (int k = 0; k < 2; ++k) dst[n][k] = *(const LAS bf16x8*)(lds + PG8_SB(b, h) + boff + n * 2048 + k * 1024); } while (0)
; #define PG8_MMA(ai, bj, At, Bt) do { __builtin_amdgcn_s_setprio(1); _Pragma("unroll") for (int m = 0; m < 4; ++m) _Pragma("unroll") for (int n = 0; n < 2; ++n) _Pragma("unroll") for (int k = 0; k < 2; ++k) \
;         acc[ai][bj][m][n] = __builtin_amdgcn_mfma_f32_16x16x32_bf16(Bt[n][k], At[m][k], acc[ai][bj][m][n], 0, 0, 0); __builtin_amdgcn_s_setprio(0); } while (0)
; #define PG8_WAIT_V(n) asm volatile("s_waitcnt vmcnt(" #n ")" ::: "memory")
; #define PG8_WAIT_L(n) asm volatile("s_waitcnt lgkmcnt(" #n ")" ::: "memory")
; #define PG8_BAR __builtin_amdgcn_s_barrier()
; #define PG8_SCHED __builtin_amdgcn_sched_barrier(0)
; template <class Epi, class Sched, bool ALIGN_EPI>
; __device__ __forceinline__ void gemm_phase(LAS unsigned char* lds, const int wid, const int lda_, const int ldb_, const int K_, const Sched& S, const Epi& E) {
;     ...
;             PG8_WAIT_V(8); PG8_WAIT_L(0); PG8_BAR; PG8_MMA(1, 0, At, B0); PG8_MMA(1, 1, At, B1); PG8_BAR; PG8_SCHED;
;             PG8_LDB(B0, 1, 0); PG8_LDB(B1, 1, 1); PG8_SCHED; PG8_LDA(At, 1, 0); PG8_STAGE(PG8_SA(0, 1), a2 + hstepA, voffA);
;             PG8_WAIT_V(8); PG8_WAIT_L(0); PG8_BAR; PG8_MMA(0, 0, At, B0); PG8_MMA(0, 1, At, B1); PG8_BAR; PG8_SCHED;
	s_setprio 1
	s_waitcnt lgkmcnt(0)
	v_mfma_f32_16x16x32_bf16 v[60:63], v[160:163], v[196:199], v[60:63]
	v_mfma_f32_16x16x32_bf16 v[56:59], v[168:171], v[196:199], v[56:59]
	v_mfma_f32_16x16x32_bf16 v[48:51], v[168:171], v[204:207], v[48:51]
	v_mfma_f32_16x16x32_bf16 v[52:55], v[160:163], v[204:207], v[52:55]
	v_mfma_f32_16x16x32_bf16 v[36:39], v[160:163], v[212:215], v[36:39]
	v_mfma_f32_16x16x32_bf16 v[32:35], v[168:171], v[212:215], v[32:35]
	v_mfma_f32_16x16x32_bf16 v[16:19], v[168:171], v[220:223], v[16:19]
	v_mfma_f32_16x16x32_bf16 v[20:23], v[160:163], v[220:223], v[20:23]
	v_mfma_f32_16x16x32_bf16 v[60:63], v[164:167], v[200:203], v[60:63]
	v_mfma_f32_16x16x32_bf16 v[56:59], v[172:175], v[200:203], v[56:59]
	v_mfma_f32_16x16x32_bf16 v[48:51], v[172:175], v[208:211], v[48:51]
	v_mfma_f32_16x16x32_bf16 v[52:55], v[164:167], v[208:211], v[52:55]
	v_mfma_f32_16x16x32_bf16 v[36:39], v[164:167], v[216:219], v[36:39]
	v_mfma_f32_16x16x32_bf16 v[32:35], v[172:175], v[216:219], v[32:35]
	v_mfma_f32_16x16x32_bf16 v[16:19], v[172:175], v[224:227], v[16:19]
	v_mfma_f32_16x16x32_bf16 v[20:23], v[164:167], v[224:227], v[20:23]
	s_setprio 0
	s_setprio 1
	v_mfma_f32_16x16x32_bf16 v[44:47], v[180:183], v[196:199], v[44:47]
	v_mfma_f32_16x16x32_bf16 v[40:43], v[188:191], v[196:199], v[40:43]
	v_mfma_f32_16x16x32_bf16 v[24:27], v[188:191], v[204:207], v[24:27]
	v_mfma_f32_16x16x32_bf16 v[28:31], v[180:183], v[204:207], v[28:31]
	v_mfma_f32_16x16x32_bf16 v[12:15], v[180:183], v[212:215], v[12:15]
	v_mfma_f32_16x16x32_bf16 v[8:11], v[188:191], v[212:215], v[8:11]
	v_mfma_f32_16x16x32_bf16 v[0:3], v[188:191], v[220:223], v[0:3]
	v_mfma_f32_16x16x32_bf16 v[4:7], v[180:183], v[220:223], v[4:7]
	v_mfma_f32_16x16x32_bf16 v[44:47], v[184:187], v[200:203], v[44:47]
	v_mfma_f32_16x16x32_bf16 v[40:43], v[192:195], v[200:203], v[40:43]
	v_mfma_f32_16x16x32_bf16 v[24:27], v[192:195], v[208:211], v[24:27]
	v_mfma_f32_16x16x32_bf16 v[28:31], v[184:187], v[208:211], v[28:31]
	v_mfma_f32_16x16x32_bf16 v[12:15], v[184:187], v[216:219], v[12:15]
	v_mfma_f32_16x16x32_bf16 v[8:11], v[192:195], v[216:219], v[8:11]
	v_mfma_f32_16x16x32_bf16 v[0:3], v[192:195], v[224:227], v[0:3]
	v_mfma_f32_16x16x32_bf16 v[4:7], v[184:187], v[224:227], v[4:7]
	s_setprio 0
	s_barrier
	s_add_i32 s17, 0, 0x18000
	v_add_u32_e32 v141, s17, v135
	s_add_i32 s27, 0, 0x1c000
	ds_read_b128 v[160:163], v141
	ds_read_b128 v[164:167], v141 offset:1024
	ds_read_b128 v[168:171], v141 offset:2048
	ds_read_b128 v[172:175], v141 offset:3072
	v_add_u32_e32 v141, s27, v135
	ds_read_b128 v[180:183], v141
	ds_read_b128 v[184:187], v141 offset:1024
	ds_read_b128 v[188:191], v141 offset:2048
	ds_read_b128 v[192:195], v141 offset:3072
	s_add_u32 s50, s50, s0
	s_addc_u32 s51, s51, s1
	s_mov_b32 m0, s26
	v_lshl_add_u64 v[248:249], s[50:51], 0, v[132:133]
	ds_read_b128 v[196:199], v139 offset:32768
	ds_read_b128 v[200:203], v139 offset:33792
	ds_read_b128 v[204:207], v139 offset:34816
	ds_read_b128 v[208:211], v139 offset:35840
	ds_read_b128 v[212:215], v139 offset:36864
	ds_read_b128 v[216:219], v139 offset:37888
	ds_read_b128 v[220:223], v139 offset:38912
	ds_read_b128 v[224:227], v139 offset:39936
	global_load_lds_dwordx4 v[248:249], off
	v_lshl_add_u64 v[248:249], s[50:51], 0, v[130:131]
	s_mov_b32 m0, s72
	s_nop 0
	global_load_lds_dwordx4 v[248:249], off
	s_waitcnt vmcnt(8)
	s_waitcnt lgkmcnt(0)
	s_barrier
	s_setprio 1
	s_waitcnt lgkmcnt(0)
	v_mfma_f32_16x16x32_bf16 v[124:127], v[160:163], v[196:199], v[124:127]
	v_mfma_f32_16x16x32_bf16 v[120:123], v[168:171], v[196:199], v[120:123]
	v_mfma_f32_16x16x32_bf16 v[112:115], v[168:171], v[204:207], v[112:115]
	v_mfma_f32_16x16x32_bf16 v[116:119], v[160:163], v[204:207], v[116:119]
	v_mfma_f32_16x16x32_bf16 v[100:103], v[160:163], v[212:215], v[100:103]
	v_mfma_f32_16x16x32_bf16 v[96:99], v[168:171], v[212:215], v[96:99]
	v_mfma_f32_16x16x32_bf16 v[80:83], v[168:171], v[220:223], v[80:83]
	v_mfma_f32_16x16x32_bf16 v[84:87], v[160:163], v[220:223], v[84:87]
	v_mfma_f32_16x16x32_bf16 v[124:127], v[164:167], v[200:203], v[124:127]
	v_mfma_f32_16x16x32_bf16 v[120:123], v[172:175], v[200:203], v[120:123]
	v_mfma_f32_16x16x32_bf16 v[112:115], v[172:175], v[208:211], v[112:115]
	v_mfma_f32_16x16x32_bf16 v[116:119], v[164:167], v[208:211], v[116:119]
	v_mfma_f32_16x16x32_bf16 v[100:103], v[164:167], v[216:219], v[100:103]
	v_mfma_f32_16x16x32_bf16 v[96:99], v[172:175], v[216:219], v[96:99]
	v_mfma_f32_16x16x32_bf16 v[80:83], v[172:175], v[224:227], v[80:83]
	v_mfma_f32_16x16x32_bf16 v[84:87], v[164:167], v[224:227], v[84:87]
	s_setprio 0
	s_setprio 1
	v_mfma_f32_16x16x32_bf16 v[108:111], v[180:183], v[196:199], v[108:111]
	v_mfma_f32_16x16x32_bf16 v[104:107], v[188:191], v[196:199], v[104:107]
	v_mfma_f32_16x16x32_bf16 v[88:91], v[188:191], v[204:207], v[88:91]
	v_mfma_f32_16x16x32_bf16 v[92:95], v[180:183], v[204:207], v[92:95]
	v_mfma_f32_16x16x32_bf16 v[76:79], v[180:183], v[212:215], v[76:79]
	v_mfma_f32_16x16x32_bf16 v[72:75], v[188:191], v[212:215], v[72:75]
	v_mfma_f32_16x16x32_bf16 v[64:67], v[188:191], v[220:223], v[64:67]
	v_mfma_f32_16x16x32_bf16 v[68:71], v[180:183], v[220:223], v[68:71]
	v_mfma_f32_16x16x32_bf16 v[108:111], v[184:187], v[200:203], v[108:111]
	v_mfma_f32_16x16x32_bf16 v[104:107], v[192:195], v[200:203], v[104:107]
	v_mfma_f32_16x16x32_bf16 v[88:91], v[192:195], v[208:211], v[88:91]
	v_mfma_f32_16x16x32_bf16 v[92:95], v[184:187], v[208:211], v[92:95]
	v_mfma_f32_16x16x32_bf16 v[76:79], v[184:187], v[216:219], v[76:79]
	v_mfma_f32_16x16x32_bf16 v[72:75], v[192:195], v[216:219], v[72:75]
	v_mfma_f32_16x16x32_bf16 v[64:67], v[192:195], v[224:227], v[64:67]
	v_mfma_f32_16x16x32_bf16 v[68:71], v[184:187], v[224:227], v[68:71]
	s_setprio 0
	s_barrier
; #define PG8_STAGE(bufoff, gbase, voff) do { _Pragma("unroll") for (int _i = 0; _i < 2; ++_i) \
;         __builtin_amdgcn_global_load_lds((const unsigned*)((const char*)(gbase) + (voff)[_i]), (LAS unsigned*)(lds + (bufoff) + ldsw + _i * 8192), 16, 0, 0); } while (0)
; #define PG8_LDA(dst, b, h) do { _Pragma("unroll") for (int m = 0; m < 4; ++m) _Pragma("unroll") for (int k = 0; k < 2; ++k) dst[m][k] = *(const LAS bf16x8*)(lds + PG8_SA(b, h) + aoff + m * 2048 + k * 1024); } while (0)
; #define PG8_MMA(ai, bj, At, Bt) do { __builtin_amdgcn_s_setprio(1); _Pragma("unroll") for (int m = 0; m < 4; ++m) _Pragma("unroll") for (int n = 0; n < 2; ++n) _Pragma("unroll") for (int k = 0; k < 2; ++k) \
;         acc[ai][bj][m][n] = __builtin_amdgcn_mfma_f32_16x16x32_bf16(Bt[n][k], At[m][k], acc[ai][bj][m][n], 0, 0, 0); __builtin_amdgcn_s_setprio(0); } while (0)
; #define PG8_WAIT_V(n) asm volatile("s_waitcnt vmcnt(" #n ")" ::: "memory")
; #define PG8_WAIT_L(n) asm volatile("s_waitcnt lgkmcnt(" #n ")" ::: "memory")
; #define PG8_BAR __builtin_amdgcn_s_barrier()
; #define PG8_SCHED __builtin_amdgcn_sched_barrier(0)
; template <class Epi, class Sched, bool ALIGN_EPI>
; __device__ __forceinline__ void gemm_phase(LAS unsigned char* lds, const int wid, const int lda_, const int ldb_, const int K_, const Sched& S, const Epi& E) {
;     ...
;             PG8_LDA(At, 1, 1); PG8_STAGE(PG8_SB(1, 0), b3, voffB); PG8_STAGE(PG8_SB(1, 1), b3 + hstepB, voffB); PG8_STAGE(PG8_SA(1, 0), a3, voffA);
;             PG8_WAIT_V(8); PG8_WAIT_L(0); PG8_BAR; PG8_MMA(1, 0, At, B0); PG8_MMA(1, 1, At, B1); PG8_BAR; PG8_SCHED;
;         }
;     __device__ __forceinline__ void out(const pg8::Unit& u, char*& o, int& ldo, int& kind) const {
;         if (u.pn < 24) { o = (char*)ws + WS_XBCP + ((size_t)u.pm * 256 * XBC + (size_t)u.pn * 256) * 2; ldo = XBC; kind = 0; }
;         else if (u.pn < 40) { o = (char*)ws + WS_Z + ((size_t)u.pm * 256 * DI + (size_t)(u.pn - 24) * 256) * 2; ldo = DI; kind = 0; }
;         else { o = (char*)ws + WS_DT + (size_t)u.pm * 256 * 128 * 4; ldo = 128; kind = 1; } }
	s_add_i32 s17, s17, s3
	v_lshl_add_u64 v[228:229], v[228:229], 0, s[24:25]
	s_mov_b32 m0, s17
	ds_read_b128 v[196:199], v139 offset:49152
	ds_read_b128 v[200:203], v139 offset:50176
	ds_read_b128 v[204:207], v139 offset:51200
	ds_read_b128 v[208:211], v139 offset:52224
	ds_read_b128 v[212:215], v139 offset:53248
	ds_read_b128 v[216:219], v139 offset:54272
	ds_read_b128 v[220:223], v139 offset:55296
	ds_read_b128 v[224:227], v139 offset:56320
	global_load_lds_dwordx4 v[228:229], off
	v_lshl_add_u64 v[228:229], v[230:231], 0, s[24:25]
	s_add_i32 m0, s17, 0x2000
	s_add_i32 s17, s27, s3
	global_load_lds_dwordx4 v[228:229], off
	v_lshl_add_u64 v[228:229], v[232:233], 0, s[24:25]
	s_mov_b32 m0, s17
	s_nop 0
	global_load_lds_dwordx4 v[228:229], off
	v_lshl_add_u64 v[228:229], v[234:235], 0, s[24:25]
	s_add_i32 m0, s17, 0x2000
	s_nop 0
	global_load_lds_dwordx4 v[228:229], off
	v_lshl_add_u64 v[228:229], v[236:237], 0, s[24:25]
	s_mov_b32 m0, s73
	s_nop 0
	global_load_lds_dwordx4 v[228:229], off
	v_lshl_add_u64 v[228:229], v[246:247], 0, s[24:25]
	s_mov_b32 m0, s74
	s_nop 0
	global_load_lds_dwordx4 v[228:229], off
	s_waitcnt vmcnt(8)
	s_waitcnt lgkmcnt(0)
	s_barrier
	s_setprio 1
	s_waitcnt lgkmcnt(0)
	v_mfma_f32_16x16x32_bf16 v[60:63], v[160:163], v[196:199], v[60:63]
	v_mfma_f32_16x16x32_bf16 v[56:59], v[168:171], v[196:199], v[56:59]
	v_mfma_f32_16x16x32_bf16 v[48:51], v[168:171], v[204:207], v[48:51]
	v_mfma_f32_16x16x32_bf16 v[52:55], v[160:163], v[204:207], v[52:55]
	v_mfma_f32_16x16x32_bf16 v[36:39], v[160:163], v[212:215], v[36:39]
	v_mfma_f32_16x16x32_bf16 v[32:35], v[168:171], v[212:215], v[32:35]
	v_mfma_f32_16x16x32_bf16 v[16:19], v[168:171], v[220:223], v[16:19]
	v_mfma_f32_16x16x32_bf16 v[20:23], v[160:163], v[220:223], v[20:23]
	v_mfma_f32_16x16x32_bf16 v[60:63], v[164:167], v[200:203], v[60:63]
	v_mfma_f32_16x16x32_bf16 v[56:59], v[172:175], v[200:203], v[56:59]
	v_mfma_f32_16x16x32_bf16 v[48:51], v[172:175], v[208:211], v[48:51]
	v_mfma_f32_16x16x32_bf16 v[52:55], v[164:167], v[208:211], v[52:55]
	v_mfma_f32_16x16x32_bf16 v[36:39], v[164:167], v[216:219], v[36:39]
	v_mfma_f32_16x16x32_bf16 v[32:35], v[172:175], v[216:219], v[32:35]
	v_mfma_f32_16x16x32_bf16 v[16:19], v[172:175], v[224:227], v[16:19]
	v_mfma_f32_16x16x32_bf16 v[20:23], v[164:167], v[224:227], v[20:23]
	s_setprio 0
	s_setprio 1
	v_mfma_f32_16x16x32_bf16 v[44:47], v[180:183], v[196:199], v[44:47]
	v_mfma_f32_16x16x32_bf16 v[40:43], v[188:191], v[196:199], v[40:43]
	v_mfma_f32_16x16x32_bf16 v[24:27], v[188:191], v[204:207], v[24:27]
	v_mfma_f32_16x16x32_bf16 v[28:31], v[180:183], v[204:207], v[28:31]
	v_mfma_f32_16x16x32_bf16 v[12:15], v[180:183], v[212:215], v[12:15]
	v_mfma_f32_16x16x32_bf16 v[8:11], v[188:191], v[212:215], v[8:11]
	v_mfma_f32_16x16x32_bf16 v[0:3], v[188:191], v[220:223], v[0:3]
	v_mfma_f32_16x16x32_bf16 v[4:7], v[180:183], v[220:223], v[4:7]
	v_mfma_f32_16x16x32_bf16 v[44:47], v[184:187], v[200:203], v[44:47]
	v_mfma_f32_16x16x32_bf16 v[40:43], v[192:195], v[200:203], v[40:43]
	v_mfma_f32_16x16x32_bf16 v[24:27], v[192:195], v[208:211], v[24:27]
	v_mfma_f32_16x16x32_bf16 v[28:31], v[184:187], v[208:211], v[28:31]
	v_mfma_f32_16x16x32_bf16 v[12:15], v[184:187], v[216:219], v[12:15]
	v_mfma_f32_16x16x32_bf16 v[8:11], v[192:195], v[216:219], v[8:11]
	v_mfma_f32_16x16x32_bf16 v[0:3], v[192:195], v[224:227], v[0:3]
	v_mfma_f32_16x16x32_bf16 v[4:7], v[184:187], v[224:227], v[4:7]
	s_setprio 0
	s_barrier
	s_add_i32 s76, s76, 2
	s_add_u32 s48, s48, 0x100
	s_addc_u32 s49, s49, 0
	s_cmp_gt_u32 s76, 29
	s_cbranch_scc0 .LBB0_299
	s_ashr_i32 s45, s44, 31
	s_cmp_gt_i32 s30, 23
	s_mov_b64 s[48:49], -1
	s_cbranch_scc0 .LBB0_305
	s_cmp_gt_u32 s30, 39
	s_mov_b64 s[4:5], -1
	s_cbranch_scc0 .LBB0_303
	s_lshl_b64 s[4:5], s[44:45], 17
	v_readlane_b32 s46, v252, 60
	v_readlane_b32 s47, v252, 61
	s_add_u32 s46, s46, s4
	s_addc_u32 s47, s47, s5
	s_mov_b64 s[4:5], 0

; #define PG8_STAGE(bufoff, gbase, voff) do { _Pragma("unroll") for (int _i = 0; _i < 2; ++_i) \
;         __builtin_amdgcn_global_load_lds((const unsigned*)((const char*)(gbase) + (voff)[_i]), (LAS unsigned*)(lds + (bufoff) + ldsw + _i * 8192), 16, 0, 0); } while (0)
; #define PG8_LDA(dst, b, h) do { _Pragma("unroll") for (int m = 0; m < 4; ++m) _Pragma("unroll") for (int k = 0; k < 2; ++k) dst[m][k] = *(const LAS bf16x8*)(lds + PG8_SA(b, h) + aoff + m * 2048 + k * 1024); } while (0)
; #define PG8_LDB(dst, b, h) do { _Pragma("unroll") for (int n = 0; n < 2; ++n) _Pragma("unroll") for (int k = 0; k < 2; ++k) dst[n][k] = *(const LAS bf16x8*)(lds + PG8_SB(b, h) + boff + n * 2048 + k * 1024); } while (0)
; #define PG8_MMA(ai, bj, At, Bt) do { __builtin_amdgcn_s_setprio(1); _Pragma("unroll") for (int m = 0; m < 4; ++m) _Pragma("unroll") for (int n = 0; n < 2; ++n) _Pragma("unroll") for (int k = 0; k < 2; ++k) \
;         acc[ai][bj][m][n] = __builtin_amdgcn_mfma_f32_16x16x32_bf16(Bt[n][k], At[m][k], acc[ai][bj][m][n], 0, 0, 0); __builtin_amdgcn_s_setprio(0); } while (0)
; #define PG8_WAIT_V(n) asm volatile("s_waitcnt vmcnt(" #n ")" ::: "memory")
; #define PG8_WAIT_L(n) asm volatile("s_waitcnt lgkmcnt(" #n ")" ::: "memory")
; #define PG8_BAR __builtin_amdgcn_s_barrier()
; #define PG8_SCHED __builtin_amdgcn_sched_barrier(0)
; template <class Epi, class Sched, bool ALIGN_EPI>
; __device__ __forceinline__ void gemm_phase(LAS unsigned char* lds, const int wid, const int lda_, const int ldb_, const int K_, const Sched& S, const Epi& E) {
;     ...
;             PG8_LDB(B0, 0, 0); PG8_LDB(B1, 0, 1); PG8_SCHED; PG8_LDA(At, 0, 0); PG8_STAGE(PG8_SA(1, 1), a1 + hstepA, voffA);
;             PG8_WAIT_V(8); PG8_WAIT_L(0); PG8_BAR; PG8_MMA(0, 0, At, B0); PG8_MMA(0, 1, At, B1); PG8_BAR; PG8_SCHED;
;             PG8_LDA(At, 0, 1); PG8_STAGE(PG8_SB(0, 0), b2, voffB); PG8_STAGE(PG8_SB(0, 1), b2 + hstepB, voffB); PG8_STAGE(PG8_SA(0, 0), a2, voffA);
;             PG8_WAIT_V(8); PG8_WAIT_L(0); PG8_BAR; PG8_MMA(1, 0, At, B0); PG8_MMA(1, 1, At, B1); PG8_BAR; PG8_SCHED;
.LBB0_671:
	s_add_i32 s78, s77, 2
	s_add_u32 s17, s94, 0x80
	s_addc_u32 s27, s95, 0
	s_add_i32 s79, 0, 0x10000
	s_cmp_eq_u32 s41, s77
	s_cselect_b32 s97, s37, s27
	s_cselect_b32 s96, s39, s17
	v_add_u32_e32 v141, s79, v135
	s_cselect_b32 s81, s4, s76
	s_cselect_b32 s80, s5, s43
	s_add_i32 s17, 0, 0x14000
	ds_read_b128 v[156:159], v141
	ds_read_b128 v[160:163], v141 offset:1024
	ds_read_b128 v[164:167], v141 offset:2048
	ds_read_b128 v[168:171], v141 offset:3072
	v_add_u32_e32 v141, s17, v135
	ds_read_b128 v[172:175], v141
	ds_read_b128 v[180:183], v141 offset:1024
	ds_read_b128 v[184:187], v141 offset:2048
	ds_read_b128 v[188:191], v141 offset:3072
	v_lshl_add_u64 v[224:225], s[94:95], 0, v[152:153]
	s_add_i32 m0, s16, 0xc000
	ds_read_b128 v[192:195], v139
	ds_read_b128 v[196:199], v139 offset:1024
	ds_read_b128 v[200:203], v139 offset:2048
	ds_read_b128 v[204:207], v139 offset:3072
	ds_read_b128 v[208:211], v139 offset:4096
	ds_read_b128 v[212:215], v139 offset:5120
	ds_read_b128 v[216:219], v139 offset:6144
	ds_read_b128 v[220:223], v139 offset:7168
	global_load_lds_dwordx4 v[224:225], off
	v_lshl_add_u64 v[224:225], s[94:95], 0, v[154:155]
	s_add_i32 m0, s16, 0xe000
	s_nop 0
	global_load_lds_dwordx4 v[224:225], off
	s_waitcnt vmcnt(8)
	s_waitcnt lgkmcnt(0)
	s_barrier
	s_setprio 1
	s_waitcnt lgkmcnt(0)
	v_mfma_f32_16x16x32_bf16 v[124:127], v[156:159], v[192:195], v[124:127]
	v_mfma_f32_16x16x32_bf16 v[120:123], v[164:167], v[192:195], v[120:123]
	v_mfma_f32_16x16x32_bf16 v[112:115], v[164:167], v[200:203], v[112:115]
	v_mfma_f32_16x16x32_bf16 v[116:119], v[156:159], v[200:203], v[116:119]
	v_mfma_f32_16x16x32_bf16 v[100:103], v[156:159], v[208:211], v[100:103]
	v_mfma_f32_16x16x32_bf16 v[96:99], v[164:167], v[208:211], v[96:99]
	v_mfma_f32_16x16x32_bf16 v[80:83], v[164:167], v[216:219], v[80:83]
	v_mfma_f32_16x16x32_bf16 v[84:87], v[156:159], v[216:219], v[84:87]
	v_mfma_f32_16x16x32_bf16 v[124:127], v[160:163], v[196:199], v[124:127]
	v_mfma_f32_16x16x32_bf16 v[120:123], v[168:171], v[196:199], v[120:123]
	v_mfma_f32_16x16x32_bf16 v[112:115], v[168:171], v[204:207], v[112:115]
	v_mfma_f32_16x16x32_bf16 v[116:119], v[160:163], v[204:207], v[116:119]
	v_mfma_f32_16x16x32_bf16 v[100:103], v[160:163], v[212:215], v[100:103]
	v_mfma_f32_16x16x32_bf16 v[96:99], v[168:171], v[212:215], v[96:99]
	v_mfma_f32_16x16x32_bf16 v[80:83], v[168:171], v[220:223], v[80:83]
	v_mfma_f32_16x16x32_bf16 v[84:87], v[160:163], v[220:223], v[84:87]
	s_setprio 0
	s_setprio 1
	v_mfma_f32_16x16x32_bf16 v[108:111], v[172:175], v[192:195], v[108:111]
	v_mfma_f32_16x16x32_bf16 v[104:107], v[184:187], v[192:195], v[104:107]
	v_mfma_f32_16x16x32_bf16 v[88:91], v[184:187], v[200:203], v[88:91]
	v_mfma_f32_16x16x32_bf16 v[92:95], v[172:175], v[200:203], v[92:95]
	v_mfma_f32_16x16x32_bf16 v[76:79], v[172:175], v[208:211], v[76:79]
	v_mfma_f32_16x16x32_bf16 v[72:75], v[184:187], v[208:211], v[72:75]
	v_mfma_f32_16x16x32_bf16 v[64:67], v[184:187], v[216:219], v[64:67]
	v_mfma_f32_16x16x32_bf16 v[68:71], v[172:175], v[216:219], v[68:71]
	v_mfma_f32_16x16x32_bf16 v[108:111], v[180:183], v[196:199], v[108:111]
	v_mfma_f32_16x16x32_bf16 v[104:107], v[188:191], v[196:199], v[104:107]
	v_mfma_f32_16x16x32_bf16 v[88:91], v[188:191], v[204:207], v[88:91]
	v_mfma_f32_16x16x32_bf16 v[92:95], v[180:183], v[204:207], v[92:95]
	v_mfma_f32_16x16x32_bf16 v[76:79], v[180:183], v[212:215], v[76:79]
	v_mfma_f32_16x16x32_bf16 v[72:75], v[188:191], v[212:215], v[72:75]
	v_mfma_f32_16x16x32_bf16 v[64:67], v[188:191], v[220:223], v[64:67]
	v_mfma_f32_16x16x32_bf16 v[68:71], v[180:183], v[220:223], v[68:71]
	s_setprio 0
	s_barrier
	s_add_i32 s27, s79, s3
	v_lshl_add_u64 v[224:225], s[80:81], 0, v[176:177]
	s_mov_b32 m0, s27
	ds_read_b128 v[192:195], v139 offset:16384
	ds_read_b128 v[196:199], v139 offset:17408
	ds_read_b128 v[200:203], v139 offset:18432
	ds_read_b128 v[204:207], v139 offset:19456
	ds_read_b128 v[208:211], v139 offset:20480
	ds_read_b128 v[212:215], v139 offset:21504
	ds_read_b128 v[216:219], v139 offset:22528
	ds_read_b128 v[220:223], v139 offset:23552
	global_load_lds_dwordx4 v[224:225], off
	s_add_i32 m0, s27, 0x2000
	v_lshl_add_u64 v[226:227], s[80:81], 0, v[132:133]
	s_add_u32 s80, s80, s30
	s_addc_u32 s81, s81, s31
	s_add_i32 s17, s17, s3
	global_load_lds_dwordx4 v[226:227], off
	v_lshl_add_u64 v[228:229], s[80:81], 0, v[176:177]
	s_mov_b32 m0, s17
	v_lshl_add_u64 v[230:231], s[80:81], 0, v[132:133]
	global_load_lds_dwordx4 v[228:229], off
	s_add_i32 m0, s17, 0x2000
	v_lshl_add_u64 v[232:233], s[96:97], 0, v[128:129]
	global_load_lds_dwordx4 v[230:231], off
	s_mov_b32 m0, s16
	v_lshl_add_u64 v[234:235], s[96:97], 0, v[130:131]
	global_load_lds_dwordx4 v[232:233], off
	s_mov_b32 m0, s14
	s_nop 0
	global_load_lds_dwordx4 v[234:235], off
	s_waitcnt vmcnt(8)
	s_waitcnt lgkmcnt(0)
	s_barrier
; #define PG8_STAGE(bufoff, gbase, voff) do { _Pragma("unroll") for (int _i = 0; _i < 2; ++_i) \
;         __builtin_amdgcn_global_load_lds((const unsigned*)((const char*)(gbase) + (voff)[_i]), (LAS unsigned*)(lds + (bufoff) + ldsw + _i * 8192), 16, 0, 0); } while (0)
; #define PG8_LDA(dst, b, h) do { _Pragma("unroll") for (int m = 0; m < 4; ++m) _Pragma("unroll") for (int k = 0; k < 2; ++k) dst[m][k] = *(const LAS bf16x8*)(lds + PG8_SA(b, h) + aoff + m * 2048 + k * 1024); } while (0)
; #define PG8_LDB(dst, b, h) do { _Pragma("unroll") for (int n = 0; n < 2; ++n) _Pragma("unroll") for (int k = 0; k < 2; ++k) dst[n][k] = *(const LAS bf16x8*)(lds + PG8_SB(b, h) + boff + n * 2048 + k * 1024); } while (0)
; #define PG8_MMA(ai, bj, At, Bt) do { __builtin_amdgcn_s_setprio(1); _Pragma("unroll") for (int m = 0; m < 4; ++m) _Pragma("unroll") for (int n = 0; n < 2; ++n) _Pragma("unroll") for (int k = 0; k < 2; ++k) \
;         acc[ai][bj][m][n] = __builtin_amdgcn_mfma_f32_16x16x32_bf16(Bt[n][k], At[m][k], acc[ai][bj][m][n], 0, 0, 0); __builtin_amdgcn_s_setprio(0); } while (0)
; #define PG8_WAIT_V(n) asm volatile("s_waitcnt vmcnt(" #n ")" ::: "memory")
; #define PG8_WAIT_L(n) asm volatile("s_waitcnt lgkmcnt(" #n ")" ::: "memory")
; #define PG8_BAR __builtin_amdgcn_s_barrier()
; #define PG8_SCHED __builtin_amdgcn_sched_barrier(0)
; template <class Epi, class Sched, bool ALIGN_EPI>
; __device__ __forceinline__ void gemm_phase(LAS unsigned char* lds, const int wid, const int lda_, const int ldb_, const int K_, const Sched& S, const Epi& E) {
;     ...
;             PG8_WAIT_V(8); PG8_WAIT_L(0); PG8_BAR; PG8_MMA(1, 0, At, B0); PG8_MMA(1, 1, At, B1); PG8_BAR; PG8_SCHED;
;             PG8_LDB(B0, 1, 0); PG8_LDB(B1, 1, 1); PG8_SCHED; PG8_LDA(At, 1, 0); PG8_STAGE(PG8_SA(0, 1), a2 + hstepA, voffA);
;             PG8_WAIT_V(8); PG8_WAIT_L(0); PG8_BAR; PG8_MMA(0, 0, At, B0); PG8_MMA(0, 1, At, B1); PG8_BAR; PG8_SCHED;
	s_setprio 1
	s_waitcnt lgkmcnt(0)
	v_mfma_f32_16x16x32_bf16 v[60:63], v[156:159], v[192:195], v[60:63]
	v_mfma_f32_16x16x32_bf16 v[56:59], v[164:167], v[192:195], v[56:59]
	v_mfma_f32_16x16x32_bf16 v[48:51], v[164:167], v[200:203], v[48:51]
	v_mfma_f32_16x16x32_bf16 v[52:55], v[156:159], v[200:203], v[52:55]
	v_mfma_f32_16x16x32_bf16 v[36:39], v[156:159], v[208:211], v[36:39]
	v_mfma_f32_16x16x32_bf16 v[32:35], v[164:167], v[208:211], v[32:35]
	v_mfma_f32_16x16x32_bf16 v[16:19], v[164:167], v[216:219], v[16:19]
	v_mfma_f32_16x16x32_bf16 v[20:23], v[156:159], v[216:219], v[20:23]
	v_mfma_f32_16x16x32_bf16 v[60:63], v[160:163], v[196:199], v[60:63]
	v_mfma_f32_16x16x32_bf16 v[56:59], v[168:171], v[196:199], v[56:59]
	v_mfma_f32_16x16x32_bf16 v[48:51], v[168:171], v[204:207], v[48:51]
	v_mfma_f32_16x16x32_bf16 v[52:55], v[160:163], v[204:207], v[52:55]
	v_mfma_f32_16x16x32_bf16 v[36:39], v[160:163], v[212:215], v[36:39]
	v_mfma_f32_16x16x32_bf16 v[32:35], v[168:171], v[212:215], v[32:35]
	v_mfma_f32_16x16x32_bf16 v[16:19], v[168:171], v[220:223], v[16:19]
	v_mfma_f32_16x16x32_bf16 v[20:23], v[160:163], v[220:223], v[20:23]
	s_setprio 0
	s_setprio 1
	v_mfma_f32_16x16x32_bf16 v[44:47], v[172:175], v[192:195], v[44:47]
	v_mfma_f32_16x16x32_bf16 v[40:43], v[184:187], v[192:195], v[40:43]
	v_mfma_f32_16x16x32_bf16 v[24:27], v[184:187], v[200:203], v[24:27]
	v_mfma_f32_16x16x32_bf16 v[28:31], v[172:175], v[200:203], v[28:31]
	v_mfma_f32_16x16x32_bf16 v[12:15], v[172:175], v[208:211], v[12:15]
	v_mfma_f32_16x16x32_bf16 v[8:11], v[184:187], v[208:211], v[8:11]
	v_mfma_f32_16x16x32_bf16 v[0:3], v[184:187], v[216:219], v[0:3]
	v_mfma_f32_16x16x32_bf16 v[4:7], v[172:175], v[216:219], v[4:7]
	v_mfma_f32_16x16x32_bf16 v[44:47], v[180:183], v[196:199], v[44:47]
	v_mfma_f32_16x16x32_bf16 v[40:43], v[188:191], v[196:199], v[40:43]
	v_mfma_f32_16x16x32_bf16 v[24:27], v[188:191], v[204:207], v[24:27]
	v_mfma_f32_16x16x32_bf16 v[28:31], v[180:183], v[204:207], v[28:31]
	v_mfma_f32_16x16x32_bf16 v[12:15], v[180:183], v[212:215], v[12:15]
	v_mfma_f32_16x16x32_bf16 v[8:11], v[188:191], v[212:215], v[8:11]
	v_mfma_f32_16x16x32_bf16 v[0:3], v[188:191], v[220:223], v[0:3]
	v_mfma_f32_16x16x32_bf16 v[4:7], v[180:183], v[220:223], v[4:7]
	s_setprio 0
	s_barrier
	s_add_i32 s17, 0, 0x18000
	v_add_u32_e32 v141, s17, v135
	s_add_i32 s27, 0, 0x1c000
	ds_read_b128 v[156:159], v141
	ds_read_b128 v[160:163], v141 offset:1024
	ds_read_b128 v[164:167], v141 offset:2048
	ds_read_b128 v[168:171], v141 offset:3072
	v_add_u32_e32 v141, s27, v135
	ds_read_b128 v[172:175], v141
	ds_read_b128 v[180:183], v141 offset:1024
	ds_read_b128 v[184:187], v141 offset:2048
	ds_read_b128 v[188:191], v141 offset:3072
	s_add_u32 s80, s96, s10
	s_addc_u32 s81, s97, s11
	s_mov_b32 m0, s15
	v_lshl_add_u64 v[236:237], s[80:81], 0, v[128:129]
	ds_read_b128 v[192:195], v139 offset:32768
	ds_read_b128 v[196:199], v139 offset:33792
	ds_read_b128 v[200:203], v139 offset:34816
	ds_read_b128 v[204:207], v139 offset:35840
	ds_read_b128 v[208:211], v139 offset:36864
	ds_read_b128 v[212:215], v139 offset:37888
	ds_read_b128 v[216:219], v139 offset:38912
	ds_read_b128 v[220:223], v139 offset:39936
	global_load_lds_dwordx4 v[236:237], off
	v_lshl_add_u64 v[236:237], s[80:81], 0, v[130:131]
	s_mov_b32 m0, s26
	s_nop 0
	global_load_lds_dwordx4 v[236:237], off
	s_waitcnt vmcnt(8)
	s_waitcnt lgkmcnt(0)
	s_barrier
	s_setprio 1
	s_waitcnt lgkmcnt(0)
	v_mfma_f32_16x16x32_bf16 v[124:127], v[156:159], v[192:195], v[124:127]
	v_mfma_f32_16x16x32_bf16 v[120:123], v[164:167], v[192:195], v[120:123]
	v_mfma_f32_16x16x32_bf16 v[112:115], v[164:167], v[200:203], v[112:115]
	v_mfma_f32_16x16x32_bf16 v[116:119], v[156:159], v[200:203], v[116:119]
	v_mfma_f32_16x16x32_bf16 v[100:103], v[156:159], v[208:211], v[100:103]
	v_mfma_f32_16x16x32_bf16 v[96:99], v[164:167], v[208:211], v[96:99]
	v_mfma_f32_16x16x32_bf16 v[80:83], v[164:167], v[216:219], v[80:83]
	v_mfma_f32_16x16x32_bf16 v[84:87], v[156:159], v[216:219], v[84:87]
	v_mfma_f32_16x16x32_bf16 v[124:127], v[160:163], v[196:199], v[124:127]
	v_mfma_f32_16x16x32_bf16 v[120:123], v[168:171], v[196:199], v[120:123]
	v_mfma_f32_16x16x32_bf16 v[112:115], v[168:171], v[204:207], v[112:115]
	v_mfma_f32_16x16x32_bf16 v[116:119], v[160:163], v[204:207], v[116:119]
	v_mfma_f32_16x16x32_bf16 v[100:103], v[160:163], v[212:215], v[100:103]
	v_mfma_f32_16x16x32_bf16 v[96:99], v[168:171], v[212:215], v[96:99]
	v_mfma_f32_16x16x32_bf16 v[80:83], v[168:171], v[220:223], v[80:83]
	v_mfma_f32_16x16x32_bf16 v[84:87], v[160:163], v[220:223], v[84:87]
	s_setprio 0
	s_setprio 1
	v_mfma_f32_16x16x32_bf16 v[108:111], v[172:175], v[192:195], v[108:111]
	v_mfma_f32_16x16x32_bf16 v[104:107], v[184:187], v[192:195], v[104:107]
	v_mfma_f32_16x16x32_bf16 v[88:91], v[184:187], v[200:203], v[88:91]
	v_mfma_f32_16x16x32_bf16 v[92:95], v[172:175], v[200:203], v[92:95]
	v_mfma_f32_16x16x32_bf16 v[76:79], v[172:175], v[208:211], v[76:79]
	v_mfma_f32_16x16x32_bf16 v[72:75], v[184:187], v[208:211], v[72:75]
	v_mfma_f32_16x16x32_bf16 v[64:67], v[184:187], v[216:219], v[64:67]
	v_mfma_f32_16x16x32_bf16 v[68:71], v[172:175], v[216:219], v[68:71]
	v_mfma_f32_16x16x32_bf16 v[108:111], v[180:183], v[196:199], v[108:111]
	v_mfma_f32_16x16x32_bf16 v[104:107], v[188:191], v[196:199], v[104:107]
	v_mfma_f32_16x16x32_bf16 v[88:91], v[188:191], v[204:207], v[88:91]
	v_mfma_f32_16x16x32_bf16 v[92:95], v[180:183], v[204:207], v[92:95]
	v_mfma_f32_16x16x32_bf16 v[76:79], v[180:183], v[212:215], v[76:79]
	v_mfma_f32_16x16x32_bf16 v[72:75], v[188:191], v[212:215], v[72:75]
	v_mfma_f32_16x16x32_bf16 v[64:67], v[188:191], v[220:223], v[64:67]
	v_mfma_f32_16x16x32_bf16 v[68:71], v[180:183], v[220:223], v[68:71]
	s_setprio 0
	s_barrier
; #define PG8_STAGE(bufoff, gbase, voff) do { _Pragma("unroll") for (int _i = 0; _i < 2; ++_i) \
;         __builtin_amdgcn_global_load_lds((const unsigned*)((const char*)(gbase) + (voff)[_i]), (LAS unsigned*)(lds + (bufoff) + ldsw + _i * 8192), 16, 0, 0); } while (0)
; #define PG8_LDA(dst, b, h) do { _Pragma("unroll") for (int m = 0; m < 4; ++m) _Pragma("unroll") for (int k = 0; k < 2; ++k) dst[m][k] = *(const LAS bf16x8*)(lds + PG8_SA(b, h) + aoff + m * 2048 + k * 1024); } while (0)
; #define PG8_MMA(ai, bj, At, Bt) do { __builtin_amdgcn_s_setprio(1); _Pragma("unroll") for (int m = 0; m < 4; ++m) _Pragma("unroll") for (int n = 0; n < 2; ++n) _Pragma("unroll") for (int k = 0; k < 2; ++k) \
;         acc[ai][bj][m][n] = __builtin_amdgcn_mfma_f32_16x16x32_bf16(Bt[n][k], At[m][k], acc[ai][bj][m][n], 0, 0, 0); __builtin_amdgcn_s_setprio(0); } while (0)
; #define PG8_WAIT_V(n) asm volatile("s_waitcnt vmcnt(" #n ")" ::: "memory")
; #define PG8_WAIT_L(n) asm volatile("s_waitcnt lgkmcnt(" #n ")" ::: "memory")
; #define PG8_BAR __builtin_amdgcn_s_barrier()
; #define PG8_SCHED __builtin_amdgcn_sched_barrier(0)
; template <class Epi, class Sched, bool ALIGN_EPI>
; __device__ __forceinline__ void gemm_phase(LAS unsigned char* lds, const int wid, const int lda_, const int ldb_, const int K_, const Sched& S, const Epi& E) {
;     ...
;             PG8_LDA(At, 1, 1); PG8_STAGE(PG8_SB(1, 0), b3, voffB); PG8_STAGE(PG8_SB(1, 1), b3 + hstepB, voffB); PG8_STAGE(PG8_SA(1, 0), a3, voffA);
;             PG8_WAIT_V(8); PG8_WAIT_L(0); PG8_BAR; PG8_MMA(1, 0, At, B0); PG8_MMA(1, 1, At, B1); PG8_BAR; PG8_SCHED;
;         }
;     __device__ __forceinline__ void out(const pg8::Unit& u, char*& o, int& ldo, int& kind) const { ldo = D;
;     ...
;         else { o = (char*)ws + WS_PART + (((size_t)u.kq * MCTX + (size_t)(u.pm - 64) * 256) * D + (size_t)u.pn * 256) * 2; kind = 0; } }
	s_add_i32 s17, s17, s3
	v_lshl_add_u64 v[224:225], v[224:225], 0, s[24:25]
	s_mov_b32 m0, s17
	ds_read_b128 v[192:195], v139 offset:49152
	ds_read_b128 v[196:199], v139 offset:50176
	ds_read_b128 v[200:203], v139 offset:51200
	ds_read_b128 v[204:207], v139 offset:52224
	ds_read_b128 v[208:211], v139 offset:53248
	ds_read_b128 v[212:215], v139 offset:54272
	ds_read_b128 v[216:219], v139 offset:55296
	ds_read_b128 v[220:223], v139 offset:56320
	global_load_lds_dwordx4 v[224:225], off
	v_lshl_add_u64 v[224:225], v[226:227], 0, s[24:25]
	s_add_i32 m0, s17, 0x2000
	s_add_i32 s17, s27, s3
	global_load_lds_dwordx4 v[224:225], off
	v_lshl_add_u64 v[224:225], v[228:229], 0, s[24:25]
	s_mov_b32 m0, s17
	s_nop 0
	global_load_lds_dwordx4 v[224:225], off
	v_lshl_add_u64 v[224:225], v[230:231], 0, s[24:25]
	s_add_i32 m0, s17, 0x2000
	s_nop 0
	global_load_lds_dwordx4 v[224:225], off
	v_lshl_add_u64 v[224:225], v[232:233], 0, s[24:25]
	s_mov_b32 m0, s72
	s_nop 0
	global_load_lds_dwordx4 v[224:225], off
	v_lshl_add_u64 v[224:225], v[234:235], 0, s[24:25]
	s_mov_b32 m0, s73
	s_nop 0
	global_load_lds_dwordx4 v[224:225], off
	s_waitcnt vmcnt(8)
	s_waitcnt lgkmcnt(0)
	s_barrier
	s_setprio 1
	s_waitcnt lgkmcnt(0)
	v_mfma_f32_16x16x32_bf16 v[60:63], v[156:159], v[192:195], v[60:63]
	v_mfma_f32_16x16x32_bf16 v[56:59], v[164:167], v[192:195], v[56:59]
	v_mfma_f32_16x16x32_bf16 v[48:51], v[164:167], v[200:203], v[48:51]
	v_mfma_f32_16x16x32_bf16 v[52:55], v[156:159], v[200:203], v[52:55]
	v_mfma_f32_16x16x32_bf16 v[36:39], v[156:159], v[208:211], v[36:39]
	v_mfma_f32_16x16x32_bf16 v[32:35], v[164:167], v[208:211], v[32:35]
	v_mfma_f32_16x16x32_bf16 v[16:19], v[164:167], v[216:219], v[16:19]
	v_mfma_f32_16x16x32_bf16 v[20:23], v[156:159], v[216:219], v[20:23]
	v_mfma_f32_16x16x32_bf16 v[60:63], v[160:163], v[196:199], v[60:63]
	v_mfma_f32_16x16x32_bf16 v[56:59], v[168:171], v[196:199], v[56:59]
	v_mfma_f32_16x16x32_bf16 v[48:51], v[168:171], v[204:207], v[48:51]
	v_mfma_f32_16x16x32_bf16 v[52:55], v[160:163], v[204:207], v[52:55]
	v_mfma_f32_16x16x32_bf16 v[36:39], v[160:163], v[212:215], v[36:39]
	v_mfma_f32_16x16x32_bf16 v[32:35], v[168:171], v[212:215], v[32:35]
	v_mfma_f32_16x16x32_bf16 v[16:19], v[168:171], v[220:223], v[16:19]
	v_mfma_f32_16x16x32_bf16 v[20:23], v[160:163], v[220:223], v[20:23]
	s_setprio 0
	s_setprio 1
	v_mfma_f32_16x16x32_bf16 v[44:47], v[172:175], v[192:195], v[44:47]
	v_mfma_f32_16x16x32_bf16 v[40:43], v[184:187], v[192:195], v[40:43]
	v_mfma_f32_16x16x32_bf16 v[24:27], v[184:187], v[200:203], v[24:27]
	v_mfma_f32_16x16x32_bf16 v[28:31], v[172:175], v[200:203], v[28:31]
	v_mfma_f32_16x16x32_bf16 v[12:15], v[172:175], v[208:211], v[12:15]
	v_mfma_f32_16x16x32_bf16 v[8:11], v[184:187], v[208:211], v[8:11]
	v_mfma_f32_16x16x32_bf16 v[0:3], v[184:187], v[216:219], v[0:3]
	v_mfma_f32_16x16x32_bf16 v[4:7], v[172:175], v[216:219], v[4:7]
	v_mfma_f32_16x16x32_bf16 v[44:47], v[180:183], v[196:199], v[44:47]
	v_mfma_f32_16x16x32_bf16 v[40:43], v[188:191], v[196:199], v[40:43]
	v_mfma_f32_16x16x32_bf16 v[24:27], v[188:191], v[204:207], v[24:27]
	v_mfma_f32_16x16x32_bf16 v[28:31], v[180:183], v[204:207], v[28:31]
	v_mfma_f32_16x16x32_bf16 v[12:15], v[180:183], v[212:215], v[12:15]
	v_mfma_f32_16x16x32_bf16 v[8:11], v[188:191], v[212:215], v[8:11]
	v_mfma_f32_16x16x32_bf16 v[0:3], v[188:191], v[220:223], v[0:3]
	v_mfma_f32_16x16x32_bf16 v[4:7], v[180:183], v[220:223], v[4:7]
	s_setprio 0
	s_barrier
	s_add_u32 s94, s94, 0x100
	s_addc_u32 s95, s95, 0
	s_add_u32 s43, s43, 0x100
	s_addc_u32 s76, s76, 0
	s_cmp_ge_u32 s78, s35
	s_mov_b32 s77, s78
	s_cbranch_scc0 .LBB0_671
	s_mov_b64 s[94:95], -1
	s_and_b64 vcc, exec, s[50:51]
	s_cbranch_vccz .LBB0_674
	s_mov_b32 s39, s92
	s_ashr_i32 s35, s34, 31
	s_ashr_i32 s37, s36, 31
	s_lshl_b64 s[4:5], s[34:35], 20
	s_lshl_b64 s[50:51], s[36:37], 9
	s_lshl_b64 s[38:39], s[38:39], 23
	v_readlane_b32 s76, v251, 28
	v_readlane_b32 s77, v251, 29
	s_add_u32 s17, s76, s50
	s_addc_u32 s27, s77, s51
	s_add_u32 s17, s17, s38
	s_addc_u32 s27, s27, s39
	s_add_u32 s4, s17, s4
	s_addc_u32 s5, s27, s5
	s_add_u32 s4, s4, 0xfc000000
	s_addc_u32 s5, s5, -1
	s_mov_b64 s[94:95], 0

; #define PG8_STAGE(bufoff, gbase, voff) do { _Pragma("unroll") for (int _i = 0; _i < 2; ++_i) \
;         __builtin_amdgcn_global_load_lds((const unsigned*)((const char*)(gbase) + (voff)[_i]), (LAS unsigned*)(lds + (bufoff) + ldsw + _i * 8192), 16, 0, 0); } while (0)
; #define PG8_LDA(dst, b, h) do { _Pragma("unroll") for (int m = 0; m < 4; ++m) _Pragma("unroll") for (int k = 0; k < 2; ++k) dst[m][k] = *(const LAS bf16x8*)(lds + PG8_SA(b, h) + aoff + m * 2048 + k * 1024); } while (0)
; #define PG8_LDB(dst, b, h) do { _Pragma("unroll") for (int n = 0; n < 2; ++n) _Pragma("unroll") for (int k = 0; k < 2; ++k) dst[n][k] = *(const LAS bf16x8*)(lds + PG8_SB(b, h) + boff + n * 2048 + k * 1024); } while (0)
; #define PG8_MMA(ai, bj, At, Bt) do { __builtin_amdgcn_s_setprio(1); _Pragma("unroll") for (int m = 0; m < 4; ++m) _Pragma("unroll") for (int n = 0; n < 2; ++n) _Pragma("unroll") for (int k = 0; k < 2; ++k) \
;         acc[ai][bj][m][n] = __builtin_amdgcn_mfma_f32_16x16x32_bf16(Bt[n][k], At[m][k], acc[ai][bj][m][n], 0, 0, 0); __builtin_amdgcn_s_setprio(0); } while (0)
; #define PG8_WAIT_V(n) asm volatile("s_waitcnt vmcnt(" #n ")" ::: "memory")
; #define PG8_WAIT_L(n) asm volatile("s_waitcnt lgkmcnt(" #n ")" ::: "memory")
; #define PG8_BAR __builtin_amdgcn_s_barrier()
; #define PG8_SCHED __builtin_amdgcn_sched_barrier(0)
; template <class Epi, class Sched, bool ALIGN_EPI>
; __device__ __forceinline__ void gemm_phase(LAS unsigned char* lds, const int wid, const int lda_, const int ldb_, const int K_, const Sched& S, const Epi& E) {
;     ...
;             PG8_LDB(B0, 0, 0); PG8_LDB(B1, 0, 1); PG8_SCHED; PG8_LDA(At, 0, 0); PG8_STAGE(PG8_SA(1, 1), a1 + hstepA, voffA);
;             PG8_WAIT_V(8); PG8_WAIT_L(0); PG8_BAR; PG8_MMA(0, 0, At, B0); PG8_MMA(0, 1, At, B1); PG8_BAR; PG8_SCHED;
;             PG8_LDA(At, 0, 1); PG8_STAGE(PG8_SB(0, 0), b2, voffB); PG8_STAGE(PG8_SB(0, 1), b2 + hstepB, voffB); PG8_STAGE(PG8_SA(0, 0), a2, voffA);
;             PG8_WAIT_V(8); PG8_WAIT_L(0); PG8_BAR; PG8_MMA(1, 0, At, B0); PG8_MMA(1, 1, At, B1); PG8_BAR; PG8_SCHED;
;     __device__ __forceinline__ const char* a(const pg8::Unit& u) const { return (const char*)ws + WS_W1 + (size_t)(u.pm & 1) * 256 * 256 * 2; }
;     __device__ __forceinline__ const char* b(const pg8::Unit& u) const { return (const char*)ws + WS_A + ((size_t)u.pn * 256 * D + (size_t)(u.pm >> 1) * 256) * 2; }
.LBB0_697:
	s_add_u32 s77, s44, s50
	s_addc_u32 s78, s45, s51
	s_add_u32 s79, s77, 0x100
	s_addc_u32 s80, s78, 0
	s_and_b64 s[42:43], s[48:49], exec
	s_cselect_b32 s95, s4, s80
	s_cselect_b32 s94, s5, s79
	s_add_u32 s42, s40, s50
	s_addc_u32 s43, s41, s51
	s_add_u32 s50, s42, 0x100
	s_addc_u32 s51, s43, 0
	s_add_i32 s93, 0, 0x10000
	s_and_b64 s[42:43], s[48:49], exec
	s_cselect_b32 s51, s31, s51
	s_cselect_b32 s50, s76, s50
	s_add_i32 s42, 0, 0x14000
	v_add_u32_e32 v141, s93, v135
	s_add_u32 vcc_lo, s77, s0
	ds_read_b128 v[152:155], v141
	ds_read_b128 v[156:159], v141 offset:1024
	ds_read_b128 v[160:163], v141 offset:2048
	ds_read_b128 v[164:167], v141 offset:3072
	v_add_u32_e32 v141, s42, v135
	s_addc_u32 vcc_hi, s78, s1
	s_add_i32 s87, s93, s3
	ds_read_b128 v[168:171], v141
	ds_read_b128 v[172:175], v141 offset:1024
	ds_read_b128 v[180:183], v141 offset:2048
	ds_read_b128 v[184:187], v141 offset:3072
	s_add_i32 m0, s16, 0xc000
	s_add_i32 s27, s16, 0xe000
	s_add_i32 s80, s87, 0x2000
	s_add_u32 s96, s50, s10
	s_addc_u32 s97, s51, s11
	s_add_i32 s86, s42, s3
	s_add_i32 s81, s86, 0x2000
	s_add_i32 s79, 0, 0x18000
	s_add_i32 s78, 0, 0x1c000
	s_add_u32 s48, s94, s0
	s_addc_u32 s49, s95, s1
	s_add_i32 s77, s79, s3
	s_add_i32 s93, s78, s3
	s_add_i32 s43, s77, 0x2000
	s_add_i32 s42, s93, 0x2000
	v_lshl_add_u64 v[220:221], vcc, 0, v[132:133]
	v_lshl_add_u64 v[220:221], v[220:221], 0, s[24:25]
	ds_read_b128 v[188:191], v139
	ds_read_b128 v[192:195], v139 offset:1024
	ds_read_b128 v[196:199], v139 offset:2048
	ds_read_b128 v[200:203], v139 offset:3072
	ds_read_b128 v[204:207], v139 offset:4096
	ds_read_b128 v[208:211], v139 offset:5120
	ds_read_b128 v[212:215], v139 offset:6144
	ds_read_b128 v[216:219], v139 offset:7168
	global_load_lds_dwordx4 v[220:221], off
	v_lshl_add_u64 v[220:221], vcc, 0, v[130:131]
	v_lshl_add_u64 v[220:221], v[220:221], 0, s[24:25]
	s_mov_b32 m0, s27
	s_nop 0
	global_load_lds_dwordx4 v[220:221], off
	s_waitcnt vmcnt(8)
	s_waitcnt lgkmcnt(0)
	s_barrier
	s_setprio 1
	s_waitcnt lgkmcnt(0)
	v_mfma_f32_16x16x32_bf16 v[124:127], v[152:155], v[188:191], v[124:127]
	v_mfma_f32_16x16x32_bf16 v[120:123], v[160:163], v[188:191], v[120:123]
	v_mfma_f32_16x16x32_bf16 v[112:115], v[160:163], v[196:199], v[112:115]
	v_mfma_f32_16x16x32_bf16 v[116:119], v[152:155], v[196:199], v[116:119]
	v_mfma_f32_16x16x32_bf16 v[100:103], v[152:155], v[204:207], v[100:103]
	v_mfma_f32_16x16x32_bf16 v[96:99], v[160:163], v[204:207], v[96:99]
	v_mfma_f32_16x16x32_bf16 v[80:83], v[160:163], v[212:215], v[80:83]
	v_mfma_f32_16x16x32_bf16 v[84:87], v[152:155], v[212:215], v[84:87]
	v_mfma_f32_16x16x32_bf16 v[124:127], v[156:159], v[192:195], v[124:127]
	v_mfma_f32_16x16x32_bf16 v[120:123], v[164:167], v[192:195], v[120:123]
	v_mfma_f32_16x16x32_bf16 v[112:115], v[164:167], v[200:203], v[112:115]
	v_mfma_f32_16x16x32_bf16 v[116:119], v[156:159], v[200:203], v[116:119]
	v_mfma_f32_16x16x32_bf16 v[100:103], v[156:159], v[208:211], v[100:103]
	v_mfma_f32_16x16x32_bf16 v[96:99], v[164:167], v[208:211], v[96:99]
	v_mfma_f32_16x16x32_bf16 v[80:83], v[164:167], v[216:219], v[80:83]
	v_mfma_f32_16x16x32_bf16 v[84:87], v[156:159], v[216:219], v[84:87]
	s_setprio 0
	s_setprio 1
	v_mfma_f32_16x16x32_bf16 v[108:111], v[168:171], v[188:191], v[108:111]
	v_mfma_f32_16x16x32_bf16 v[104:107], v[180:183], v[188:191], v[104:107]
	v_mfma_f32_16x16x32_bf16 v[88:91], v[180:183], v[196:199], v[88:91]
	v_mfma_f32_16x16x32_bf16 v[92:95], v[168:171], v[196:199], v[92:95]
	v_mfma_f32_16x16x32_bf16 v[76:79], v[168:171], v[204:207], v[76:79]
	v_mfma_f32_16x16x32_bf16 v[72:75], v[180:183], v[204:207], v[72:75]
	v_mfma_f32_16x16x32_bf16 v[64:67], v[180:183], v[212:215], v[64:67]
	v_mfma_f32_16x16x32_bf16 v[68:71], v[168:171], v[212:215], v[68:71]
	v_mfma_f32_16x16x32_bf16 v[108:111], v[172:175], v[192:195], v[108:111]
	v_mfma_f32_16x16x32_bf16 v[104:107], v[184:187], v[192:195], v[104:107]
	v_mfma_f32_16x16x32_bf16 v[88:91], v[184:187], v[200:203], v[88:91]
	v_mfma_f32_16x16x32_bf16 v[92:95], v[172:175], v[200:203], v[92:95]
	v_mfma_f32_16x16x32_bf16 v[76:79], v[172:175], v[208:211], v[76:79]
	v_mfma_f32_16x16x32_bf16 v[72:75], v[184:187], v[208:211], v[72:75]
	v_mfma_f32_16x16x32_bf16 v[64:67], v[184:187], v[216:219], v[64:67]
	v_mfma_f32_16x16x32_bf16 v[68:71], v[172:175], v[216:219], v[68:71]
	s_setprio 0
	s_barrier
	s_mov_b32 m0, s87
	v_lshl_add_u64 v[220:221], s[50:51], 0, v[176:177]
	ds_read_b128 v[188:191], v139 offset:16384
	ds_read_b128 v[192:195], v139 offset:17408
	ds_read_b128 v[196:199], v139 offset:18432
	ds_read_b128 v[200:203], v139 offset:19456
	ds_read_b128 v[204:207], v139 offset:20480
	ds_read_b128 v[208:211], v139 offset:21504
	ds_read_b128 v[212:215], v139 offset:22528
	ds_read_b128 v[216:219], v139 offset:23552
	global_load_lds_dwordx4 v[220:221], off
	v_lshl_add_u64 v[222:223], s[50:51], 0, v[128:129]
	s_mov_b32 m0, s80
	v_lshl_add_u64 v[224:225], s[96:97], 0, v[176:177]
	global_load_lds_dwordx4 v[222:223], off
	s_mov_b32 m0, s86
	v_lshl_add_u64 v[226:227], s[96:97], 0, v[128:129]
	global_load_lds_dwordx4 v[224:225], off
	s_mov_b32 m0, s81
	v_lshl_add_u64 v[228:229], s[94:95], 0, v[132:133]
	global_load_lds_dwordx4 v[226:227], off
	s_mov_b32 m0, s16
	v_lshl_add_u64 v[230:231], s[94:95], 0, v[130:131]
	global_load_lds_dwordx4 v[228:229], off
	s_mov_b32 m0, s6
	s_nop 0
	global_load_lds_dwordx4 v[230:231], off
	s_waitcnt vmcnt(8)
	s_waitcnt lgkmcnt(0)
	s_barrier
; #define PG8_STAGE(bufoff, gbase, voff) do { _Pragma("unroll") for (int _i = 0; _i < 2; ++_i) \
;         __builtin_amdgcn_global_load_lds((const unsigned*)((const char*)(gbase) + (voff)[_i]), (LAS unsigned*)(lds + (bufoff) + ldsw + _i * 8192), 16, 0, 0); } while (0)
; #define PG8_LDA(dst, b, h) do { _Pragma("unroll") for (int m = 0; m < 4; ++m) _Pragma("unroll") for (int k = 0; k < 2; ++k) dst[m][k] = *(const LAS bf16x8*)(lds + PG8_SA(b, h) + aoff + m * 2048 + k * 1024); } while (0)
; #define PG8_LDB(dst, b, h) do { _Pragma("unroll") for (int n = 0; n < 2; ++n) _Pragma("unroll") for (int k = 0; k < 2; ++k) dst[n][k] = *(const LAS bf16x8*)(lds + PG8_SB(b, h) + boff + n * 2048 + k * 1024); } while (0)
; #define PG8_MMA(ai, bj, At, Bt) do { __builtin_amdgcn_s_setprio(1); _Pragma("unroll") for (int m = 0; m < 4; ++m) _Pragma("unroll") for (int n = 0; n < 2; ++n) _Pragma("unroll") for (int k = 0; k < 2; ++k) \
;         acc[ai][bj][m][n] = __builtin_amdgcn_mfma_f32_16x16x32_bf16(Bt[n][k], At[m][k], acc[ai][bj][m][n], 0, 0, 0); __builtin_amdgcn_s_setprio(0); } while (0)
; #define PG8_WAIT_V(n) asm volatile("s_waitcnt vmcnt(" #n ")" ::: "memory")
; #define PG8_WAIT_L(n) asm volatile("s_waitcnt lgkmcnt(" #n ")" ::: "memory")
; #define PG8_BAR __builtin_amdgcn_s_barrier()
; #define PG8_SCHED __builtin_amdgcn_sched_barrier(0)
; template <class Epi, class Sched, bool ALIGN_EPI>
; __device__ __forceinline__ void gemm_phase(LAS unsigned char* lds, const int wid, const int lda_, const int ldb_, const int K_, const Sched& S, const Epi& E) {
;     ...
;             PG8_WAIT_V(8); PG8_WAIT_L(0); PG8_BAR; PG8_MMA(1, 0, At, B0); PG8_MMA(1, 1, At, B1); PG8_BAR; PG8_SCHED;
;             PG8_LDB(B0, 1, 0); PG8_LDB(B1, 1, 1); PG8_SCHED; PG8_LDA(At, 1, 0); PG8_STAGE(PG8_SA(0, 1), a2 + hstepA, voffA);
;             PG8_WAIT_V(8); PG8_WAIT_L(0); PG8_BAR; PG8_MMA(0, 0, At, B0); PG8_MMA(0, 1, At, B1); PG8_BAR; PG8_SCHED;
	s_setprio 1
	s_waitcnt lgkmcnt(0)
	v_mfma_f32_16x16x32_bf16 v[60:63], v[152:155], v[188:191], v[60:63]
	v_mfma_f32_16x16x32_bf16 v[56:59], v[160:163], v[188:191], v[56:59]
	v_mfma_f32_16x16x32_bf16 v[48:51], v[160:163], v[196:199], v[48:51]
	v_mfma_f32_16x16x32_bf16 v[52:55], v[152:155], v[196:199], v[52:55]
	v_mfma_f32_16x16x32_bf16 v[36:39], v[152:155], v[204:207], v[36:39]
	v_mfma_f32_16x16x32_bf16 v[32:35], v[160:163], v[204:207], v[32:35]
	v_mfma_f32_16x16x32_bf16 v[16:19], v[160:163], v[212:215], v[16:19]
	v_mfma_f32_16x16x32_bf16 v[20:23], v[152:155], v[212:215], v[20:23]
	v_mfma_f32_16x16x32_bf16 v[60:63], v[156:159], v[192:195], v[60:63]
	v_mfma_f32_16x16x32_bf16 v[56:59], v[164:167], v[192:195], v[56:59]
	v_mfma_f32_16x16x32_bf16 v[48:51], v[164:167], v[200:203], v[48:51]
	v_mfma_f32_16x16x32_bf16 v[52:55], v[156:159], v[200:203], v[52:55]
	v_mfma_f32_16x16x32_bf16 v[36:39], v[156:159], v[208:211], v[36:39]
	v_mfma_f32_16x16x32_bf16 v[32:35], v[164:167], v[208:211], v[32:35]
	v_mfma_f32_16x16x32_bf16 v[16:19], v[164:167], v[216:219], v[16:19]
	v_mfma_f32_16x16x32_bf16 v[20:23], v[156:159], v[216:219], v[20:23]
	s_setprio 0
	s_setprio 1
	v_mfma_f32_16x16x32_bf16 v[44:47], v[168:171], v[188:191], v[44:47]
	v_mfma_f32_16x16x32_bf16 v[40:43], v[180:183], v[188:191], v[40:43]
	v_mfma_f32_16x16x32_bf16 v[24:27], v[180:183], v[196:199], v[24:27]
	v_mfma_f32_16x16x32_bf16 v[28:31], v[168:171], v[196:199], v[28:31]
	v_mfma_f32_16x16x32_bf16 v[12:15], v[168:171], v[204:207], v[12:15]
	v_mfma_f32_16x16x32_bf16 v[8:11], v[180:183], v[204:207], v[8:11]
	v_mfma_f32_16x16x32_bf16 v[0:3], v[180:183], v[212:215], v[0:3]
	v_mfma_f32_16x16x32_bf16 v[4:7], v[168:171], v[212:215], v[4:7]
	v_mfma_f32_16x16x32_bf16 v[44:47], v[172:175], v[192:195], v[44:47]
	v_mfma_f32_16x16x32_bf16 v[40:43], v[184:187], v[192:195], v[40:43]
	v_mfma_f32_16x16x32_bf16 v[24:27], v[184:187], v[200:203], v[24:27]
	v_mfma_f32_16x16x32_bf16 v[28:31], v[172:175], v[200:203], v[28:31]
	v_mfma_f32_16x16x32_bf16 v[12:15], v[172:175], v[208:211], v[12:15]
	v_mfma_f32_16x16x32_bf16 v[8:11], v[184:187], v[208:211], v[8:11]
	v_mfma_f32_16x16x32_bf16 v[0:3], v[184:187], v[216:219], v[0:3]
	v_mfma_f32_16x16x32_bf16 v[4:7], v[172:175], v[216:219], v[4:7]
	s_setprio 0
	s_barrier
	v_add_u32_e32 v141, s79, v135
	ds_read_b128 v[152:155], v141
	ds_read_b128 v[156:159], v141 offset:1024
	ds_read_b128 v[160:163], v141 offset:2048
	ds_read_b128 v[164:167], v141 offset:3072
	v_add_u32_e32 v141, s78, v135
	ds_read_b128 v[168:171], v141
	ds_read_b128 v[172:175], v141 offset:1024
	ds_read_b128 v[180:183], v141 offset:2048
	ds_read_b128 v[184:187], v141 offset:3072
	s_mov_b32 m0, s7
	v_lshl_add_u64 v[232:233], s[48:49], 0, v[132:133]
	ds_read_b128 v[188:191], v139 offset:32768
	ds_read_b128 v[192:195], v139 offset:33792
	ds_read_b128 v[196:199], v139 offset:34816
	ds_read_b128 v[200:203], v139 offset:35840
	ds_read_b128 v[204:207], v139 offset:36864
	ds_read_b128 v[208:211], v139 offset:37888
	ds_read_b128 v[212:215], v139 offset:38912
	ds_read_b128 v[216:219], v139 offset:39936
	global_load_lds_dwordx4 v[232:233], off
	v_lshl_add_u64 v[232:233], s[48:49], 0, v[130:131]
	s_mov_b32 m0, s14
	s_nop 0
	global_load_lds_dwordx4 v[232:233], off
	s_waitcnt vmcnt(8)
	s_waitcnt lgkmcnt(0)
	s_barrier
	s_setprio 1
	s_waitcnt lgkmcnt(0)
	v_mfma_f32_16x16x32_bf16 v[124:127], v[152:155], v[188:191], v[124:127]
	v_mfma_f32_16x16x32_bf16 v[120:123], v[160:163], v[188:191], v[120:123]
	v_mfma_f32_16x16x32_bf16 v[112:115], v[160:163], v[196:199], v[112:115]
	v_mfma_f32_16x16x32_bf16 v[116:119], v[152:155], v[196:199], v[116:119]
	v_mfma_f32_16x16x32_bf16 v[100:103], v[152:155], v[204:207], v[100:103]
	v_mfma_f32_16x16x32_bf16 v[96:99], v[160:163], v[204:207], v[96:99]
	v_mfma_f32_16x16x32_bf16 v[80:83], v[160:163], v[212:215], v[80:83]
	v_mfma_f32_16x16x32_bf16 v[84:87], v[152:155], v[212:215], v[84:87]
	v_mfma_f32_16x16x32_bf16 v[124:127], v[156:159], v[192:195], v[124:127]
	v_mfma_f32_16x16x32_bf16 v[120:123], v[164:167], v[192:195], v[120:123]
	v_mfma_f32_16x16x32_bf16 v[112:115], v[164:167], v[200:203], v[112:115]
	v_mfma_f32_16x16x32_bf16 v[116:119], v[156:159], v[200:203], v[116:119]
	v_mfma_f32_16x16x32_bf16 v[100:103], v[156:159], v[208:211], v[100:103]
	v_mfma_f32_16x16x32_bf16 v[96:99], v[164:167], v[208:211], v[96:99]
	v_mfma_f32_16x16x32_bf16 v[80:83], v[164:167], v[216:219], v[80:83]
	v_mfma_f32_16x16x32_bf16 v[84:87], v[156:159], v[216:219], v[84:87]
	s_setprio 0
	s_setprio 1
	v_mfma_f32_16x16x32_bf16 v[108:111], v[168:171], v[188:191], v[108:111]
	v_mfma_f32_16x16x32_bf16 v[104:107], v[180:183], v[188:191], v[104:107]
	v_mfma_f32_16x16x32_bf16 v[88:91], v[180:183], v[196:199], v[88:91]
	v_mfma_f32_16x16x32_bf16 v[92:95], v[168:171], v[196:199], v[92:95]
	v_mfma_f32_16x16x32_bf16 v[76:79], v[168:171], v[204:207], v[76:79]
	v_mfma_f32_16x16x32_bf16 v[72:75], v[180:183], v[204:207], v[72:75]
	v_mfma_f32_16x16x32_bf16 v[64:67], v[180:183], v[212:215], v[64:67]
	v_mfma_f32_16x16x32_bf16 v[68:71], v[168:171], v[212:215], v[68:71]
	v_mfma_f32_16x16x32_bf16 v[108:111], v[172:175], v[192:195], v[108:111]
	v_mfma_f32_16x16x32_bf16 v[104:107], v[184:187], v[192:195], v[104:107]
	v_mfma_f32_16x16x32_bf16 v[88:91], v[184:187], v[200:203], v[88:91]
	v_mfma_f32_16x16x32_bf16 v[92:95], v[172:175], v[200:203], v[92:95]
	v_mfma_f32_16x16x32_bf16 v[76:79], v[172:175], v[208:211], v[76:79]
	v_mfma_f32_16x16x32_bf16 v[72:75], v[184:187], v[208:211], v[72:75]
	v_mfma_f32_16x16x32_bf16 v[64:67], v[184:187], v[216:219], v[64:67]
	v_mfma_f32_16x16x32_bf16 v[68:71], v[172:175], v[216:219], v[68:71]
	s_setprio 0
	s_barrier
; #define PG8_STAGE(bufoff, gbase, voff) do { _Pragma("unroll") for (int _i = 0; _i < 2; ++_i) \
;         __builtin_amdgcn_global_load_lds((const unsigned*)((const char*)(gbase) + (voff)[_i]), (LAS unsigned*)(lds + (bufoff) + ldsw + _i * 8192), 16, 0, 0); } while (0)
; #define PG8_LDA(dst, b, h) do { _Pragma("unroll") for (int m = 0; m < 4; ++m) _Pragma("unroll") for (int k = 0; k < 2; ++k) dst[m][k] = *(const LAS bf16x8*)(lds + PG8_SA(b, h) + aoff + m * 2048 + k * 1024); } while (0)
; #define PG8_MMA(ai, bj, At, Bt) do { __builtin_amdgcn_s_setprio(1); _Pragma("unroll") for (int m = 0; m < 4; ++m) _Pragma("unroll") for (int n = 0; n < 2; ++n) _Pragma("unroll") for (int k = 0; k < 2; ++k) \
;         acc[ai][bj][m][n] = __builtin_amdgcn_mfma_f32_16x16x32_bf16(Bt[n][k], At[m][k], acc[ai][bj][m][n], 0, 0, 0); __builtin_amdgcn_s_setprio(0); } while (0)
; #define PG8_WAIT_V(n) asm volatile("s_waitcnt vmcnt(" #n ")" ::: "memory")
; #define PG8_WAIT_L(n) asm volatile("s_waitcnt lgkmcnt(" #n ")" ::: "memory")
; #define PG8_BAR __builtin_amdgcn_s_barrier()
; #define PG8_SCHED __builtin_amdgcn_sched_barrier(0)
;     __device__ __forceinline__ const char* b(const pg8::Unit& u) const { return (const char*)ws + boff + (size_t)u.pn * 256 * K_ * 2 + (u.kq < 0 ? 0 : u.kq * (K_ / 4) * 2); }
;     __device__ __forceinline__ const char* b(const pg8::Unit& u) const { return (const char*)ws + boff + (size_t)u.pn * 256 * D * 2; }
; template <class Epi, class Sched, bool ALIGN_EPI>
; __device__ __forceinline__ void gemm_phase(LAS unsigned char* lds, const int wid, const int lda_, const int ldb_, const int K_, const Sched& S, const Epi& E) {
;     ...
;             PG8_LDA(At, 1, 1); PG8_STAGE(PG8_SB(1, 0), b3, voffB); PG8_STAGE(PG8_SB(1, 1), b3 + hstepB, voffB); PG8_STAGE(PG8_SA(1, 0), a3, voffA);
;             PG8_WAIT_V(8); PG8_WAIT_L(0); PG8_BAR; PG8_MMA(1, 0, At, B0); PG8_MMA(1, 1, At, B1); PG8_BAR; PG8_SCHED;
;         }
;     __device__ __forceinline__ void out(const pg8::Unit& u, char*& o, int& ldo, int& kind) const { const int g = u.pm >> 1, cs = u.pm & 1;
;         if (u.pn < 64) { const int b = u.pn >> 3, p0 = (u.pn & 7) * 256; o = (char*)ws + WS_PQT + (((size_t)(b * 2048 + g * 256)) * 4096 + (size_t)cs * 2048 + p0) * 2; ldo = 4096; }
;         else { const int b = u.pn - 64; o = (char*)ws + WS_PQTC + (((size_t)(b * 2048 + g * 256)) * 512 + (size_t)cs * 256) * 2; ldo = 512; }
	s_mov_b32 m0, s77
	v_lshl_add_u64 v[220:221], v[220:221], 0, s[24:25]
	ds_read_b128 v[188:191], v139 offset:49152
	ds_read_b128 v[192:195], v139 offset:50176
	ds_read_b128 v[196:199], v139 offset:51200
	ds_read_b128 v[200:203], v139 offset:52224
	ds_read_b128 v[204:207], v139 offset:53248
	ds_read_b128 v[208:211], v139 offset:54272
	ds_read_b128 v[212:215], v139 offset:55296
	ds_read_b128 v[216:219], v139 offset:56320
	global_load_lds_dwordx4 v[220:221], off
	v_lshl_add_u64 v[220:221], v[222:223], 0, s[24:25]
	s_mov_b32 m0, s43
	s_nop 0
	global_load_lds_dwordx4 v[220:221], off
	v_lshl_add_u64 v[220:221], v[224:225], 0, s[24:25]
	s_mov_b32 m0, s93
	s_nop 0
	global_load_lds_dwordx4 v[220:221], off
	v_lshl_add_u64 v[220:221], v[226:227], 0, s[24:25]
	s_mov_b32 m0, s42
	s_nop 0
	global_load_lds_dwordx4 v[220:221], off
	v_lshl_add_u64 v[220:221], v[228:229], 0, s[24:25]
	s_mov_b32 m0, s15
	s_nop 0
	global_load_lds_dwordx4 v[220:221], off
	v_lshl_add_u64 v[220:221], v[230:231], 0, s[24:25]
	s_mov_b32 m0, s26
	s_nop 0
	global_load_lds_dwordx4 v[220:221], off
	s_waitcnt vmcnt(8)
	s_waitcnt lgkmcnt(0)
	s_barrier
	s_setprio 1
	s_waitcnt lgkmcnt(0)
	v_mfma_f32_16x16x32_bf16 v[60:63], v[152:155], v[188:191], v[60:63]
	v_mfma_f32_16x16x32_bf16 v[56:59], v[160:163], v[188:191], v[56:59]
	v_mfma_f32_16x16x32_bf16 v[48:51], v[160:163], v[196:199], v[48:51]
	v_mfma_f32_16x16x32_bf16 v[52:55], v[152:155], v[196:199], v[52:55]
	v_mfma_f32_16x16x32_bf16 v[36:39], v[152:155], v[204:207], v[36:39]
	v_mfma_f32_16x16x32_bf16 v[32:35], v[160:163], v[204:207], v[32:35]
	v_mfma_f32_16x16x32_bf16 v[16:19], v[160:163], v[212:215], v[16:19]
	v_mfma_f32_16x16x32_bf16 v[20:23], v[152:155], v[212:215], v[20:23]
	v_mfma_f32_16x16x32_bf16 v[60:63], v[156:159], v[192:195], v[60:63]
	v_mfma_f32_16x16x32_bf16 v[56:59], v[164:167], v[192:195], v[56:59]
	v_mfma_f32_16x16x32_bf16 v[48:51], v[164:167], v[200:203], v[48:51]
	v_mfma_f32_16x16x32_bf16 v[52:55], v[156:159], v[200:203], v[52:55]
	v_mfma_f32_16x16x32_bf16 v[36:39], v[156:159], v[208:211], v[36:39]
	v_mfma_f32_16x16x32_bf16 v[32:35], v[164:167], v[208:211], v[32:35]
	v_mfma_f32_16x16x32_bf16 v[16:19], v[164:167], v[216:219], v[16:19]
	v_mfma_f32_16x16x32_bf16 v[20:23], v[156:159], v[216:219], v[20:23]
	s_setprio 0
	s_setprio 1
	v_mfma_f32_16x16x32_bf16 v[44:47], v[168:171], v[188:191], v[44:47]
	v_mfma_f32_16x16x32_bf16 v[40:43], v[180:183], v[188:191], v[40:43]
	v_mfma_f32_16x16x32_bf16 v[24:27], v[180:183], v[196:199], v[24:27]
	v_mfma_f32_16x16x32_bf16 v[28:31], v[168:171], v[196:199], v[28:31]
	v_mfma_f32_16x16x32_bf16 v[12:15], v[168:171], v[204:207], v[12:15]
	v_mfma_f32_16x16x32_bf16 v[8:11], v[180:183], v[204:207], v[8:11]
	v_mfma_f32_16x16x32_bf16 v[0:3], v[180:183], v[212:215], v[0:3]
	v_mfma_f32_16x16x32_bf16 v[4:7], v[168:171], v[212:215], v[4:7]
	v_mfma_f32_16x16x32_bf16 v[44:47], v[172:175], v[192:195], v[44:47]
	v_mfma_f32_16x16x32_bf16 v[40:43], v[184:187], v[192:195], v[40:43]
	v_mfma_f32_16x16x32_bf16 v[24:27], v[184:187], v[200:203], v[24:27]
	v_mfma_f32_16x16x32_bf16 v[28:31], v[172:175], v[200:203], v[28:31]
	v_mfma_f32_16x16x32_bf16 v[12:15], v[172:175], v[208:211], v[12:15]
	v_mfma_f32_16x16x32_bf16 v[8:11], v[184:187], v[208:211], v[8:11]
	v_mfma_f32_16x16x32_bf16 v[0:3], v[184:187], v[216:219], v[0:3]
	v_mfma_f32_16x16x32_bf16 v[4:7], v[172:175], v[216:219], v[4:7]
	s_setprio 0
	s_barrier
	s_andn2_b64 vcc, exec, s[46:47]
	s_mov_b64 s[48:49], -1
	s_mov_b64 s[46:47], 0
	s_mov_b64 s[50:51], 0x100
	s_cbranch_vccz .LBB0_697
	s_ashr_i32 s43, s75, 1
	s_and_b32 s42, s75, 1
	s_cmp_gt_i32 s74, 63
	s_mov_b64 s[40:41], -1
	s_cbranch_scc0 .LBB0_700
	s_lshl_b32 s4, s74, 11
	s_lshl_b32 s5, s43, 8
	s_add_i32 s4, s4, s5
	s_add_i32 s4, s4, 0xfffe0000
	s_ashr_i32 s5, s4, 31
	s_lshl_b32 s31, s42, 9
	s_lshl_b64 s[4:5], s[4:5], 10
	v_readlane_b32 s17, v254, 2
	s_add_u32 s4, s17, s4
	v_readlane_b32 s17, v254, 3
	s_addc_u32 s5, s17, s5
	s_add_u32 s4, s4, s31
	s_addc_u32 s5, s5, 0
	s_mov_b64 s[40:41], 0

; #define PG8_STAGE(bufoff, gbase, voff) do { _Pragma("unroll") for (int _i = 0; _i < 2; ++_i) \
;         __builtin_amdgcn_global_load_lds((const unsigned*)((const char*)(gbase) + (voff)[_i]), (LAS unsigned*)(lds + (bufoff) + ldsw + _i * 8192), 16, 0, 0); } while (0)
; #define PG8_LDA(dst, b, h) do { _Pragma("unroll") for (int m = 0; m < 4; ++m) _Pragma("unroll") for (int k = 0; k < 2; ++k) dst[m][k] = *(const LAS bf16x8*)(lds + PG8_SA(b, h) + aoff + m * 2048 + k * 1024); } while (0)
; #define PG8_LDB(dst, b, h) do { _Pragma("unroll") for (int n = 0; n < 2; ++n) _Pragma("unroll") for (int k = 0; k < 2; ++k) dst[n][k] = *(const LAS bf16x8*)(lds + PG8_SB(b, h) + boff + n * 2048 + k * 1024); } while (0)
; #define PG8_MMA(ai, bj, At, Bt) do { __builtin_amdgcn_s_setprio(1); _Pragma("unroll") for (int m = 0; m < 4; ++m) _Pragma("unroll") for (int n = 0; n < 2; ++n) _Pragma("unroll") for (int k = 0; k < 2; ++k) \
;         acc[ai][bj][m][n] = __builtin_amdgcn_mfma_f32_16x16x32_bf16(Bt[n][k], At[m][k], acc[ai][bj][m][n], 0, 0, 0); __builtin_amdgcn_s_setprio(0); } while (0)
; #define PG8_WAIT_V(n) asm volatile("s_waitcnt vmcnt(" #n ")" ::: "memory")
; #define PG8_WAIT_L(n) asm volatile("s_waitcnt lgkmcnt(" #n ")" ::: "memory")
; #define PG8_BAR __builtin_amdgcn_s_barrier()
; #define PG8_SCHED __builtin_amdgcn_sched_barrier(0)
; template <class Epi, class Sched, bool ALIGN_EPI>
; __device__ __forceinline__ void gemm_phase(LAS unsigned char* lds, const int wid, const int lda_, const int ldb_, const int K_, const Sched& S, const Epi& E) {
;     ...
;             PG8_LDB(B0, 0, 0); PG8_LDB(B1, 0, 1); PG8_SCHED; PG8_LDA(At, 0, 0); PG8_STAGE(PG8_SA(1, 1), a1 + hstepA, voffA);
;             PG8_WAIT_V(8); PG8_WAIT_L(0); PG8_BAR; PG8_MMA(0, 0, At, B0); PG8_MMA(0, 1, At, B1); PG8_BAR; PG8_SCHED;
;             PG8_LDA(At, 0, 1); PG8_STAGE(PG8_SB(0, 0), b2, voffB); PG8_STAGE(PG8_SB(0, 1), b2 + hstepB, voffB); PG8_STAGE(PG8_SA(0, 0), a2, voffA);
;             PG8_WAIT_V(8); PG8_WAIT_L(0); PG8_BAR; PG8_MMA(1, 0, At, B0); PG8_MMA(1, 1, At, B1); PG8_BAR; PG8_SCHED;
.LBB0_883:
	s_add_u32 s17, s46, s48
	s_addc_u32 s27, s47, s49
	s_add_u32 s17, s17, 0x100
	s_addc_u32 s27, s27, 0
	s_add_u32 s42, s31, s48
	s_addc_u32 s43, s35, s49
	s_add_i32 s74, 0, 0x10000
	s_cmpk_eq_i32 s48, 0x300
	s_cselect_b32 s51, s4, s27
	s_cselect_b32 s50, s5, s17
	v_add_u32_e32 v141, s74, v135
	s_cselect_b32 s43, s39, s43
	s_cselect_b32 s42, s38, s42
	s_add_i32 s17, 0, 0x14000
	ds_read_b128 v[160:163], v141
	ds_read_b128 v[164:167], v141 offset:1024
	ds_read_b128 v[168:171], v141 offset:2048
	ds_read_b128 v[172:175], v141 offset:3072
	v_add_u32_e32 v141, s17, v135
	ds_read_b128 v[180:183], v141
	ds_read_b128 v[184:187], v141 offset:1024
	ds_read_b128 v[188:191], v141 offset:2048
	ds_read_b128 v[192:195], v141 offset:3072
	v_lshl_add_u64 v[228:229], v[158:159], 0, s[48:49]
	s_add_i32 m0, s16, 0xc000
	ds_read_b128 v[196:199], v139
	ds_read_b128 v[200:203], v139 offset:1024
	ds_read_b128 v[204:207], v139 offset:2048
	ds_read_b128 v[208:211], v139 offset:3072
	ds_read_b128 v[212:215], v139 offset:4096
	ds_read_b128 v[216:219], v139 offset:5120
	ds_read_b128 v[220:223], v139 offset:6144
	ds_read_b128 v[224:227], v139 offset:7168
	global_load_lds_dwordx4 v[228:229], off
	v_lshl_add_u64 v[228:229], v[156:157], 0, s[48:49]
	s_add_i32 m0, s16, 0xe000
	s_nop 0
	global_load_lds_dwordx4 v[228:229], off
	s_waitcnt vmcnt(8)
	s_waitcnt lgkmcnt(0)
	s_barrier
	s_setprio 1
	s_waitcnt lgkmcnt(0)
	v_mfma_f32_16x16x32_bf16 v[124:127], v[160:163], v[196:199], v[124:127]
	v_mfma_f32_16x16x32_bf16 v[120:123], v[168:171], v[196:199], v[120:123]
	v_mfma_f32_16x16x32_bf16 v[112:115], v[168:171], v[204:207], v[112:115]
	v_mfma_f32_16x16x32_bf16 v[116:119], v[160:163], v[204:207], v[116:119]
	v_mfma_f32_16x16x32_bf16 v[100:103], v[160:163], v[212:215], v[100:103]
	v_mfma_f32_16x16x32_bf16 v[96:99], v[168:171], v[212:215], v[96:99]
	v_mfma_f32_16x16x32_bf16 v[80:83], v[168:171], v[220:223], v[80:83]
	v_mfma_f32_16x16x32_bf16 v[84:87], v[160:163], v[220:223], v[84:87]
	v_mfma_f32_16x16x32_bf16 v[124:127], v[164:167], v[200:203], v[124:127]
	v_mfma_f32_16x16x32_bf16 v[120:123], v[172:175], v[200:203], v[120:123]
	v_mfma_f32_16x16x32_bf16 v[112:115], v[172:175], v[208:211], v[112:115]
	v_mfma_f32_16x16x32_bf16 v[116:119], v[164:167], v[208:211], v[116:119]
	v_mfma_f32_16x16x32_bf16 v[100:103], v[164:167], v[216:219], v[100:103]
	v_mfma_f32_16x16x32_bf16 v[96:99], v[172:175], v[216:219], v[96:99]
	v_mfma_f32_16x16x32_bf16 v[80:83], v[172:175], v[224:227], v[80:83]
	v_mfma_f32_16x16x32_bf16 v[84:87], v[164:167], v[224:227], v[84:87]
	s_setprio 0
	s_setprio 1
	v_mfma_f32_16x16x32_bf16 v[108:111], v[180:183], v[196:199], v[108:111]
	v_mfma_f32_16x16x32_bf16 v[104:107], v[188:191], v[196:199], v[104:107]
	v_mfma_f32_16x16x32_bf16 v[88:91], v[188:191], v[204:207], v[88:91]
	v_mfma_f32_16x16x32_bf16 v[92:95], v[180:183], v[204:207], v[92:95]
	v_mfma_f32_16x16x32_bf16 v[76:79], v[180:183], v[212:215], v[76:79]
	v_mfma_f32_16x16x32_bf16 v[72:75], v[188:191], v[212:215], v[72:75]
	v_mfma_f32_16x16x32_bf16 v[64:67], v[188:191], v[220:223], v[64:67]
	v_mfma_f32_16x16x32_bf16 v[68:71], v[180:183], v[220:223], v[68:71]
	v_mfma_f32_16x16x32_bf16 v[108:111], v[184:187], v[200:203], v[108:111]
	v_mfma_f32_16x16x32_bf16 v[104:107], v[192:195], v[200:203], v[104:107]
	v_mfma_f32_16x16x32_bf16 v[88:91], v[192:195], v[208:211], v[88:91]
	v_mfma_f32_16x16x32_bf16 v[92:95], v[184:187], v[208:211], v[92:95]
	v_mfma_f32_16x16x32_bf16 v[76:79], v[184:187], v[216:219], v[76:79]
	v_mfma_f32_16x16x32_bf16 v[72:75], v[192:195], v[216:219], v[72:75]
	v_mfma_f32_16x16x32_bf16 v[64:67], v[192:195], v[224:227], v[64:67]
	v_mfma_f32_16x16x32_bf16 v[68:71], v[184:187], v[224:227], v[68:71]
	s_setprio 0
	s_barrier
	s_add_i32 s27, s74, s3
	v_lshl_add_u64 v[228:229], s[42:43], 0, v[176:177]
	s_mov_b32 m0, s27
	ds_read_b128 v[196:199], v139 offset:16384
	ds_read_b128 v[200:203], v139 offset:17408
	ds_read_b128 v[204:207], v139 offset:18432
	ds_read_b128 v[208:211], v139 offset:19456
	ds_read_b128 v[212:215], v139 offset:20480
	ds_read_b128 v[216:219], v139 offset:21504
	ds_read_b128 v[220:223], v139 offset:22528
	ds_read_b128 v[224:227], v139 offset:23552
	global_load_lds_dwordx4 v[228:229], off
	s_add_i32 m0, s27, 0x2000
	v_lshl_add_u64 v[230:231], s[42:43], 0, v[132:133]
	s_add_u32 s42, s42, s10
	s_addc_u32 s43, s43, s11
	s_add_i32 s17, s17, s3
	global_load_lds_dwordx4 v[230:231], off
	v_lshl_add_u64 v[232:233], s[42:43], 0, v[176:177]
	s_mov_b32 m0, s17
	v_lshl_add_u64 v[234:235], s[42:43], 0, v[132:133]
	global_load_lds_dwordx4 v[232:233], off
	s_add_i32 m0, s17, 0x2000
	v_lshl_add_u64 v[236:237], s[50:51], 0, v[128:129]
	global_load_lds_dwordx4 v[234:235], off
	s_mov_b32 m0, s16
	v_lshl_add_u64 v[246:247], s[50:51], 0, v[130:131]
	global_load_lds_dwordx4 v[236:237], off
	s_mov_b32 m0, s6
	s_nop 0
	global_load_lds_dwordx4 v[246:247], off
	s_waitcnt vmcnt(8)
	s_waitcnt lgkmcnt(0)
	s_barrier
; #define PG8_STAGE(bufoff, gbase, voff) do { _Pragma("unroll") for (int _i = 0; _i < 2; ++_i) \
;         __builtin_amdgcn_global_load_lds((const unsigned*)((const char*)(gbase) + (voff)[_i]), (LAS unsigned*)(lds + (bufoff) + ldsw + _i * 8192), 16, 0, 0); } while (0)
; #define PG8_LDA(dst, b, h) do { _Pragma("unroll") for (int m = 0; m < 4; ++m) _Pragma("unroll") for (int k = 0; k < 2; ++k) dst[m][k] = *(const LAS bf16x8*)(lds + PG8_SA(b, h) + aoff + m * 2048 + k * 1024); } while (0)
; #define PG8_LDB(dst, b, h) do { _Pragma("unroll") for (int n = 0; n < 2; ++n) _Pragma("unroll") for (int k = 0; k < 2; ++k) dst[n][k] = *(const LAS bf16x8*)(lds + PG8_SB(b, h) + boff + n * 2048 + k * 1024); } while (0)
; #define PG8_MMA(ai, bj, At, Bt) do { __builtin_amdgcn_s_setprio(1); _Pragma("unroll") for (int m = 0; m < 4; ++m) _Pragma("unroll") for (int n = 0; n < 2; ++n) _Pragma("unroll") for (int k = 0; k < 2; ++k) \
;         acc[ai][bj][m][n] = __builtin_amdgcn_mfma_f32_16x16x32_bf16(Bt[n][k], At[m][k], acc[ai][bj][m][n], 0, 0, 0); __builtin_amdgcn_s_setprio(0); } while (0)
; #define PG8_WAIT_V(n) asm volatile("s_waitcnt vmcnt(" #n ")" ::: "memory")
; #define PG8_WAIT_L(n) asm volatile("s_waitcnt lgkmcnt(" #n ")" ::: "memory")
; #define PG8_BAR __builtin_amdgcn_s_barrier()
; #define PG8_SCHED __builtin_amdgcn_sched_barrier(0)
; template <class Epi, class Sched, bool ALIGN_EPI>
; __device__ __forceinline__ void gemm_phase(LAS unsigned char* lds, const int wid, const int lda_, const int ldb_, const int K_, const Sched& S, const Epi& E) {
;     ...
;             PG8_WAIT_V(8); PG8_WAIT_L(0); PG8_BAR; PG8_MMA(1, 0, At, B0); PG8_MMA(1, 1, At, B1); PG8_BAR; PG8_SCHED;
;             PG8_LDB(B0, 1, 0); PG8_LDB(B1, 1, 1); PG8_SCHED; PG8_LDA(At, 1, 0); PG8_STAGE(PG8_SA(0, 1), a2 + hstepA, voffA);
;             PG8_WAIT_V(8); PG8_WAIT_L(0); PG8_BAR; PG8_MMA(0, 0, At, B0); PG8_MMA(0, 1, At, B1); PG8_BAR; PG8_SCHED;
	s_setprio 1
	s_waitcnt lgkmcnt(0)
	v_mfma_f32_16x16x32_bf16 v[60:63], v[160:163], v[196:199], v[60:63]
	v_mfma_f32_16x16x32_bf16 v[56:59], v[168:171], v[196:199], v[56:59]
	v_mfma_f32_16x16x32_bf16 v[48:51], v[168:171], v[204:207], v[48:51]
	v_mfma_f32_16x16x32_bf16 v[52:55], v[160:163], v[204:207], v[52:55]
	v_mfma_f32_16x16x32_bf16 v[36:39], v[160:163], v[212:215], v[36:39]
	v_mfma_f32_16x16x32_bf16 v[32:35], v[168:171], v[212:215], v[32:35]
	v_mfma_f32_16x16x32_bf16 v[16:19], v[168:171], v[220:223], v[16:19]
	v_mfma_f32_16x16x32_bf16 v[20:23], v[160:163], v[220:223], v[20:23]
	v_mfma_f32_16x16x32_bf16 v[60:63], v[164:167], v[200:203], v[60:63]
	v_mfma_f32_16x16x32_bf16 v[56:59], v[172:175], v[200:203], v[56:59]
	v_mfma_f32_16x16x32_bf16 v[48:51], v[172:175], v[208:211], v[48:51]
	v_mfma_f32_16x16x32_bf16 v[52:55], v[164:167], v[208:211], v[52:55]
	v_mfma_f32_16x16x32_bf16 v[36:39], v[164:167], v[216:219], v[36:39]
	v_mfma_f32_16x16x32_bf16 v[32:35], v[172:175], v[216:219], v[32:35]
	v_mfma_f32_16x16x32_bf16 v[16:19], v[172:175], v[224:227], v[16:19]
	v_mfma_f32_16x16x32_bf16 v[20:23], v[164:167], v[224:227], v[20:23]
	s_setprio 0
	s_setprio 1
	v_mfma_f32_16x16x32_bf16 v[44:47], v[180:183], v[196:199], v[44:47]
	v_mfma_f32_16x16x32_bf16 v[40:43], v[188:191], v[196:199], v[40:43]
	v_mfma_f32_16x16x32_bf16 v[24:27], v[188:191], v[204:207], v[24:27]
	v_mfma_f32_16x16x32_bf16 v[28:31], v[180:183], v[204:207], v[28:31]
	v_mfma_f32_16x16x32_bf16 v[12:15], v[180:183], v[212:215], v[12:15]
	v_mfma_f32_16x16x32_bf16 v[8:11], v[188:191], v[212:215], v[8:11]
	v_mfma_f32_16x16x32_bf16 v[0:3], v[188:191], v[220:223], v[0:3]
	v_mfma_f32_16x16x32_bf16 v[4:7], v[180:183], v[220:223], v[4:7]
	v_mfma_f32_16x16x32_bf16 v[44:47], v[184:187], v[200:203], v[44:47]
	v_mfma_f32_16x16x32_bf16 v[40:43], v[192:195], v[200:203], v[40:43]
	v_mfma_f32_16x16x32_bf16 v[24:27], v[192:195], v[208:211], v[24:27]
	v_mfma_f32_16x16x32_bf16 v[28:31], v[184:187], v[208:211], v[28:31]
	v_mfma_f32_16x16x32_bf16 v[12:15], v[184:187], v[216:219], v[12:15]
	v_mfma_f32_16x16x32_bf16 v[8:11], v[192:195], v[216:219], v[8:11]
	v_mfma_f32_16x16x32_bf16 v[0:3], v[192:195], v[224:227], v[0:3]
	v_mfma_f32_16x16x32_bf16 v[4:7], v[184:187], v[224:227], v[4:7]
	s_setprio 0
	s_barrier
	s_add_i32 s17, 0, 0x18000
	v_add_u32_e32 v141, s17, v135
	s_add_i32 s27, 0, 0x1c000
	ds_read_b128 v[160:163], v141
	ds_read_b128 v[164:167], v141 offset:1024
	ds_read_b128 v[168:171], v141 offset:2048
	ds_read_b128 v[172:175], v141 offset:3072
	v_add_u32_e32 v141, s27, v135
	ds_read_b128 v[180:183], v141
	ds_read_b128 v[184:187], v141 offset:1024
	ds_read_b128 v[188:191], v141 offset:2048
	ds_read_b128 v[192:195], v141 offset:3072
	s_add_u32 s42, s50, s0
	s_addc_u32 s43, s51, s1
	s_mov_b32 m0, s7
	v_lshl_add_u64 v[248:249], s[42:43], 0, v[128:129]
	ds_read_b128 v[196:199], v139 offset:32768
	ds_read_b128 v[200:203], v139 offset:33792
	ds_read_b128 v[204:207], v139 offset:34816
	ds_read_b128 v[208:211], v139 offset:35840
	ds_read_b128 v[212:215], v139 offset:36864
	ds_read_b128 v[216:219], v139 offset:37888
	ds_read_b128 v[220:223], v139 offset:38912
	ds_read_b128 v[224:227], v139 offset:39936
	global_load_lds_dwordx4 v[248:249], off
	v_lshl_add_u64 v[248:249], s[42:43], 0, v[130:131]
	s_mov_b32 m0, s14
	s_nop 0
	global_load_lds_dwordx4 v[248:249], off
	s_waitcnt vmcnt(8)
	s_waitcnt lgkmcnt(0)
	s_barrier
	s_setprio 1
	s_waitcnt lgkmcnt(0)
	v_mfma_f32_16x16x32_bf16 v[124:127], v[160:163], v[196:199], v[124:127]
	v_mfma_f32_16x16x32_bf16 v[120:123], v[168:171], v[196:199], v[120:123]
	v_mfma_f32_16x16x32_bf16 v[112:115], v[168:171], v[204:207], v[112:115]
	v_mfma_f32_16x16x32_bf16 v[116:119], v[160:163], v[204:207], v[116:119]
	v_mfma_f32_16x16x32_bf16 v[100:103], v[160:163], v[212:215], v[100:103]
	v_mfma_f32_16x16x32_bf16 v[96:99], v[168:171], v[212:215], v[96:99]
	v_mfma_f32_16x16x32_bf16 v[80:83], v[168:171], v[220:223], v[80:83]
	v_mfma_f32_16x16x32_bf16 v[84:87], v[160:163], v[220:223], v[84:87]
	v_mfma_f32_16x16x32_bf16 v[124:127], v[164:167], v[200:203], v[124:127]
	v_mfma_f32_16x16x32_bf16 v[120:123], v[172:175], v[200:203], v[120:123]
	v_mfma_f32_16x16x32_bf16 v[112:115], v[172:175], v[208:211], v[112:115]
	v_mfma_f32_16x16x32_bf16 v[116:119], v[164:167], v[208:211], v[116:119]
	v_mfma_f32_16x16x32_bf16 v[100:103], v[164:167], v[216:219], v[100:103]
	v_mfma_f32_16x16x32_bf16 v[96:99], v[172:175], v[216:219], v[96:99]
	v_mfma_f32_16x16x32_bf16 v[80:83], v[172:175], v[224:227], v[80:83]
	v_mfma_f32_16x16x32_bf16 v[84:87], v[164:167], v[224:227], v[84:87]
	s_setprio 0
	s_setprio 1
	v_mfma_f32_16x16x32_bf16 v[108:111], v[180:183], v[196:199], v[108:111]
	v_mfma_f32_16x16x32_bf16 v[104:107], v[188:191], v[196:199], v[104:107]
	v_mfma_f32_16x16x32_bf16 v[88:91], v[188:191], v[204:207], v[88:91]
	v_mfma_f32_16x16x32_bf16 v[92:95], v[180:183], v[204:207], v[92:95]
	v_mfma_f32_16x16x32_bf16 v[76:79], v[180:183], v[212:215], v[76:79]
	v_mfma_f32_16x16x32_bf16 v[72:75], v[188:191], v[212:215], v[72:75]
	v_mfma_f32_16x16x32_bf16 v[64:67], v[188:191], v[220:223], v[64:67]
	v_mfma_f32_16x16x32_bf16 v[68:71], v[180:183], v[220:223], v[68:71]
	v_mfma_f32_16x16x32_bf16 v[108:111], v[184:187], v[200:203], v[108:111]
	v_mfma_f32_16x16x32_bf16 v[104:107], v[192:195], v[200:203], v[104:107]
	v_mfma_f32_16x16x32_bf16 v[88:91], v[192:195], v[208:211], v[88:91]
	v_mfma_f32_16x16x32_bf16 v[92:95], v[184:187], v[208:211], v[92:95]
	v_mfma_f32_16x16x32_bf16 v[76:79], v[184:187], v[216:219], v[76:79]
	v_mfma_f32_16x16x32_bf16 v[72:75], v[192:195], v[216:219], v[72:75]
	v_mfma_f32_16x16x32_bf16 v[64:67], v[192:195], v[224:227], v[64:67]
	v_mfma_f32_16x16x32_bf16 v[68:71], v[184:187], v[224:227], v[68:71]
	s_setprio 0
	s_barrier
; #define PG8_STAGE(bufoff, gbase, voff) do { _Pragma("unroll") for (int _i = 0; _i < 2; ++_i) \
;         __builtin_amdgcn_global_load_lds((const unsigned*)((const char*)(gbase) + (voff)[_i]), (LAS unsigned*)(lds + (bufoff) + ldsw + _i * 8192), 16, 0, 0); } while (0)
; #define PG8_LDA(dst, b, h) do { _Pragma("unroll") for (int m = 0; m < 4; ++m) _Pragma("unroll") for (int k = 0; k < 2; ++k) dst[m][k] = *(const LAS bf16x8*)(lds + PG8_SA(b, h) + aoff + m * 2048 + k * 1024); } while (0)
; #define PG8_MMA(ai, bj, At, Bt) do { __builtin_amdgcn_s_setprio(1); _Pragma("unroll") for (int m = 0; m < 4; ++m) _Pragma("unroll") for (int n = 0; n < 2; ++n) _Pragma("unroll") for (int k = 0; k < 2; ++k) \
;         acc[ai][bj][m][n] = __builtin_amdgcn_mfma_f32_16x16x32_bf16(Bt[n][k], At[m][k], acc[ai][bj][m][n], 0, 0, 0); __builtin_amdgcn_s_setprio(0); } while (0)
; #define PG8_WAIT_V(n) asm volatile("s_waitcnt vmcnt(" #n ")" ::: "memory")
; #define PG8_WAIT_L(n) asm volatile("s_waitcnt lgkmcnt(" #n ")" ::: "memory")
; #define PG8_BAR __builtin_amdgcn_s_barrier()
; #define PG8_SCHED __builtin_amdgcn_sched_barrier(0)
; template <class Epi, class Sched, bool ALIGN_EPI>
; __device__ __forceinline__ void gemm_phase(LAS unsigned char* lds, const int wid, const int lda_, const int ldb_, const int K_, const Sched& S, const Epi& E) {
;     ...
;             PG8_LDA(At, 1, 1); PG8_STAGE(PG8_SB(1, 0), b3, voffB); PG8_STAGE(PG8_SB(1, 1), b3 + hstepB, voffB); PG8_STAGE(PG8_SA(1, 0), a3, voffA);
;             PG8_WAIT_V(8); PG8_WAIT_L(0); PG8_BAR; PG8_MMA(1, 0, At, B0); PG8_MMA(1, 1, At, B1); PG8_BAR; PG8_SCHED;
;         }
	s_add_i32 s17, s17, s3
	v_lshl_add_u64 v[228:229], v[228:229], 0, s[24:25]
	s_mov_b32 m0, s17
	ds_read_b128 v[196:199], v139 offset:49152
	ds_read_b128 v[200:203], v139 offset:50176
	ds_read_b128 v[204:207], v139 offset:51200
	ds_read_b128 v[208:211], v139 offset:52224
	ds_read_b128 v[212:215], v139 offset:53248
	ds_read_b128 v[216:219], v139 offset:54272
	ds_read_b128 v[220:223], v139 offset:55296
	ds_read_b128 v[224:227], v139 offset:56320
	global_load_lds_dwordx4 v[228:229], off
	v_lshl_add_u64 v[228:229], v[230:231], 0, s[24:25]
	s_add_i32 m0, s17, 0x2000
	s_add_i32 s17, s27, s3
	global_load_lds_dwordx4 v[228:229], off
	v_lshl_add_u64 v[228:229], v[232:233], 0, s[24:25]
	s_mov_b32 m0, s17
	s_nop 0
	global_load_lds_dwordx4 v[228:229], off
	v_lshl_add_u64 v[228:229], v[234:235], 0, s[24:25]
	s_add_i32 m0, s17, 0x2000
	s_nop 0
	global_load_lds_dwordx4 v[228:229], off
	v_lshl_add_u64 v[228:229], v[236:237], 0, s[24:25]
	s_mov_b32 m0, s15
	s_nop 0
	global_load_lds_dwordx4 v[228:229], off
	v_lshl_add_u64 v[228:229], v[246:247], 0, s[24:25]
	s_mov_b32 m0, s26
	s_nop 0
	global_load_lds_dwordx4 v[228:229], off
	s_waitcnt vmcnt(8)
	s_waitcnt lgkmcnt(0)
	s_barrier
	s_setprio 1
	s_waitcnt lgkmcnt(0)
	v_mfma_f32_16x16x32_bf16 v[60:63], v[160:163], v[196:199], v[60:63]
	v_mfma_f32_16x16x32_bf16 v[56:59], v[168:171], v[196:199], v[56:59]
	v_mfma_f32_16x16x32_bf16 v[48:51], v[168:171], v[204:207], v[48:51]
	v_mfma_f32_16x16x32_bf16 v[52:55], v[160:163], v[204:207], v[52:55]
	v_mfma_f32_16x16x32_bf16 v[36:39], v[160:163], v[212:215], v[36:39]
	v_mfma_f32_16x16x32_bf16 v[32:35], v[168:171], v[212:215], v[32:35]
	v_mfma_f32_16x16x32_bf16 v[16:19], v[168:171], v[220:223], v[16:19]
	v_mfma_f32_16x16x32_bf16 v[20:23], v[160:163], v[220:223], v[20:23]
	v_mfma_f32_16x16x32_bf16 v[60:63], v[164:167], v[200:203], v[60:63]
	v_mfma_f32_16x16x32_bf16 v[56:59], v[172:175], v[200:203], v[56:59]
	v_mfma_f32_16x16x32_bf16 v[48:51], v[172:175], v[208:211], v[48:51]
	v_mfma_f32_16x16x32_bf16 v[52:55], v[164:167], v[208:211], v[52:55]
	v_mfma_f32_16x16x32_bf16 v[36:39], v[164:167], v[216:219], v[36:39]
	v_mfma_f32_16x16x32_bf16 v[32:35], v[172:175], v[216:219], v[32:35]
	v_mfma_f32_16x16x32_bf16 v[16:19], v[172:175], v[224:227], v[16:19]
	v_mfma_f32_16x16x32_bf16 v[20:23], v[164:167], v[224:227], v[20:23]
	s_setprio 0
	s_setprio 1
	v_mfma_f32_16x16x32_bf16 v[44:47], v[180:183], v[196:199], v[44:47]
	v_mfma_f32_16x16x32_bf16 v[40:43], v[188:191], v[196:199], v[40:43]
	v_mfma_f32_16x16x32_bf16 v[24:27], v[188:191], v[204:207], v[24:27]
	v_mfma_f32_16x16x32_bf16 v[28:31], v[180:183], v[204:207], v[28:31]
	v_mfma_f32_16x16x32_bf16 v[12:15], v[180:183], v[212:215], v[12:15]
	v_mfma_f32_16x16x32_bf16 v[8:11], v[188:191], v[212:215], v[8:11]
	v_mfma_f32_16x16x32_bf16 v[0:3], v[188:191], v[220:223], v[0:3]
	v_mfma_f32_16x16x32_bf16 v[4:7], v[180:183], v[220:223], v[4:7]
	v_mfma_f32_16x16x32_bf16 v[44:47], v[184:187], v[200:203], v[44:47]
	v_mfma_f32_16x16x32_bf16 v[40:43], v[192:195], v[200:203], v[40:43]
	v_mfma_f32_16x16x32_bf16 v[24:27], v[192:195], v[208:211], v[24:27]
	v_mfma_f32_16x16x32_bf16 v[28:31], v[184:187], v[208:211], v[28:31]
	v_mfma_f32_16x16x32_bf16 v[12:15], v[184:187], v[216:219], v[12:15]
	v_mfma_f32_16x16x32_bf16 v[8:11], v[192:195], v[216:219], v[8:11]
	v_mfma_f32_16x16x32_bf16 v[0:3], v[192:195], v[224:227], v[0:3]
	v_mfma_f32_16x16x32_bf16 v[4:7], v[184:187], v[224:227], v[4:7]
	s_setprio 0
	s_barrier
	s_add_i32 s73, s73, 2
	s_add_u32 s48, s48, 0x100
	s_addc_u32 s49, s49, 0
	s_cmp_gt_u32 s73, 5
	s_cbranch_scc0 .LBB0_883
; __device__ __forceinline__ unsigned cvt_pk_bf16(float lo, float hi) { const f32x2 v = {lo, hi}; return __builtin_bit_cast(unsigned, __builtin_convertvector(v, bf16x2_t)); }
;     template <class Sched> __device__ __forceinline__ void operator()(const f32x4 (&acc)[2][2][4][2], const Unit& u, const Sched& S, int wr, int wc, int fr, int fq) const {
;     ...
;         if (kind == 0) {
;             bf16_t* base = (bf16_t*)uo;
; #pragma unroll
;             for (int ai = 0; ai < 2; ++ai)
; #pragma unroll
;                 for (int m = 0; m < 4; ++m) { bf16_t* rowp = base + (size_t)(rl0 + ai * HALF + m * 16) * ldo + cl0;
; #pragma unroll
;                     for (int bj = 0; bj < 2; ++bj) { const f32x4 v0 = acc[ai][bj][m][0], v1 = acc[ai][bj][m][1];
;                         u32x4 w; w.x = cvt_pk_bf16(v0[0], v0[1]); w.y = cvt_pk_bf16(v0[2], v0[3]); w.z = cvt_pk_bf16(v1[0], v1[1]); w.w = cvt_pk_bf16(v1[2], v1[3]);
;                         *(u32x4*)(rowp + bj * HALF) = w; } }
;         if (u.pm < 64) { o = (char*)ws + WS_F + (((size_t)((u.pm >> 3) * 2048 + (u.pm & 7))) * D + (size_t)u.pn * 256) * 2; ldo = 8 * D; }
;         else { o = (char*)ws + WS_F + (((size_t)(MLAT + (u.pm - 64) * 256)) * D + (size_t)u.pn * 256) * 2; ldo = D; } }
	s_lshl_b32 s4, s41, 8
	s_and_b32 s5, s4, 0xfffff800
	s_and_b32 s17, s41, 7
	s_or_b32 s17, s5, s17
	s_ashr_i32 s5, s17, 31
	s_cmp_lt_i32 s41, 64
	s_cselect_b32 s4, s17, s4
	s_movk_i32 s17, 0x800
	s_cselect_b32 s5, s5, 0
	s_cselect_b32 s17, 0x4000, s17
	s_ashr_i32 s41, s40, 31
	s_lshl_b64 s[40:41], s[40:41], 9
	s_lshl_b64 s[4:5], s[4:5], 12
	v_readlane_b32 s27, v254, 19
	s_add_u32 s4, s27, s4
	v_readlane_b32 s27, v254, 20
	s_addc_u32 s5, s27, s5
	s_add_u32 s4, s4, s40
	s_addc_u32 s5, s5, s41
	v_lshl_add_u64 v[156:157], v[136:137], 1, s[4:5]
	v_mad_i64_i32 v[158:159], s[4:5], s17, v134, 0
	v_lshl_add_u64 v[158:159], v[158:159], 1, v[156:157]
	v_cvt_pk_bf16_f32 v108, v108, v109
	v_cvt_pk_bf16_f32 v109, v110, v111
	v_cvt_pk_bf16_f32 v110, v104, v105
	v_cvt_pk_bf16_f32 v111, v106, v107
	v_mad_i64_i32 v[104:105], s[4:5], s17, v138, 0
	v_cvt_pk_bf16_f32 v124, v124, v125
	v_cvt_pk_bf16_f32 v125, v126, v127
	v_cvt_pk_bf16_f32 v126, v120, v121
	v_cvt_pk_bf16_f32 v127, v122, v123
	global_store_dwordx4 v[158:159], v[108:111], off offset:256
	v_cvt_pk_bf16_f32 v92, v92, v93
	v_cvt_pk_bf16_f32 v93, v94, v95
	v_lshl_add_u64 v[108:109], v[104:105], 1, v[156:157]
	v_cvt_pk_bf16_f32 v94, v88, v89
	v_cvt_pk_bf16_f32 v95, v90, v91
	v_mad_i64_i32 v[88:89], s[4:5], s17, v140, 0
	global_store_dwordx4 v[158:159], v[124:127], off
	v_cvt_pk_bf16_f32 v104, v116, v117
	v_cvt_pk_bf16_f32 v105, v118, v119
	v_cvt_pk_bf16_f32 v106, v112, v113
	v_cvt_pk_bf16_f32 v107, v114, v115
	global_store_dwordx4 v[108:109], v[92:95], off offset:256
	v_cvt_pk_bf16_f32 v76, v76, v77
	v_cvt_pk_bf16_f32 v77, v78, v79
	v_lshl_add_u64 v[92:93], v[88:89], 1, v[156:157]
	v_cvt_pk_bf16_f32 v78, v72, v73
	v_cvt_pk_bf16_f32 v79, v74, v75
	v_mad_i64_i32 v[72:73], s[4:5], s17, v142, 0
	v_cvt_pk_bf16_f32 v68, v68, v69
	v_cvt_pk_bf16_f32 v69, v70, v71
	v_cvt_pk_bf16_f32 v70, v64, v65
	v_mad_i64_i32 v[64:65], s[4:5], s17, v144, 0
	global_store_dwordx4 v[108:109], v[104:107], off
	v_cvt_pk_bf16_f32 v88, v100, v101
	v_cvt_pk_bf16_f32 v89, v102, v103
	v_cvt_pk_bf16_f32 v90, v96, v97
	v_cvt_pk_bf16_f32 v91, v98, v99
	global_store_dwordx4 v[92:93], v[76:79], off offset:256
	v_cvt_pk_bf16_f32 v74, v80, v81
	v_cvt_pk_bf16_f32 v75, v82, v83
	v_lshl_add_u64 v[76:77], v[72:73], 1, v[156:157]
	v_cvt_pk_bf16_f32 v72, v84, v85
	v_cvt_pk_bf16_f32 v73, v86, v87
	v_cvt_pk_bf16_f32 v71, v66, v67
	v_lshl_add_u64 v[64:65], v[64:65], 1, v[156:157]
	v_cvt_pk_bf16_f32 v44, v44, v45
	v_cvt_pk_bf16_f32 v45, v46, v47
	v_cvt_pk_bf16_f32 v46, v40, v41
	v_cvt_pk_bf16_f32 v47, v42, v43
	v_mad_i64_i32 v[40:41], s[4:5], s17, v146, 0
	global_store_dwordx4 v[92:93], v[88:91], off
	global_store_dwordx4 v[76:77], v[72:75], off
	global_store_dwordx4 v[76:77], v[68:71], off offset:256
	v_cvt_pk_bf16_f32 v60, v60, v61
	v_cvt_pk_bf16_f32 v61, v62, v63
	v_cvt_pk_bf16_f32 v62, v56, v57
	v_cvt_pk_bf16_f32 v63, v58, v59
	global_store_dwordx4 v[64:65], v[44:47], off offset:256
	v_cvt_pk_bf16_f32 v28, v28, v29
	v_cvt_pk_bf16_f32 v29, v30, v31
	v_lshl_add_u64 v[44:45], v[40:41], 1, v[156:157]
	v_cvt_pk_bf16_f32 v30, v24, v25
	v_cvt_pk_bf16_f32 v31, v26, v27
	v_mad_i64_i32 v[24:25], s[4:5], s17, v148, 0
	global_store_dwordx4 v[64:65], v[60:63], off
	v_cvt_pk_bf16_f32 v40, v52, v53
	v_cvt_pk_bf16_f32 v41, v54, v55
	v_cvt_pk_bf16_f32 v42, v48, v49
	v_cvt_pk_bf16_f32 v43, v50, v51
	global_store_dwordx4 v[44:45], v[28:31], off offset:256
	v_cvt_pk_bf16_f32 v12, v12, v13
	v_cvt_pk_bf16_f32 v13, v14, v15
	v_lshl_add_u64 v[28:29], v[24:25], 1, v[156:157]
	v_cvt_pk_bf16_f32 v14, v8, v9
	v_cvt_pk_bf16_f32 v15, v10, v11
	v_mad_i64_i32 v[8:9], s[4:5], s17, v150, 0
	global_store_dwordx4 v[44:45], v[40:43], off
	v_cvt_pk_bf16_f32 v24, v36, v37
	v_cvt_pk_bf16_f32 v25, v38, v39
	v_cvt_pk_bf16_f32 v26, v32, v33
	v_cvt_pk_bf16_f32 v27, v34, v35
	global_store_dwordx4 v[28:29], v[12:15], off offset:256
	v_cvt_pk_bf16_f32 v10, v16, v17
	v_cvt_pk_bf16_f32 v11, v18, v19
	v_lshl_add_u64 v[12:13], v[8:9], 1, v[156:157]
	v_cvt_pk_bf16_f32 v8, v20, v21
	v_cvt_pk_bf16_f32 v9, v22, v23
	v_cvt_pk_bf16_f32 v4, v4, v5
	v_cvt_pk_bf16_f32 v5, v6, v7
	v_cvt_pk_bf16_f32 v6, v0, v1
	v_cvt_pk_bf16_f32 v7, v2, v3
	s_and_b64 vcc, exec, s[36:37]
	s_mov_b32 s40, s30
	s_mov_b32 s41, s34
	s_mov_b64 s[48:49], s[38:39]
	s_mov_b64 s[46:47], s[44:45]
	global_store_dwordx4 v[28:29], v[24:27], off
	global_store_dwordx4 v[12:13], v[8:11], off
	global_store_dwordx4 v[12:13], v[4:7], off offset:256
	s_cbranch_vccz .LBB0_868
	v_readlane_b32 s0, v253, 1
	s_waitcnt vmcnt(0)
	v_readlane_b32 s1, v253, 2
	v_readlane_b32 s72, v255, 28
	s_andn2_b64 vcc, exec, s[0:1]
	v_readlane_b32 s73, v255, 29
	s_cbranch_vccnz .LBB0_887
	s_barrier

; #define PG8_STAGE(bufoff, gbase, voff) do { _Pragma("unroll") for (int _i = 0; _i < 2; ++_i) \
;         __builtin_amdgcn_global_load_lds((const unsigned*)((const char*)(gbase) + (voff)[_i]), (LAS unsigned*)(lds + (bufoff) + ldsw + _i * 8192), 16, 0, 0); } while (0)
; #define PG8_LDA(dst, b, h) do { _Pragma("unroll") for (int m = 0; m < 4; ++m) _Pragma("unroll") for (int k = 0; k < 2; ++k) dst[m][k] = *(const LAS bf16x8*)(lds + PG8_SA(b, h) + aoff + m * 2048 + k * 1024); } while (0)
; #define PG8_LDB(dst, b, h) do { _Pragma("unroll") for (int n = 0; n < 2; ++n) _Pragma("unroll") for (int k = 0; k < 2; ++k) dst[n][k] = *(const LAS bf16x8*)(lds + PG8_SB(b, h) + boff + n * 2048 + k * 1024); } while (0)
; #define PG8_MMA(ai, bj, At, Bt) do { __builtin_amdgcn_s_setprio(1); _Pragma("unroll") for (int m = 0; m < 4; ++m) _Pragma("unroll") for (int n = 0; n < 2; ++n) _Pragma("unroll") for (int k = 0; k < 2; ++k) \
;         acc[ai][bj][m][n] = __builtin_amdgcn_mfma_f32_16x16x32_bf16(Bt[n][k], At[m][k], acc[ai][bj][m][n], 0, 0, 0); __builtin_amdgcn_s_setprio(0); } while (0)
; #define PG8_WAIT_V(n) asm volatile("s_waitcnt vmcnt(" #n ")" ::: "memory")
; #define PG8_WAIT_L(n) asm volatile("s_waitcnt lgkmcnt(" #n ")" ::: "memory")
; #define PG8_BAR __builtin_amdgcn_s_barrier()
; #define PG8_SCHED __builtin_amdgcn_sched_barrier(0)
; template <class Epi, class Sched, bool ALIGN_EPI>
; __device__ __forceinline__ void gemm_phase(LAS unsigned char* lds, const int wid, const int lda_, const int ldb_, const int K_, const Sched& S, const Epi& E) {
;     ...
;             PG8_LDB(B0, 0, 0); PG8_LDB(B1, 0, 1); PG8_SCHED; PG8_LDA(At, 0, 0); PG8_STAGE(PG8_SA(1, 1), a1 + hstepA, voffA);
;             PG8_WAIT_V(8); PG8_WAIT_L(0); PG8_BAR; PG8_MMA(0, 0, At, B0); PG8_MMA(0, 1, At, B1); PG8_BAR; PG8_SCHED;
;             PG8_LDA(At, 0, 1); PG8_STAGE(PG8_SB(0, 0), b2, voffB); PG8_STAGE(PG8_SB(0, 1), b2 + hstepB, voffB); PG8_STAGE(PG8_SA(0, 0), a2, voffA);
;             PG8_WAIT_V(8); PG8_WAIT_L(0); PG8_BAR; PG8_MMA(1, 0, At, B0); PG8_MMA(1, 1, At, B1); PG8_BAR; PG8_SCHED;
.LBB0_962:
	s_add_i32 s78, s77, 2
	s_add_u32 s17, s94, 0x80
	s_addc_u32 s27, s95, 0
	s_add_i32 s79, 0, 0x10000
	s_cmp_eq_u32 s31, s77
	s_cselect_b32 s97, s35, s27
	s_cselect_b32 s96, s47, s17
	v_add_u32_e32 v141, s79, v135
	s_cselect_b32 s43, s4, s76
	s_cselect_b32 s42, s5, s49
	s_add_i32 s17, 0, 0x14000
	ds_read_b128 v[156:159], v141
	ds_read_b128 v[160:163], v141 offset:1024
	ds_read_b128 v[164:167], v141 offset:2048
	ds_read_b128 v[168:171], v141 offset:3072
	v_add_u32_e32 v141, s17, v135
	ds_read_b128 v[172:175], v141
	ds_read_b128 v[180:183], v141 offset:1024
	ds_read_b128 v[184:187], v141 offset:2048
	ds_read_b128 v[188:191], v141 offset:3072
	v_lshl_add_u64 v[224:225], s[94:95], 0, v[152:153]
	s_add_i32 m0, s16, 0xc000
	ds_read_b128 v[192:195], v139
	ds_read_b128 v[196:199], v139 offset:1024
	ds_read_b128 v[200:203], v139 offset:2048
	ds_read_b128 v[204:207], v139 offset:3072
	ds_read_b128 v[208:211], v139 offset:4096
	ds_read_b128 v[212:215], v139 offset:5120
	ds_read_b128 v[216:219], v139 offset:6144
	ds_read_b128 v[220:223], v139 offset:7168
	global_load_lds_dwordx4 v[224:225], off
	v_lshl_add_u64 v[224:225], s[94:95], 0, v[154:155]
	s_add_i32 m0, s16, 0xe000
	s_nop 0
	global_load_lds_dwordx4 v[224:225], off
	s_waitcnt vmcnt(8)
	s_waitcnt lgkmcnt(0)
	s_barrier
	s_setprio 1
	s_waitcnt lgkmcnt(0)
	v_mfma_f32_16x16x32_bf16 v[124:127], v[156:159], v[192:195], v[124:127]
	v_mfma_f32_16x16x32_bf16 v[120:123], v[164:167], v[192:195], v[120:123]
	v_mfma_f32_16x16x32_bf16 v[112:115], v[164:167], v[200:203], v[112:115]
	v_mfma_f32_16x16x32_bf16 v[116:119], v[156:159], v[200:203], v[116:119]
	v_mfma_f32_16x16x32_bf16 v[100:103], v[156:159], v[208:211], v[100:103]
	v_mfma_f32_16x16x32_bf16 v[96:99], v[164:167], v[208:211], v[96:99]
	v_mfma_f32_16x16x32_bf16 v[80:83], v[164:167], v[216:219], v[80:83]
	v_mfma_f32_16x16x32_bf16 v[84:87], v[156:159], v[216:219], v[84:87]
	v_mfma_f32_16x16x32_bf16 v[124:127], v[160:163], v[196:199], v[124:127]
	v_mfma_f32_16x16x32_bf16 v[120:123], v[168:171], v[196:199], v[120:123]
	v_mfma_f32_16x16x32_bf16 v[112:115], v[168:171], v[204:207], v[112:115]
	v_mfma_f32_16x16x32_bf16 v[116:119], v[160:163], v[204:207], v[116:119]
	v_mfma_f32_16x16x32_bf16 v[100:103], v[160:163], v[212:215], v[100:103]
	v_mfma_f32_16x16x32_bf16 v[96:99], v[168:171], v[212:215], v[96:99]
	v_mfma_f32_16x16x32_bf16 v[80:83], v[168:171], v[220:223], v[80:83]
	v_mfma_f32_16x16x32_bf16 v[84:87], v[160:163], v[220:223], v[84:87]
	s_setprio 0
	s_setprio 1
	v_mfma_f32_16x16x32_bf16 v[108:111], v[172:175], v[192:195], v[108:111]
	v_mfma_f32_16x16x32_bf16 v[104:107], v[184:187], v[192:195], v[104:107]
	v_mfma_f32_16x16x32_bf16 v[88:91], v[184:187], v[200:203], v[88:91]
	v_mfma_f32_16x16x32_bf16 v[92:95], v[172:175], v[200:203], v[92:95]
	v_mfma_f32_16x16x32_bf16 v[76:79], v[172:175], v[208:211], v[76:79]
	v_mfma_f32_16x16x32_bf16 v[72:75], v[184:187], v[208:211], v[72:75]
	v_mfma_f32_16x16x32_bf16 v[64:67], v[184:187], v[216:219], v[64:67]
	v_mfma_f32_16x16x32_bf16 v[68:71], v[172:175], v[216:219], v[68:71]
	v_mfma_f32_16x16x32_bf16 v[108:111], v[180:183], v[196:199], v[108:111]
	v_mfma_f32_16x16x32_bf16 v[104:107], v[188:191], v[196:199], v[104:107]
	v_mfma_f32_16x16x32_bf16 v[88:91], v[188:191], v[204:207], v[88:91]
	v_mfma_f32_16x16x32_bf16 v[92:95], v[180:183], v[204:207], v[92:95]
	v_mfma_f32_16x16x32_bf16 v[76:79], v[180:183], v[212:215], v[76:79]
	v_mfma_f32_16x16x32_bf16 v[72:75], v[188:191], v[212:215], v[72:75]
	v_mfma_f32_16x16x32_bf16 v[64:67], v[188:191], v[220:223], v[64:67]
	v_mfma_f32_16x16x32_bf16 v[68:71], v[180:183], v[220:223], v[68:71]
	s_setprio 0
	s_barrier
	s_add_i32 s27, s79, s3
	v_lshl_add_u64 v[224:225], s[42:43], 0, v[176:177]
	s_mov_b32 m0, s27
	ds_read_b128 v[192:195], v139 offset:16384
	ds_read_b128 v[196:199], v139 offset:17408
	ds_read_b128 v[200:203], v139 offset:18432
	ds_read_b128 v[204:207], v139 offset:19456
	ds_read_b128 v[208:211], v139 offset:20480
	ds_read_b128 v[212:215], v139 offset:21504
	ds_read_b128 v[216:219], v139 offset:22528
	ds_read_b128 v[220:223], v139 offset:23552
	global_load_lds_dwordx4 v[224:225], off
	s_add_i32 m0, s27, 0x2000
	v_lshl_add_u64 v[226:227], s[42:43], 0, v[128:129]
	s_add_u32 s42, s42, s10
	s_addc_u32 s43, s43, s11
	s_add_i32 s17, s17, s3
	global_load_lds_dwordx4 v[226:227], off
	v_lshl_add_u64 v[228:229], s[42:43], 0, v[176:177]
	s_mov_b32 m0, s17
	v_lshl_add_u64 v[230:231], s[42:43], 0, v[128:129]
	global_load_lds_dwordx4 v[228:229], off
	s_add_i32 m0, s17, 0x2000
	v_lshl_add_u64 v[232:233], s[96:97], 0, v[132:133]
	global_load_lds_dwordx4 v[230:231], off
	s_mov_b32 m0, s16
	v_lshl_add_u64 v[234:235], s[96:97], 0, v[130:131]
	global_load_lds_dwordx4 v[232:233], off
	s_mov_b32 m0, s14
	s_nop 0
	global_load_lds_dwordx4 v[234:235], off
	s_waitcnt vmcnt(8)
	s_waitcnt lgkmcnt(0)
	s_barrier
; #define PG8_STAGE(bufoff, gbase, voff) do { _Pragma("unroll") for (int _i = 0; _i < 2; ++_i) \
;         __builtin_amdgcn_global_load_lds((const unsigned*)((const char*)(gbase) + (voff)[_i]), (LAS unsigned*)(lds + (bufoff) + ldsw + _i * 8192), 16, 0, 0); } while (0)
; #define PG8_LDA(dst, b, h) do { _Pragma("unroll") for (int m = 0; m < 4; ++m) _Pragma("unroll") for (int k = 0; k < 2; ++k) dst[m][k] = *(const LAS bf16x8*)(lds + PG8_SA(b, h) + aoff + m * 2048 + k * 1024); } while (0)
; #define PG8_LDB(dst, b, h) do { _Pragma("unroll") for (int n = 0; n < 2; ++n) _Pragma("unroll") for (int k = 0; k < 2; ++k) dst[n][k] = *(const LAS bf16x8*)(lds + PG8_SB(b, h) + boff + n * 2048 + k * 1024); } while (0)
; #define PG8_MMA(ai, bj, At, Bt) do { __builtin_amdgcn_s_setprio(1); _Pragma("unroll") for (int m = 0; m < 4; ++m) _Pragma("unroll") for (int n = 0; n < 2; ++n) _Pragma("unroll") for (int k = 0; k < 2; ++k) \
;         acc[ai][bj][m][n] = __builtin_amdgcn_mfma_f32_16x16x32_bf16(Bt[n][k], At[m][k], acc[ai][bj][m][n], 0, 0, 0); __builtin_amdgcn_s_setprio(0); } while (0)
; #define PG8_WAIT_V(n) asm volatile("s_waitcnt vmcnt(" #n ")" ::: "memory")
; #define PG8_WAIT_L(n) asm volatile("s_waitcnt lgkmcnt(" #n ")" ::: "memory")
; #define PG8_BAR __builtin_amdgcn_s_barrier()
; #define PG8_SCHED __builtin_amdgcn_sched_barrier(0)
; template <class Epi, class Sched, bool ALIGN_EPI>
; __device__ __forceinline__ void gemm_phase(LAS unsigned char* lds, const int wid, const int lda_, const int ldb_, const int K_, const Sched& S, const Epi& E) {
;     ...
;             PG8_WAIT_V(8); PG8_WAIT_L(0); PG8_BAR; PG8_MMA(1, 0, At, B0); PG8_MMA(1, 1, At, B1); PG8_BAR; PG8_SCHED;
;             PG8_LDB(B0, 1, 0); PG8_LDB(B1, 1, 1); PG8_SCHED; PG8_LDA(At, 1, 0); PG8_STAGE(PG8_SA(0, 1), a2 + hstepA, voffA);
;             PG8_WAIT_V(8); PG8_WAIT_L(0); PG8_BAR; PG8_MMA(0, 0, At, B0); PG8_MMA(0, 1, At, B1); PG8_BAR; PG8_SCHED;
	s_setprio 1
	s_waitcnt lgkmcnt(0)
	v_mfma_f32_16x16x32_bf16 v[60:63], v[156:159], v[192:195], v[60:63]
	v_mfma_f32_16x16x32_bf16 v[56:59], v[164:167], v[192:195], v[56:59]
	v_mfma_f32_16x16x32_bf16 v[48:51], v[164:167], v[200:203], v[48:51]
	v_mfma_f32_16x16x32_bf16 v[52:55], v[156:159], v[200:203], v[52:55]
	v_mfma_f32_16x16x32_bf16 v[36:39], v[156:159], v[208:211], v[36:39]
	v_mfma_f32_16x16x32_bf16 v[32:35], v[164:167], v[208:211], v[32:35]
	v_mfma_f32_16x16x32_bf16 v[16:19], v[164:167], v[216:219], v[16:19]
	v_mfma_f32_16x16x32_bf16 v[20:23], v[156:159], v[216:219], v[20:23]
	v_mfma_f32_16x16x32_bf16 v[60:63], v[160:163], v[196:199], v[60:63]
	v_mfma_f32_16x16x32_bf16 v[56:59], v[168:171], v[196:199], v[56:59]
	v_mfma_f32_16x16x32_bf16 v[48:51], v[168:171], v[204:207], v[48:51]
	v_mfma_f32_16x16x32_bf16 v[52:55], v[160:163], v[204:207], v[52:55]
	v_mfma_f32_16x16x32_bf16 v[36:39], v[160:163], v[212:215], v[36:39]
	v_mfma_f32_16x16x32_bf16 v[32:35], v[168:171], v[212:215], v[32:35]
	v_mfma_f32_16x16x32_bf16 v[16:19], v[168:171], v[220:223], v[16:19]
	v_mfma_f32_16x16x32_bf16 v[20:23], v[160:163], v[220:223], v[20:23]
	s_setprio 0
	s_setprio 1
	v_mfma_f32_16x16x32_bf16 v[44:47], v[172:175], v[192:195], v[44:47]
	v_mfma_f32_16x16x32_bf16 v[40:43], v[184:187], v[192:195], v[40:43]
	v_mfma_f32_16x16x32_bf16 v[24:27], v[184:187], v[200:203], v[24:27]
	v_mfma_f32_16x16x32_bf16 v[28:31], v[172:175], v[200:203], v[28:31]
	v_mfma_f32_16x16x32_bf16 v[12:15], v[172:175], v[208:211], v[12:15]
	v_mfma_f32_16x16x32_bf16 v[8:11], v[184:187], v[208:211], v[8:11]
	v_mfma_f32_16x16x32_bf16 v[0:3], v[184:187], v[216:219], v[0:3]
	v_mfma_f32_16x16x32_bf16 v[4:7], v[172:175], v[216:219], v[4:7]
	v_mfma_f32_16x16x32_bf16 v[44:47], v[180:183], v[196:199], v[44:47]
	v_mfma_f32_16x16x32_bf16 v[40:43], v[188:191], v[196:199], v[40:43]
	v_mfma_f32_16x16x32_bf16 v[24:27], v[188:191], v[204:207], v[24:27]
	v_mfma_f32_16x16x32_bf16 v[28:31], v[180:183], v[204:207], v[28:31]
	v_mfma_f32_16x16x32_bf16 v[12:15], v[180:183], v[212:215], v[12:15]
	v_mfma_f32_16x16x32_bf16 v[8:11], v[188:191], v[212:215], v[8:11]
	v_mfma_f32_16x16x32_bf16 v[0:3], v[188:191], v[220:223], v[0:3]
	v_mfma_f32_16x16x32_bf16 v[4:7], v[180:183], v[220:223], v[4:7]
	s_setprio 0
	s_barrier
	s_add_i32 s17, 0, 0x18000
	v_add_u32_e32 v141, s17, v135
	s_add_i32 s27, 0, 0x1c000
	ds_read_b128 v[156:159], v141
	ds_read_b128 v[160:163], v141 offset:1024
	ds_read_b128 v[164:167], v141 offset:2048
	ds_read_b128 v[168:171], v141 offset:3072
	v_add_u32_e32 v141, s27, v135
	ds_read_b128 v[172:175], v141
	ds_read_b128 v[180:183], v141 offset:1024
	ds_read_b128 v[184:187], v141 offset:2048
	ds_read_b128 v[188:191], v141 offset:3072
	s_add_u32 s42, s96, s0
	s_addc_u32 s43, s97, s1
	s_mov_b32 m0, s15
	v_lshl_add_u64 v[236:237], s[42:43], 0, v[132:133]
	ds_read_b128 v[192:195], v139 offset:32768
	ds_read_b128 v[196:199], v139 offset:33792
	ds_read_b128 v[200:203], v139 offset:34816
	ds_read_b128 v[204:207], v139 offset:35840
	ds_read_b128 v[208:211], v139 offset:36864
	ds_read_b128 v[212:215], v139 offset:37888
	ds_read_b128 v[216:219], v139 offset:38912
	ds_read_b128 v[220:223], v139 offset:39936
	global_load_lds_dwordx4 v[236:237], off
	v_lshl_add_u64 v[236:237], s[42:43], 0, v[130:131]
	s_mov_b32 m0, s26
	s_nop 0
	global_load_lds_dwordx4 v[236:237], off
	s_waitcnt vmcnt(8)
	s_waitcnt lgkmcnt(0)
	s_barrier
	s_setprio 1
	s_waitcnt lgkmcnt(0)
	v_mfma_f32_16x16x32_bf16 v[124:127], v[156:159], v[192:195], v[124:127]
	v_mfma_f32_16x16x32_bf16 v[120:123], v[164:167], v[192:195], v[120:123]
	v_mfma_f32_16x16x32_bf16 v[112:115], v[164:167], v[200:203], v[112:115]
	v_mfma_f32_16x16x32_bf16 v[116:119], v[156:159], v[200:203], v[116:119]
	v_mfma_f32_16x16x32_bf16 v[100:103], v[156:159], v[208:211], v[100:103]
	v_mfma_f32_16x16x32_bf16 v[96:99], v[164:167], v[208:211], v[96:99]
	v_mfma_f32_16x16x32_bf16 v[80:83], v[164:167], v[216:219], v[80:83]
	v_mfma_f32_16x16x32_bf16 v[84:87], v[156:159], v[216:219], v[84:87]
	v_mfma_f32_16x16x32_bf16 v[124:127], v[160:163], v[196:199], v[124:127]
	v_mfma_f32_16x16x32_bf16 v[120:123], v[168:171], v[196:199], v[120:123]
	v_mfma_f32_16x16x32_bf16 v[112:115], v[168:171], v[204:207], v[112:115]
	v_mfma_f32_16x16x32_bf16 v[116:119], v[160:163], v[204:207], v[116:119]
	v_mfma_f32_16x16x32_bf16 v[100:103], v[160:163], v[212:215], v[100:103]
	v_mfma_f32_16x16x32_bf16 v[96:99], v[168:171], v[212:215], v[96:99]
	v_mfma_f32_16x16x32_bf16 v[80:83], v[168:171], v[220:223], v[80:83]
	v_mfma_f32_16x16x32_bf16 v[84:87], v[160:163], v[220:223], v[84:87]
	s_setprio 0
	s_setprio 1
	v_mfma_f32_16x16x32_bf16 v[108:111], v[172:175], v[192:195], v[108:111]
	v_mfma_f32_16x16x32_bf16 v[104:107], v[184:187], v[192:195], v[104:107]
	v_mfma_f32_16x16x32_bf16 v[88:91], v[184:187], v[200:203], v[88:91]
	v_mfma_f32_16x16x32_bf16 v[92:95], v[172:175], v[200:203], v[92:95]
	v_mfma_f32_16x16x32_bf16 v[76:79], v[172:175], v[208:211], v[76:79]
	v_mfma_f32_16x16x32_bf16 v[72:75], v[184:187], v[208:211], v[72:75]
	v_mfma_f32_16x16x32_bf16 v[64:67], v[184:187], v[216:219], v[64:67]
	v_mfma_f32_16x16x32_bf16 v[68:71], v[172:175], v[216:219], v[68:71]
	v_mfma_f32_16x16x32_bf16 v[108:111], v[180:183], v[196:199], v[108:111]
	v_mfma_f32_16x16x32_bf16 v[104:107], v[188:191], v[196:199], v[104:107]
	v_mfma_f32_16x16x32_bf16 v[88:91], v[188:191], v[204:207], v[88:91]
	v_mfma_f32_16x16x32_bf16 v[92:95], v[180:183], v[204:207], v[92:95]
	v_mfma_f32_16x16x32_bf16 v[76:79], v[180:183], v[212:215], v[76:79]
	v_mfma_f32_16x16x32_bf16 v[72:75], v[188:191], v[212:215], v[72:75]
	v_mfma_f32_16x16x32_bf16 v[64:67], v[188:191], v[220:223], v[64:67]
	v_mfma_f32_16x16x32_bf16 v[68:71], v[180:183], v[220:223], v[68:71]
	s_setprio 0
	s_barrier
; #define PG8_STAGE(bufoff, gbase, voff) do { _Pragma("unroll") for (int _i = 0; _i < 2; ++_i) \
;         __builtin_amdgcn_global_load_lds((const unsigned*)((const char*)(gbase) + (voff)[_i]), (LAS unsigned*)(lds + (bufoff) + ldsw + _i * 8192), 16, 0, 0); } while (0)
; #define PG8_LDA(dst, b, h) do { _Pragma("unroll") for (int m = 0; m < 4; ++m) _Pragma("unroll") for (int k = 0; k < 2; ++k) dst[m][k] = *(const LAS bf16x8*)(lds + PG8_SA(b, h) + aoff + m * 2048 + k * 1024); } while (0)
; #define PG8_MMA(ai, bj, At, Bt) do { __builtin_amdgcn_s_setprio(1); _Pragma("unroll") for (int m = 0; m < 4; ++m) _Pragma("unroll") for (int n = 0; n < 2; ++n) _Pragma("unroll") for (int k = 0; k < 2; ++k) \
;         acc[ai][bj][m][n] = __builtin_amdgcn_mfma_f32_16x16x32_bf16(Bt[n][k], At[m][k], acc[ai][bj][m][n], 0, 0, 0); __builtin_amdgcn_s_setprio(0); } while (0)
; #define PG8_WAIT_V(n) asm volatile("s_waitcnt vmcnt(" #n ")" ::: "memory")
; #define PG8_WAIT_L(n) asm volatile("s_waitcnt lgkmcnt(" #n ")" ::: "memory")
; #define PG8_BAR __builtin_amdgcn_s_barrier()
; #define PG8_SCHED __builtin_amdgcn_sched_barrier(0)
; template <class Epi, class Sched, bool ALIGN_EPI>
; __device__ __forceinline__ void gemm_phase(LAS unsigned char* lds, const int wid, const int lda_, const int ldb_, const int K_, const Sched& S, const Epi& E) {
;     ...
;             PG8_LDA(At, 1, 1); PG8_STAGE(PG8_SB(1, 0), b3, voffB); PG8_STAGE(PG8_SB(1, 1), b3 + hstepB, voffB); PG8_STAGE(PG8_SA(1, 0), a3, voffA);
;             PG8_WAIT_V(8); PG8_WAIT_L(0); PG8_BAR; PG8_MMA(1, 0, At, B0); PG8_MMA(1, 1, At, B1); PG8_BAR; PG8_SCHED;
;         }
;     __device__ __forceinline__ void out(const pg8::Unit& u, char*& o, int& ldo, int& kind) const { ldo = D;
;     ...
;         else { o = (char*)ws + WS_PART + (((size_t)u.kq * MCTX + (size_t)(u.pm - 64) * 256) * D + (size_t)u.pn * 256) * 2; kind = 0; } }
	s_add_i32 s17, s17, s3
	v_lshl_add_u64 v[224:225], v[224:225], 0, s[24:25]
	s_mov_b32 m0, s17
	ds_read_b128 v[192:195], v139 offset:49152
	ds_read_b128 v[196:199], v139 offset:50176
	ds_read_b128 v[200:203], v139 offset:51200
	ds_read_b128 v[204:207], v139 offset:52224
	ds_read_b128 v[208:211], v139 offset:53248
	ds_read_b128 v[212:215], v139 offset:54272
	ds_read_b128 v[216:219], v139 offset:55296
	ds_read_b128 v[220:223], v139 offset:56320
	global_load_lds_dwordx4 v[224:225], off
	v_lshl_add_u64 v[224:225], v[226:227], 0, s[24:25]
	s_add_i32 m0, s17, 0x2000
	s_add_i32 s17, s27, s3
	global_load_lds_dwordx4 v[224:225], off
	v_lshl_add_u64 v[224:225], v[228:229], 0, s[24:25]
	s_mov_b32 m0, s17
	s_nop 0
	global_load_lds_dwordx4 v[224:225], off
	v_lshl_add_u64 v[224:225], v[230:231], 0, s[24:25]
	s_add_i32 m0, s17, 0x2000
	s_nop 0
	global_load_lds_dwordx4 v[224:225], off
	v_lshl_add_u64 v[224:225], v[232:233], 0, s[24:25]
	s_mov_b32 m0, s72
	s_nop 0
	global_load_lds_dwordx4 v[224:225], off
	v_lshl_add_u64 v[224:225], v[234:235], 0, s[24:25]
	s_mov_b32 m0, s73
	s_nop 0
	global_load_lds_dwordx4 v[224:225], off
	s_waitcnt vmcnt(8)
	s_waitcnt lgkmcnt(0)
	s_barrier
	s_setprio 1
	s_waitcnt lgkmcnt(0)
	v_mfma_f32_16x16x32_bf16 v[60:63], v[156:159], v[192:195], v[60:63]
	v_mfma_f32_16x16x32_bf16 v[56:59], v[164:167], v[192:195], v[56:59]
	v_mfma_f32_16x16x32_bf16 v[48:51], v[164:167], v[200:203], v[48:51]
	v_mfma_f32_16x16x32_bf16 v[52:55], v[156:159], v[200:203], v[52:55]
	v_mfma_f32_16x16x32_bf16 v[36:39], v[156:159], v[208:211], v[36:39]
	v_mfma_f32_16x16x32_bf16 v[32:35], v[164:167], v[208:211], v[32:35]
	v_mfma_f32_16x16x32_bf16 v[16:19], v[164:167], v[216:219], v[16:19]
	v_mfma_f32_16x16x32_bf16 v[20:23], v[156:159], v[216:219], v[20:23]
	v_mfma_f32_16x16x32_bf16 v[60:63], v[160:163], v[196:199], v[60:63]
	v_mfma_f32_16x16x32_bf16 v[56:59], v[168:171], v[196:199], v[56:59]
	v_mfma_f32_16x16x32_bf16 v[48:51], v[168:171], v[204:207], v[48:51]
	v_mfma_f32_16x16x32_bf16 v[52:55], v[160:163], v[204:207], v[52:55]
	v_mfma_f32_16x16x32_bf16 v[36:39], v[160:163], v[212:215], v[36:39]
	v_mfma_f32_16x16x32_bf16 v[32:35], v[168:171], v[212:215], v[32:35]
	v_mfma_f32_16x16x32_bf16 v[16:19], v[168:171], v[220:223], v[16:19]
	v_mfma_f32_16x16x32_bf16 v[20:23], v[160:163], v[220:223], v[20:23]
	s_setprio 0
	s_setprio 1
	v_mfma_f32_16x16x32_bf16 v[44:47], v[172:175], v[192:195], v[44:47]
	v_mfma_f32_16x16x32_bf16 v[40:43], v[184:187], v[192:195], v[40:43]
	v_mfma_f32_16x16x32_bf16 v[24:27], v[184:187], v[200:203], v[24:27]
	v_mfma_f32_16x16x32_bf16 v[28:31], v[172:175], v[200:203], v[28:31]
	v_mfma_f32_16x16x32_bf16 v[12:15], v[172:175], v[208:211], v[12:15]
	v_mfma_f32_16x16x32_bf16 v[8:11], v[184:187], v[208:211], v[8:11]
	v_mfma_f32_16x16x32_bf16 v[0:3], v[184:187], v[216:219], v[0:3]
	v_mfma_f32_16x16x32_bf16 v[4:7], v[172:175], v[216:219], v[4:7]
	v_mfma_f32_16x16x32_bf16 v[44:47], v[180:183], v[196:199], v[44:47]
	v_mfma_f32_16x16x32_bf16 v[40:43], v[188:191], v[196:199], v[40:43]
	v_mfma_f32_16x16x32_bf16 v[24:27], v[188:191], v[204:207], v[24:27]
	v_mfma_f32_16x16x32_bf16 v[28:31], v[180:183], v[204:207], v[28:31]
	v_mfma_f32_16x16x32_bf16 v[12:15], v[180:183], v[212:215], v[12:15]
	v_mfma_f32_16x16x32_bf16 v[8:11], v[188:191], v[212:215], v[8:11]
	v_mfma_f32_16x16x32_bf16 v[0:3], v[188:191], v[220:223], v[0:3]
	v_mfma_f32_16x16x32_bf16 v[4:7], v[180:183], v[220:223], v[4:7]
	s_setprio 0
	s_barrier
	s_add_u32 s94, s94, 0x100
	s_addc_u32 s95, s95, 0
	s_add_u32 s49, s49, 0x100
	s_addc_u32 s76, s76, 0
	s_cmp_ge_u32 s78, s45
	s_mov_b32 s77, s78
	s_cbranch_scc0 .LBB0_962
	s_mov_b64 s[94:95], -1
	s_and_b64 vcc, exec, s[50:51]
	s_cbranch_vccz .LBB0_965
	s_mov_b32 s49, s92
	s_ashr_i32 s47, s46, 31
	s_ashr_i32 s45, s44, 31
	s_lshl_b64 s[4:5], s[46:47], 20
	s_lshl_b64 s[42:43], s[44:45], 9
	s_lshl_b64 s[48:49], s[48:49], 23
	v_readlane_b32 s50, v251, 28
	v_readlane_b32 s51, v251, 29
	s_add_u32 s17, s50, s42
	s_addc_u32 s27, s51, s43
	s_add_u32 s17, s17, s48
	s_addc_u32 s27, s27, s49
	s_add_u32 s4, s17, s4
	s_addc_u32 s5, s27, s5
	s_add_u32 s4, s4, 0xfc000000
	s_addc_u32 s5, s5, -1
	s_mov_b64 s[94:95], 0

; #define PG8_STAGE(bufoff, gbase, voff) do { _Pragma("unroll") for (int _i = 0; _i < 2; ++_i) \
;         __builtin_amdgcn_global_load_lds((const unsigned*)((const char*)(gbase) + (voff)[_i]), (LAS unsigned*)(lds + (bufoff) + ldsw + _i * 8192), 16, 0, 0); } while (0)
; #define PG8_LDA(dst, b, h) do { _Pragma("unroll") for (int m = 0; m < 4; ++m) _Pragma("unroll") for (int k = 0; k < 2; ++k) dst[m][k] = *(const LAS bf16x8*)(lds + PG8_SA(b, h) + aoff + m * 2048 + k * 1024); } while (0)
; #define PG8_LDB(dst, b, h) do { _Pragma("unroll") for (int n = 0; n < 2; ++n) _Pragma("unroll") for (int k = 0; k < 2; ++k) dst[n][k] = *(const LAS bf16x8*)(lds + PG8_SB(b, h) + boff + n * 2048 + k * 1024); } while (0)
; #define PG8_MMA(ai, bj, At, Bt) do { __builtin_amdgcn_s_setprio(1); _Pragma("unroll") for (int m = 0; m < 4; ++m) _Pragma("unroll") for (int n = 0; n < 2; ++n) _Pragma("unroll") for (int k = 0; k < 2; ++k) \
;         acc[ai][bj][m][n] = __builtin_amdgcn_mfma_f32_16x16x32_bf16(Bt[n][k], At[m][k], acc[ai][bj][m][n], 0, 0, 0); __builtin_amdgcn_s_setprio(0); } while (0)
; #define PG8_WAIT_V(n) asm volatile("s_waitcnt vmcnt(" #n ")" ::: "memory")
; #define PG8_WAIT_L(n) asm volatile("s_waitcnt lgkmcnt(" #n ")" ::: "memory")
; #define PG8_BAR __builtin_amdgcn_s_barrier()
; #define PG8_SCHED __builtin_amdgcn_sched_barrier(0)
; template <class Epi, class Sched, bool ALIGN_EPI>
; __device__ __forceinline__ void gemm_phase(LAS unsigned char* lds, const int wid, const int lda_, const int ldb_, const int K_, const Sched& S, const Epi& E) {
;     ...
;             PG8_LDB(B0, 0, 0); PG8_LDB(B1, 0, 1); PG8_SCHED; PG8_LDA(At, 0, 0); PG8_STAGE(PG8_SA(1, 1), a1 + hstepA, voffA);
;             PG8_WAIT_V(8); PG8_WAIT_L(0); PG8_BAR; PG8_MMA(0, 0, At, B0); PG8_MMA(0, 1, At, B1); PG8_BAR; PG8_SCHED;
;             PG8_LDA(At, 0, 1); PG8_STAGE(PG8_SB(0, 0), b2, voffB); PG8_STAGE(PG8_SB(0, 1), b2 + hstepB, voffB); PG8_STAGE(PG8_SA(0, 0), a2, voffA);
;             PG8_WAIT_V(8); PG8_WAIT_L(0); PG8_BAR; PG8_MMA(1, 0, At, B0); PG8_MMA(1, 1, At, B1); PG8_BAR; PG8_SCHED;
.LBB0_1120:
	s_add_u32 s17, s40, s50
	s_addc_u32 s27, s41, s51
	s_add_u32 s17, s17, 0x100
	s_addc_u32 s27, s27, 0
	s_add_u32 s79, s76, s50
	s_addc_u32 s80, s77, s51
	s_add_i32 s86, 0, 0x10000
	s_cmpk_eq_i32 s50, 0xf00
	s_cselect_b32 s95, s4, s27
	s_cselect_b32 s94, s5, s17
	v_add_u32_e32 v141, s86, v135
	s_cselect_b32 s81, s43, s80
	s_cselect_b32 s80, s45, s79
	s_add_i32 s17, 0, 0x14000
	ds_read_b128 v[160:163], v141
	ds_read_b128 v[164:167], v141 offset:1024
	ds_read_b128 v[168:171], v141 offset:2048
	ds_read_b128 v[172:175], v141 offset:3072
	v_add_u32_e32 v141, s17, v135
	ds_read_b128 v[180:183], v141
	ds_read_b128 v[184:187], v141 offset:1024
	ds_read_b128 v[188:191], v141 offset:2048
	ds_read_b128 v[192:195], v141 offset:3072
	v_lshl_add_u64 v[228:229], v[158:159], 0, s[50:51]
	s_add_i32 m0, s16, 0xc000
	ds_read_b128 v[196:199], v139
	ds_read_b128 v[200:203], v139 offset:1024
	ds_read_b128 v[204:207], v139 offset:2048
	ds_read_b128 v[208:211], v139 offset:3072
	ds_read_b128 v[212:215], v139 offset:4096
	ds_read_b128 v[216:219], v139 offset:5120
	ds_read_b128 v[220:223], v139 offset:6144
	ds_read_b128 v[224:227], v139 offset:7168
	global_load_lds_dwordx4 v[228:229], off
	v_lshl_add_u64 v[228:229], v[156:157], 0, s[50:51]
	s_add_i32 m0, s16, 0xe000
	s_nop 0
	global_load_lds_dwordx4 v[228:229], off
	s_waitcnt vmcnt(8)
	s_waitcnt lgkmcnt(0)
	s_barrier
	s_setprio 1
	s_waitcnt lgkmcnt(0)
	v_mfma_f32_16x16x32_bf16 v[124:127], v[160:163], v[196:199], v[124:127]
	v_mfma_f32_16x16x32_bf16 v[120:123], v[168:171], v[196:199], v[120:123]
	v_mfma_f32_16x16x32_bf16 v[112:115], v[168:171], v[204:207], v[112:115]
	v_mfma_f32_16x16x32_bf16 v[116:119], v[160:163], v[204:207], v[116:119]
	v_mfma_f32_16x16x32_bf16 v[100:103], v[160:163], v[212:215], v[100:103]
	v_mfma_f32_16x16x32_bf16 v[96:99], v[168:171], v[212:215], v[96:99]
	v_mfma_f32_16x16x32_bf16 v[80:83], v[168:171], v[220:223], v[80:83]
	v_mfma_f32_16x16x32_bf16 v[84:87], v[160:163], v[220:223], v[84:87]
	v_mfma_f32_16x16x32_bf16 v[124:127], v[164:167], v[200:203], v[124:127]
	v_mfma_f32_16x16x32_bf16 v[120:123], v[172:175], v[200:203], v[120:123]
	v_mfma_f32_16x16x32_bf16 v[112:115], v[172:175], v[208:211], v[112:115]
	v_mfma_f32_16x16x32_bf16 v[116:119], v[164:167], v[208:211], v[116:119]
	v_mfma_f32_16x16x32_bf16 v[100:103], v[164:167], v[216:219], v[100:103]
	v_mfma_f32_16x16x32_bf16 v[96:99], v[172:175], v[216:219], v[96:99]
	v_mfma_f32_16x16x32_bf16 v[80:83], v[172:175], v[224:227], v[80:83]
	v_mfma_f32_16x16x32_bf16 v[84:87], v[164:167], v[224:227], v[84:87]
	s_setprio 0
	s_setprio 1
	v_mfma_f32_16x16x32_bf16 v[108:111], v[180:183], v[196:199], v[108:111]
	v_mfma_f32_16x16x32_bf16 v[104:107], v[188:191], v[196:199], v[104:107]
	v_mfma_f32_16x16x32_bf16 v[88:91], v[188:191], v[204:207], v[88:91]
	v_mfma_f32_16x16x32_bf16 v[92:95], v[180:183], v[204:207], v[92:95]
	v_mfma_f32_16x16x32_bf16 v[76:79], v[180:183], v[212:215], v[76:79]
	v_mfma_f32_16x16x32_bf16 v[72:75], v[188:191], v[212:215], v[72:75]
	v_mfma_f32_16x16x32_bf16 v[64:67], v[188:191], v[220:223], v[64:67]
	v_mfma_f32_16x16x32_bf16 v[68:71], v[180:183], v[220:223], v[68:71]
	v_mfma_f32_16x16x32_bf16 v[108:111], v[184:187], v[200:203], v[108:111]
	v_mfma_f32_16x16x32_bf16 v[104:107], v[192:195], v[200:203], v[104:107]
	v_mfma_f32_16x16x32_bf16 v[88:91], v[192:195], v[208:211], v[88:91]
	v_mfma_f32_16x16x32_bf16 v[92:95], v[184:187], v[208:211], v[92:95]
	v_mfma_f32_16x16x32_bf16 v[76:79], v[184:187], v[216:219], v[76:79]
	v_mfma_f32_16x16x32_bf16 v[72:75], v[192:195], v[216:219], v[72:75]
	v_mfma_f32_16x16x32_bf16 v[64:67], v[192:195], v[224:227], v[64:67]
	v_mfma_f32_16x16x32_bf16 v[68:71], v[184:187], v[224:227], v[68:71]
	s_setprio 0
	s_barrier
	s_add_i32 s27, s86, s3
	v_lshl_add_u64 v[228:229], s[80:81], 0, v[176:177]
	s_mov_b32 m0, s27
	ds_read_b128 v[196:199], v139 offset:16384
	ds_read_b128 v[200:203], v139 offset:17408
	ds_read_b128 v[204:207], v139 offset:18432
	ds_read_b128 v[208:211], v139 offset:19456
	ds_read_b128 v[212:215], v139 offset:20480
	ds_read_b128 v[216:219], v139 offset:21504
	ds_read_b128 v[220:223], v139 offset:22528
	ds_read_b128 v[224:227], v139 offset:23552
	global_load_lds_dwordx4 v[228:229], off
	s_add_i32 m0, s27, 0x2000
	v_lshl_add_u64 v[230:231], s[80:81], 0, v[128:129]
	s_add_u32 s80, s80, s30
	s_addc_u32 s81, s81, s31
	s_add_i32 s17, s17, s3
	global_load_lds_dwordx4 v[230:231], off
	v_lshl_add_u64 v[232:233], s[80:81], 0, v[176:177]
	s_mov_b32 m0, s17
	v_lshl_add_u64 v[234:235], s[80:81], 0, v[128:129]
	global_load_lds_dwordx4 v[232:233], off
	s_add_i32 m0, s17, 0x2000
	v_lshl_add_u64 v[236:237], s[94:95], 0, v[132:133]
	global_load_lds_dwordx4 v[234:235], off
	s_mov_b32 m0, s16
	v_lshl_add_u64 v[246:247], s[94:95], 0, v[130:131]
	global_load_lds_dwordx4 v[236:237], off
	s_mov_b32 m0, s35
	s_nop 0
	global_load_lds_dwordx4 v[246:247], off
	s_waitcnt vmcnt(8)
	s_waitcnt lgkmcnt(0)
	s_barrier
; #define PG8_STAGE(bufoff, gbase, voff) do { _Pragma("unroll") for (int _i = 0; _i < 2; ++_i) \
;         __builtin_amdgcn_global_load_lds((const unsigned*)((const char*)(gbase) + (voff)[_i]), (LAS unsigned*)(lds + (bufoff) + ldsw + _i * 8192), 16, 0, 0); } while (0)
; #define PG8_LDA(dst, b, h) do { _Pragma("unroll") for (int m = 0; m < 4; ++m) _Pragma("unroll") for (int k = 0; k < 2; ++k) dst[m][k] = *(const LAS bf16x8*)(lds + PG8_SA(b, h) + aoff + m * 2048 + k * 1024); } while (0)
; #define PG8_LDB(dst, b, h) do { _Pragma("unroll") for (int n = 0; n < 2; ++n) _Pragma("unroll") for (int k = 0; k < 2; ++k) dst[n][k] = *(const LAS bf16x8*)(lds + PG8_SB(b, h) + boff + n * 2048 + k * 1024); } while (0)
; #define PG8_MMA(ai, bj, At, Bt) do { __builtin_amdgcn_s_setprio(1); _Pragma("unroll") for (int m = 0; m < 4; ++m) _Pragma("unroll") for (int n = 0; n < 2; ++n) _Pragma("unroll") for (int k = 0; k < 2; ++k) \
;         acc[ai][bj][m][n] = __builtin_amdgcn_mfma_f32_16x16x32_bf16(Bt[n][k], At[m][k], acc[ai][bj][m][n], 0, 0, 0); __builtin_amdgcn_s_setprio(0); } while (0)
; #define PG8_WAIT_V(n) asm volatile("s_waitcnt vmcnt(" #n ")" ::: "memory")
; #define PG8_WAIT_L(n) asm volatile("s_waitcnt lgkmcnt(" #n ")" ::: "memory")
; #define PG8_BAR __builtin_amdgcn_s_barrier()
; #define PG8_SCHED __builtin_amdgcn_sched_barrier(0)
; template <class Epi, class Sched, bool ALIGN_EPI>
; __device__ __forceinline__ void gemm_phase(LAS unsigned char* lds, const int wid, const int lda_, const int ldb_, const int K_, const Sched& S, const Epi& E) {
;     ...
;             PG8_WAIT_V(8); PG8_WAIT_L(0); PG8_BAR; PG8_MMA(1, 0, At, B0); PG8_MMA(1, 1, At, B1); PG8_BAR; PG8_SCHED;
;             PG8_LDB(B0, 1, 0); PG8_LDB(B1, 1, 1); PG8_SCHED; PG8_LDA(At, 1, 0); PG8_STAGE(PG8_SA(0, 1), a2 + hstepA, voffA);
;             PG8_WAIT_V(8); PG8_WAIT_L(0); PG8_BAR; PG8_MMA(0, 0, At, B0); PG8_MMA(0, 1, At, B1); PG8_BAR; PG8_SCHED;
	s_setprio 1
	s_waitcnt lgkmcnt(0)
	v_mfma_f32_16x16x32_bf16 v[60:63], v[160:163], v[196:199], v[60:63]
	v_mfma_f32_16x16x32_bf16 v[56:59], v[168:171], v[196:199], v[56:59]
	v_mfma_f32_16x16x32_bf16 v[48:51], v[168:171], v[204:207], v[48:51]
	v_mfma_f32_16x16x32_bf16 v[52:55], v[160:163], v[204:207], v[52:55]
	v_mfma_f32_16x16x32_bf16 v[36:39], v[160:163], v[212:215], v[36:39]
	v_mfma_f32_16x16x32_bf16 v[32:35], v[168:171], v[212:215], v[32:35]
	v_mfma_f32_16x16x32_bf16 v[16:19], v[168:171], v[220:223], v[16:19]
	v_mfma_f32_16x16x32_bf16 v[20:23], v[160:163], v[220:223], v[20:23]
	v_mfma_f32_16x16x32_bf16 v[60:63], v[164:167], v[200:203], v[60:63]
	v_mfma_f32_16x16x32_bf16 v[56:59], v[172:175], v[200:203], v[56:59]
	v_mfma_f32_16x16x32_bf16 v[48:51], v[172:175], v[208:211], v[48:51]
	v_mfma_f32_16x16x32_bf16 v[52:55], v[164:167], v[208:211], v[52:55]
	v_mfma_f32_16x16x32_bf16 v[36:39], v[164:167], v[216:219], v[36:39]
	v_mfma_f32_16x16x32_bf16 v[32:35], v[172:175], v[216:219], v[32:35]
	v_mfma_f32_16x16x32_bf16 v[16:19], v[172:175], v[224:227], v[16:19]
	v_mfma_f32_16x16x32_bf16 v[20:23], v[164:167], v[224:227], v[20:23]
	s_setprio 0
	s_setprio 1
	v_mfma_f32_16x16x32_bf16 v[44:47], v[180:183], v[196:199], v[44:47]
	v_mfma_f32_16x16x32_bf16 v[40:43], v[188:191], v[196:199], v[40:43]
	v_mfma_f32_16x16x32_bf16 v[24:27], v[188:191], v[204:207], v[24:27]
	v_mfma_f32_16x16x32_bf16 v[28:31], v[180:183], v[204:207], v[28:31]
	v_mfma_f32_16x16x32_bf16 v[12:15], v[180:183], v[212:215], v[12:15]
	v_mfma_f32_16x16x32_bf16 v[8:11], v[188:191], v[212:215], v[8:11]
	v_mfma_f32_16x16x32_bf16 v[0:3], v[188:191], v[220:223], v[0:3]
	v_mfma_f32_16x16x32_bf16 v[4:7], v[180:183], v[220:223], v[4:7]
	v_mfma_f32_16x16x32_bf16 v[44:47], v[184:187], v[200:203], v[44:47]
	v_mfma_f32_16x16x32_bf16 v[40:43], v[192:195], v[200:203], v[40:43]
	v_mfma_f32_16x16x32_bf16 v[24:27], v[192:195], v[208:211], v[24:27]
	v_mfma_f32_16x16x32_bf16 v[28:31], v[184:187], v[208:211], v[28:31]
	v_mfma_f32_16x16x32_bf16 v[12:15], v[184:187], v[216:219], v[12:15]
	v_mfma_f32_16x16x32_bf16 v[8:11], v[192:195], v[216:219], v[8:11]
	v_mfma_f32_16x16x32_bf16 v[0:3], v[192:195], v[224:227], v[0:3]
	v_mfma_f32_16x16x32_bf16 v[4:7], v[184:187], v[224:227], v[4:7]
	s_setprio 0
	s_barrier
	s_add_i32 s17, 0, 0x18000
	v_add_u32_e32 v141, s17, v135
	s_add_i32 s27, 0, 0x1c000
	ds_read_b128 v[160:163], v141
	ds_read_b128 v[164:167], v141 offset:1024
	ds_read_b128 v[168:171], v141 offset:2048
	ds_read_b128 v[172:175], v141 offset:3072
	v_add_u32_e32 v141, s27, v135
	ds_read_b128 v[180:183], v141
	ds_read_b128 v[184:187], v141 offset:1024
	ds_read_b128 v[188:191], v141 offset:2048
	ds_read_b128 v[192:195], v141 offset:3072
	s_add_u32 s80, s94, s10
	s_addc_u32 s81, s95, s11
	s_mov_b32 m0, s39
	v_lshl_add_u64 v[248:249], s[80:81], 0, v[132:133]
	ds_read_b128 v[196:199], v139 offset:32768
	ds_read_b128 v[200:203], v139 offset:33792
	ds_read_b128 v[204:207], v139 offset:34816
	ds_read_b128 v[208:211], v139 offset:35840
	ds_read_b128 v[212:215], v139 offset:36864
	ds_read_b128 v[216:219], v139 offset:37888
	ds_read_b128 v[220:223], v139 offset:38912
	ds_read_b128 v[224:227], v139 offset:39936
	global_load_lds_dwordx4 v[248:249], off
	v_lshl_add_u64 v[248:249], s[80:81], 0, v[130:131]
	s_mov_b32 m0, s72
	s_nop 0
	global_load_lds_dwordx4 v[248:249], off
	s_waitcnt vmcnt(8)
	s_waitcnt lgkmcnt(0)
	s_barrier
	s_setprio 1
	s_waitcnt lgkmcnt(0)
	v_mfma_f32_16x16x32_bf16 v[124:127], v[160:163], v[196:199], v[124:127]
	v_mfma_f32_16x16x32_bf16 v[120:123], v[168:171], v[196:199], v[120:123]
	v_mfma_f32_16x16x32_bf16 v[112:115], v[168:171], v[204:207], v[112:115]
	v_mfma_f32_16x16x32_bf16 v[116:119], v[160:163], v[204:207], v[116:119]
	v_mfma_f32_16x16x32_bf16 v[100:103], v[160:163], v[212:215], v[100:103]
	v_mfma_f32_16x16x32_bf16 v[96:99], v[168:171], v[212:215], v[96:99]
	v_mfma_f32_16x16x32_bf16 v[80:83], v[168:171], v[220:223], v[80:83]
	v_mfma_f32_16x16x32_bf16 v[84:87], v[160:163], v[220:223], v[84:87]
	v_mfma_f32_16x16x32_bf16 v[124:127], v[164:167], v[200:203], v[124:127]
	v_mfma_f32_16x16x32_bf16 v[120:123], v[172:175], v[200:203], v[120:123]
	v_mfma_f32_16x16x32_bf16 v[112:115], v[172:175], v[208:211], v[112:115]
	v_mfma_f32_16x16x32_bf16 v[116:119], v[164:167], v[208:211], v[116:119]
	v_mfma_f32_16x16x32_bf16 v[100:103], v[164:167], v[216:219], v[100:103]
	v_mfma_f32_16x16x32_bf16 v[96:99], v[172:175], v[216:219], v[96:99]
	v_mfma_f32_16x16x32_bf16 v[80:83], v[172:175], v[224:227], v[80:83]
	v_mfma_f32_16x16x32_bf16 v[84:87], v[164:167], v[224:227], v[84:87]
	s_setprio 0
	s_setprio 1
	v_mfma_f32_16x16x32_bf16 v[108:111], v[180:183], v[196:199], v[108:111]
	v_mfma_f32_16x16x32_bf16 v[104:107], v[188:191], v[196:199], v[104:107]
	v_mfma_f32_16x16x32_bf16 v[88:91], v[188:191], v[204:207], v[88:91]
	v_mfma_f32_16x16x32_bf16 v[92:95], v[180:183], v[204:207], v[92:95]
	v_mfma_f32_16x16x32_bf16 v[76:79], v[180:183], v[212:215], v[76:79]
	v_mfma_f32_16x16x32_bf16 v[72:75], v[188:191], v[212:215], v[72:75]
	v_mfma_f32_16x16x32_bf16 v[64:67], v[188:191], v[220:223], v[64:67]
	v_mfma_f32_16x16x32_bf16 v[68:71], v[180:183], v[220:223], v[68:71]
	v_mfma_f32_16x16x32_bf16 v[108:111], v[184:187], v[200:203], v[108:111]
	v_mfma_f32_16x16x32_bf16 v[104:107], v[192:195], v[200:203], v[104:107]
	v_mfma_f32_16x16x32_bf16 v[88:91], v[192:195], v[208:211], v[88:91]
	v_mfma_f32_16x16x32_bf16 v[92:95], v[184:187], v[208:211], v[92:95]
	v_mfma_f32_16x16x32_bf16 v[76:79], v[184:187], v[216:219], v[76:79]
	v_mfma_f32_16x16x32_bf16 v[72:75], v[192:195], v[216:219], v[72:75]
	v_mfma_f32_16x16x32_bf16 v[64:67], v[192:195], v[224:227], v[64:67]
	v_mfma_f32_16x16x32_bf16 v[68:71], v[184:187], v[224:227], v[68:71]
	s_setprio 0
	s_barrier
; #define PG8_STAGE(bufoff, gbase, voff) do { _Pragma("unroll") for (int _i = 0; _i < 2; ++_i) \
;         __builtin_amdgcn_global_load_lds((const unsigned*)((const char*)(gbase) + (voff)[_i]), (LAS unsigned*)(lds + (bufoff) + ldsw + _i * 8192), 16, 0, 0); } while (0)
; #define PG8_LDA(dst, b, h) do { _Pragma("unroll") for (int m = 0; m < 4; ++m) _Pragma("unroll") for (int k = 0; k < 2; ++k) dst[m][k] = *(const LAS bf16x8*)(lds + PG8_SA(b, h) + aoff + m * 2048 + k * 1024); } while (0)
; #define PG8_MMA(ai, bj, At, Bt) do { __builtin_amdgcn_s_setprio(1); _Pragma("unroll") for (int m = 0; m < 4; ++m) _Pragma("unroll") for (int n = 0; n < 2; ++n) _Pragma("unroll") for (int k = 0; k < 2; ++k) \
;         acc[ai][bj][m][n] = __builtin_amdgcn_mfma_f32_16x16x32_bf16(Bt[n][k], At[m][k], acc[ai][bj][m][n], 0, 0, 0); __builtin_amdgcn_s_setprio(0); } while (0)
; #define PG8_WAIT_V(n) asm volatile("s_waitcnt vmcnt(" #n ")" ::: "memory")
; #define PG8_WAIT_L(n) asm volatile("s_waitcnt lgkmcnt(" #n ")" ::: "memory")
; #define PG8_BAR __builtin_amdgcn_s_barrier()
; #define PG8_SCHED __builtin_amdgcn_sched_barrier(0)
; template <class Epi, class Sched, bool ALIGN_EPI>
; __device__ __forceinline__ void gemm_phase(LAS unsigned char* lds, const int wid, const int lda_, const int ldb_, const int K_, const Sched& S, const Epi& E) {
;     ...
;             PG8_LDA(At, 1, 1); PG8_STAGE(PG8_SB(1, 0), b3, voffB); PG8_STAGE(PG8_SB(1, 1), b3 + hstepB, voffB); PG8_STAGE(PG8_SA(1, 0), a3, voffA);
;             PG8_WAIT_V(8); PG8_WAIT_L(0); PG8_BAR; PG8_MMA(1, 0, At, B0); PG8_MMA(1, 1, At, B1); PG8_BAR; PG8_SCHED;
;         }
	s_add_i32 s17, s17, s3
	v_lshl_add_u64 v[228:229], v[228:229], 0, s[24:25]
	s_mov_b32 m0, s17
	ds_read_b128 v[196:199], v139 offset:49152
	ds_read_b128 v[200:203], v139 offset:50176
	ds_read_b128 v[204:207], v139 offset:51200
	ds_read_b128 v[208:211], v139 offset:52224
	ds_read_b128 v[212:215], v139 offset:53248
	ds_read_b128 v[216:219], v139 offset:54272
	ds_read_b128 v[220:223], v139 offset:55296
	ds_read_b128 v[224:227], v139 offset:56320
	global_load_lds_dwordx4 v[228:229], off
	v_lshl_add_u64 v[228:229], v[230:231], 0, s[24:25]
	s_add_i32 m0, s17, 0x2000
	s_add_i32 s17, s27, s3
	global_load_lds_dwordx4 v[228:229], off
	v_lshl_add_u64 v[228:229], v[232:233], 0, s[24:25]
	s_mov_b32 m0, s17
	s_nop 0
	global_load_lds_dwordx4 v[228:229], off
	v_lshl_add_u64 v[228:229], v[234:235], 0, s[24:25]
	s_add_i32 m0, s17, 0x2000
	s_nop 0
	global_load_lds_dwordx4 v[228:229], off
	v_lshl_add_u64 v[228:229], v[236:237], 0, s[24:25]
	s_mov_b32 m0, s73
	s_nop 0
	global_load_lds_dwordx4 v[228:229], off
	v_lshl_add_u64 v[228:229], v[246:247], 0, s[24:25]
	s_mov_b32 m0, s74
	s_nop 0
	global_load_lds_dwordx4 v[228:229], off
	s_waitcnt vmcnt(8)
	s_waitcnt lgkmcnt(0)
	s_barrier
	s_setprio 1
	s_waitcnt lgkmcnt(0)
	v_mfma_f32_16x16x32_bf16 v[60:63], v[160:163], v[196:199], v[60:63]
	v_mfma_f32_16x16x32_bf16 v[56:59], v[168:171], v[196:199], v[56:59]
	v_mfma_f32_16x16x32_bf16 v[48:51], v[168:171], v[204:207], v[48:51]
	v_mfma_f32_16x16x32_bf16 v[52:55], v[160:163], v[204:207], v[52:55]
	v_mfma_f32_16x16x32_bf16 v[36:39], v[160:163], v[212:215], v[36:39]
	v_mfma_f32_16x16x32_bf16 v[32:35], v[168:171], v[212:215], v[32:35]
	v_mfma_f32_16x16x32_bf16 v[16:19], v[168:171], v[220:223], v[16:19]
	v_mfma_f32_16x16x32_bf16 v[20:23], v[160:163], v[220:223], v[20:23]
	v_mfma_f32_16x16x32_bf16 v[60:63], v[164:167], v[200:203], v[60:63]
	v_mfma_f32_16x16x32_bf16 v[56:59], v[172:175], v[200:203], v[56:59]
	v_mfma_f32_16x16x32_bf16 v[48:51], v[172:175], v[208:211], v[48:51]
	v_mfma_f32_16x16x32_bf16 v[52:55], v[164:167], v[208:211], v[52:55]
	v_mfma_f32_16x16x32_bf16 v[36:39], v[164:167], v[216:219], v[36:39]
	v_mfma_f32_16x16x32_bf16 v[32:35], v[172:175], v[216:219], v[32:35]
	v_mfma_f32_16x16x32_bf16 v[16:19], v[172:175], v[224:227], v[16:19]
	v_mfma_f32_16x16x32_bf16 v[20:23], v[164:167], v[224:227], v[20:23]
	s_setprio 0
	s_setprio 1
	v_mfma_f32_16x16x32_bf16 v[44:47], v[180:183], v[196:199], v[44:47]
	v_mfma_f32_16x16x32_bf16 v[40:43], v[188:191], v[196:199], v[40:43]
	v_mfma_f32_16x16x32_bf16 v[24:27], v[188:191], v[204:207], v[24:27]
	v_mfma_f32_16x16x32_bf16 v[28:31], v[180:183], v[204:207], v[28:31]
	v_mfma_f32_16x16x32_bf16 v[12:15], v[180:183], v[212:215], v[12:15]
	v_mfma_f32_16x16x32_bf16 v[8:11], v[188:191], v[212:215], v[8:11]
	v_mfma_f32_16x16x32_bf16 v[0:3], v[188:191], v[220:223], v[0:3]
	v_mfma_f32_16x16x32_bf16 v[4:7], v[180:183], v[220:223], v[4:7]
	v_mfma_f32_16x16x32_bf16 v[44:47], v[184:187], v[200:203], v[44:47]
	v_mfma_f32_16x16x32_bf16 v[40:43], v[192:195], v[200:203], v[40:43]
	v_mfma_f32_16x16x32_bf16 v[24:27], v[192:195], v[208:211], v[24:27]
	v_mfma_f32_16x16x32_bf16 v[28:31], v[184:187], v[208:211], v[28:31]
	v_mfma_f32_16x16x32_bf16 v[12:15], v[184:187], v[216:219], v[12:15]
	v_mfma_f32_16x16x32_bf16 v[8:11], v[192:195], v[216:219], v[8:11]
	v_mfma_f32_16x16x32_bf16 v[0:3], v[192:195], v[224:227], v[0:3]
	v_mfma_f32_16x16x32_bf16 v[4:7], v[184:187], v[224:227], v[4:7]
	s_setprio 0
	s_barrier
	s_add_i32 s78, s78, 2
	s_add_u32 s50, s50, 0x100
	s_addc_u32 s51, s51, 0
	s_cmp_gt_u32 s78, 29
	s_cbranch_scc0 .LBB0_1120
; __device__ __forceinline__ unsigned cvt_pk_bf16(float lo, float hi) { const f32x2 v = {lo, hi}; return __builtin_bit_cast(unsigned, __builtin_convertvector(v, bf16x2_t)); }
;     template <class Sched> __device__ __forceinline__ void operator()(const f32x4 (&acc)[2][2][4][2], const Unit& u, const Sched& S, int wr, int wc, int fr, int fq) const {
;     ...
;         if (kind == 0) {
;             bf16_t* base = (bf16_t*)uo;
; #pragma unroll
;             for (int ai = 0; ai < 2; ++ai)
; #pragma unroll
;                 for (int m = 0; m < 4; ++m) { bf16_t* rowp = base + (size_t)(rl0 + ai * HALF + m * 16) * ldo + cl0;
; #pragma unroll
;                     for (int bj = 0; bj < 2; ++bj) { const f32x4 v0 = acc[ai][bj][m][0], v1 = acc[ai][bj][m][1];
;                         u32x4 w; w.x = cvt_pk_bf16(v0[0], v0[1]); w.y = cvt_pk_bf16(v0[2], v0[3]); w.z = cvt_pk_bf16(v1[0], v1[1]); w.w = cvt_pk_bf16(v1[2], v1[3]);
;                         *(u32x4*)(rowp + bj * HALF) = w; } }
	s_sub_i32 s4, s38, 22
	s_ashr_i32 s5, s38, 31
	s_cmp_lt_i32 s38, 22
	s_cselect_b32 s5, s5, 0
	s_cselect_b32 s4, s38, s4
	s_mov_b32 s17, 0x2bc00000
	s_cselect_b32 s17, 0x1f600000, s17
	s_lshl_b64 s[4:5], s[4:5], 9
	s_add_u32 s4, s66, s4
	s_addc_u32 s5, s67, s5
	s_add_u32 s4, s4, s17
	s_addc_u32 s5, s5, 0
	s_mul_i32 s27, s34, 0x2c0000
	s_mul_hi_i32 s17, s34, 0x2c0000
	s_add_u32 s4, s4, s27
	s_addc_u32 s5, s5, s17
	s_movk_i32 s17, 0x1600
	v_lshl_add_u64 v[156:157], v[136:137], 1, s[4:5]
	v_mad_i64_i32 v[158:159], s[4:5], s17, v134, 0
	v_lshl_add_u64 v[158:159], v[158:159], 1, v[156:157]
	v_cvt_pk_bf16_f32 v108, v108, v109
	v_cvt_pk_bf16_f32 v109, v110, v111
	v_cvt_pk_bf16_f32 v110, v104, v105
	v_cvt_pk_bf16_f32 v111, v106, v107
	v_mad_i64_i32 v[104:105], s[4:5], s17, v138, 0
	v_cvt_pk_bf16_f32 v124, v124, v125
	v_cvt_pk_bf16_f32 v125, v126, v127
	v_cvt_pk_bf16_f32 v126, v120, v121
	v_cvt_pk_bf16_f32 v127, v122, v123
	global_store_dwordx4 v[158:159], v[108:111], off offset:256
	v_cvt_pk_bf16_f32 v92, v92, v93
	v_cvt_pk_bf16_f32 v93, v94, v95
	v_lshl_add_u64 v[108:109], v[104:105], 1, v[156:157]
	v_cvt_pk_bf16_f32 v94, v88, v89
	v_cvt_pk_bf16_f32 v95, v90, v91
	v_mad_i64_i32 v[88:89], s[4:5], s17, v140, 0
	global_store_dwordx4 v[158:159], v[124:127], off
	v_cvt_pk_bf16_f32 v104, v116, v117
	v_cvt_pk_bf16_f32 v105, v118, v119
	v_cvt_pk_bf16_f32 v106, v112, v113
	v_cvt_pk_bf16_f32 v107, v114, v115
	global_store_dwordx4 v[108:109], v[92:95], off offset:256
	v_cvt_pk_bf16_f32 v76, v76, v77
	v_cvt_pk_bf16_f32 v77, v78, v79
	v_lshl_add_u64 v[92:93], v[88:89], 1, v[156:157]
	v_cvt_pk_bf16_f32 v78, v72, v73
	v_cvt_pk_bf16_f32 v79, v74, v75
	v_mad_i64_i32 v[72:73], s[4:5], s17, v142, 0
	v_cvt_pk_bf16_f32 v68, v68, v69
	v_cvt_pk_bf16_f32 v69, v70, v71
	v_cvt_pk_bf16_f32 v70, v64, v65
	v_mad_i64_i32 v[64:65], s[4:5], s17, v144, 0
	global_store_dwordx4 v[108:109], v[104:107], off
	v_cvt_pk_bf16_f32 v88, v100, v101
	v_cvt_pk_bf16_f32 v89, v102, v103
	v_cvt_pk_bf16_f32 v90, v96, v97
	v_cvt_pk_bf16_f32 v91, v98, v99
	global_store_dwordx4 v[92:93], v[76:79], off offset:256
	v_cvt_pk_bf16_f32 v74, v80, v81
	v_cvt_pk_bf16_f32 v75, v82, v83
	v_lshl_add_u64 v[76:77], v[72:73], 1, v[156:157]
	v_cvt_pk_bf16_f32 v72, v84, v85
	v_cvt_pk_bf16_f32 v73, v86, v87
	v_cvt_pk_bf16_f32 v71, v66, v67
	v_lshl_add_u64 v[64:65], v[64:65], 1, v[156:157]
	v_cvt_pk_bf16_f32 v44, v44, v45
	v_cvt_pk_bf16_f32 v45, v46, v47
	v_cvt_pk_bf16_f32 v46, v40, v41
	v_cvt_pk_bf16_f32 v47, v42, v43
	v_mad_i64_i32 v[40:41], s[4:5], s17, v146, 0
	global_store_dwordx4 v[92:93], v[88:91], off
	global_store_dwordx4 v[76:77], v[72:75], off
	global_store_dwordx4 v[76:77], v[68:71], off offset:256
	v_cvt_pk_bf16_f32 v60, v60, v61
	v_cvt_pk_bf16_f32 v61, v62, v63
	v_cvt_pk_bf16_f32 v62, v56, v57
	v_cvt_pk_bf16_f32 v63, v58, v59
	global_store_dwordx4 v[64:65], v[44:47], off offset:256
	v_cvt_pk_bf16_f32 v28, v28, v29
	v_cvt_pk_bf16_f32 v29, v30, v31
	v_lshl_add_u64 v[44:45], v[40:41], 1, v[156:157]
	v_cvt_pk_bf16_f32 v30, v24, v25
	v_cvt_pk_bf16_f32 v31, v26, v27
	v_mad_i64_i32 v[24:25], s[4:5], s17, v148, 0
	global_store_dwordx4 v[64:65], v[60:63], off
	v_cvt_pk_bf16_f32 v40, v52, v53
	v_cvt_pk_bf16_f32 v41, v54, v55
	v_cvt_pk_bf16_f32 v42, v48, v49
	v_cvt_pk_bf16_f32 v43, v50, v51
	global_store_dwordx4 v[44:45], v[28:31], off offset:256
	v_cvt_pk_bf16_f32 v12, v12, v13
	v_cvt_pk_bf16_f32 v13, v14, v15
	v_lshl_add_u64 v[28:29], v[24:25], 1, v[156:157]
	v_cvt_pk_bf16_f32 v14, v8, v9
	v_cvt_pk_bf16_f32 v15, v10, v11
	v_mad_i64_i32 v[8:9], s[4:5], s17, v150, 0
	global_store_dwordx4 v[44:45], v[40:43], off
	v_cvt_pk_bf16_f32 v24, v36, v37
	v_cvt_pk_bf16_f32 v25, v38, v39
	v_cvt_pk_bf16_f32 v26, v32, v33
	v_cvt_pk_bf16_f32 v27, v34, v35
	global_store_dwordx4 v[28:29], v[12:15], off offset:256
	v_cvt_pk_bf16_f32 v10, v16, v17
	v_cvt_pk_bf16_f32 v11, v18, v19
	v_lshl_add_u64 v[12:13], v[8:9], 1, v[156:157]
	v_cvt_pk_bf16_f32 v8, v20, v21
	v_cvt_pk_bf16_f32 v9, v22, v23
	v_cvt_pk_bf16_f32 v4, v4, v5
	v_cvt_pk_bf16_f32 v5, v6, v7
	v_cvt_pk_bf16_f32 v6, v0, v1
	v_cvt_pk_bf16_f32 v7, v2, v3
	s_and_b64 vcc, exec, s[36:37]
	s_mov_b32 s38, s42
	s_mov_b32 s34, s44
	s_mov_b64 s[50:51], s[48:49]
	s_mov_b64 s[40:41], s[46:47]
	global_store_dwordx4 v[28:29], v[24:27], off
	global_store_dwordx4 v[12:13], v[8:11], off
	global_store_dwordx4 v[12:13], v[4:7], off offset:256
	s_cbranch_vccz .LBB0_1117
	v_readlane_b32 s4, v253, 1
	s_waitcnt vmcnt(0)
	v_readlane_b32 s5, v253, 2
	s_andn2_b64 vcc, exec, s[4:5]
	s_cbranch_vccnz .LBB0_1124
	s_barrier

; #define PG8_STAGE(bufoff, gbase, voff) do { _Pragma("unroll") for (int _i = 0; _i < 2; ++_i) \
;         __builtin_amdgcn_global_load_lds((const unsigned*)((const char*)(gbase) + (voff)[_i]), (LAS unsigned*)(lds + (bufoff) + ldsw + _i * 8192), 16, 0, 0); } while (0)
; #define PG8_LDA(dst, b, h) do { _Pragma("unroll") for (int m = 0; m < 4; ++m) _Pragma("unroll") for (int k = 0; k < 2; ++k) dst[m][k] = *(const LAS bf16x8*)(lds + PG8_SA(b, h) + aoff + m * 2048 + k * 1024); } while (0)
; #define PG8_LDB(dst, b, h) do { _Pragma("unroll") for (int n = 0; n < 2; ++n) _Pragma("unroll") for (int k = 0; k < 2; ++k) dst[n][k] = *(const LAS bf16x8*)(lds + PG8_SB(b, h) + boff + n * 2048 + k * 1024); } while (0)
; #define PG8_MMA(ai, bj, At, Bt) do { __builtin_amdgcn_s_setprio(1); _Pragma("unroll") for (int m = 0; m < 4; ++m) _Pragma("unroll") for (int n = 0; n < 2; ++n) _Pragma("unroll") for (int k = 0; k < 2; ++k) \
;         acc[ai][bj][m][n] = __builtin_amdgcn_mfma_f32_16x16x32_bf16(Bt[n][k], At[m][k], acc[ai][bj][m][n], 0, 0, 0); __builtin_amdgcn_s_setprio(0); } while (0)
; #define PG8_WAIT_V(n) asm volatile("s_waitcnt vmcnt(" #n ")" ::: "memory")
; #define PG8_WAIT_L(n) asm volatile("s_waitcnt lgkmcnt(" #n ")" ::: "memory")
; #define PG8_BAR __builtin_amdgcn_s_barrier()
; #define PG8_SCHED __builtin_amdgcn_sched_barrier(0)
; template <class Epi, class Sched, bool ALIGN_EPI>
; __device__ __forceinline__ void gemm_phase(LAS unsigned char* lds, const int wid, const int lda_, const int ldb_, const int K_, const Sched& S, const Epi& E) {
;     ...
;             PG8_LDB(B0, 0, 0); PG8_LDB(B1, 0, 1); PG8_SCHED; PG8_LDA(At, 0, 0); PG8_STAGE(PG8_SA(1, 1), a1 + hstepA, voffA);
;             PG8_WAIT_V(8); PG8_WAIT_L(0); PG8_BAR; PG8_MMA(0, 0, At, B0); PG8_MMA(0, 1, At, B1); PG8_BAR; PG8_SCHED;
;             PG8_LDA(At, 0, 1); PG8_STAGE(PG8_SB(0, 0), b2, voffB); PG8_STAGE(PG8_SB(0, 1), b2 + hstepB, voffB); PG8_STAGE(PG8_SA(0, 0), a2, voffA);
;             PG8_WAIT_V(8); PG8_WAIT_L(0); PG8_BAR; PG8_MMA(1, 0, At, B0); PG8_MMA(1, 1, At, B1); PG8_BAR; PG8_SCHED;
.LBB0_1341:
	s_add_i32 s76, s39, 2
	s_add_u32 s17, s46, 0x80
	s_addc_u32 s27, s47, 0
	s_add_i32 s77, 0, 0x10000
	s_cmp_eq_u32 s5, s39
	s_cselect_b32 s49, s43, s27
	s_cselect_b32 s48, s42, s17
	v_add_u32_e32 v141, s77, v135
	s_cselect_b32 s79, s37, s35
	s_cselect_b32 s78, s36, s31
	s_add_i32 s17, 0, 0x14000
	ds_read_b128 v[156:159], v141
	ds_read_b128 v[160:163], v141 offset:1024
	ds_read_b128 v[164:167], v141 offset:2048
	ds_read_b128 v[168:171], v141 offset:3072
	v_add_u32_e32 v141, s17, v135
	ds_read_b128 v[172:175], v141
	ds_read_b128 v[180:183], v141 offset:1024
	ds_read_b128 v[184:187], v141 offset:2048
	ds_read_b128 v[188:191], v141 offset:3072
	v_lshl_add_u64 v[224:225], s[46:47], 0, v[152:153]
	s_add_i32 m0, s16, 0xc000
	ds_read_b128 v[192:195], v139
	ds_read_b128 v[196:199], v139 offset:1024
	ds_read_b128 v[200:203], v139 offset:2048
	ds_read_b128 v[204:207], v139 offset:3072
	ds_read_b128 v[208:211], v139 offset:4096
	ds_read_b128 v[212:215], v139 offset:5120
	ds_read_b128 v[216:219], v139 offset:6144
	ds_read_b128 v[220:223], v139 offset:7168
	global_load_lds_dwordx4 v[224:225], off
	v_lshl_add_u64 v[224:225], s[46:47], 0, v[154:155]
	s_add_i32 m0, s16, 0xe000
	s_nop 0
	global_load_lds_dwordx4 v[224:225], off
	s_waitcnt vmcnt(8)
	s_waitcnt lgkmcnt(0)
	s_barrier
	s_setprio 1
	s_waitcnt lgkmcnt(0)
	v_mfma_f32_16x16x32_bf16 v[124:127], v[156:159], v[192:195], v[124:127]
	v_mfma_f32_16x16x32_bf16 v[120:123], v[164:167], v[192:195], v[120:123]
	v_mfma_f32_16x16x32_bf16 v[112:115], v[164:167], v[200:203], v[112:115]
	v_mfma_f32_16x16x32_bf16 v[116:119], v[156:159], v[200:203], v[116:119]
	v_mfma_f32_16x16x32_bf16 v[100:103], v[156:159], v[208:211], v[100:103]
	v_mfma_f32_16x16x32_bf16 v[96:99], v[164:167], v[208:211], v[96:99]
	v_mfma_f32_16x16x32_bf16 v[80:83], v[164:167], v[216:219], v[80:83]
	v_mfma_f32_16x16x32_bf16 v[84:87], v[156:159], v[216:219], v[84:87]
	v_mfma_f32_16x16x32_bf16 v[124:127], v[160:163], v[196:199], v[124:127]
	v_mfma_f32_16x16x32_bf16 v[120:123], v[168:171], v[196:199], v[120:123]
	v_mfma_f32_16x16x32_bf16 v[112:115], v[168:171], v[204:207], v[112:115]
	v_mfma_f32_16x16x32_bf16 v[116:119], v[160:163], v[204:207], v[116:119]
	v_mfma_f32_16x16x32_bf16 v[100:103], v[160:163], v[212:215], v[100:103]
	v_mfma_f32_16x16x32_bf16 v[96:99], v[168:171], v[212:215], v[96:99]
	v_mfma_f32_16x16x32_bf16 v[80:83], v[168:171], v[220:223], v[80:83]
	v_mfma_f32_16x16x32_bf16 v[84:87], v[160:163], v[220:223], v[84:87]
	s_setprio 0
	s_setprio 1
	v_mfma_f32_16x16x32_bf16 v[108:111], v[172:175], v[192:195], v[108:111]
	v_mfma_f32_16x16x32_bf16 v[104:107], v[184:187], v[192:195], v[104:107]
	v_mfma_f32_16x16x32_bf16 v[88:91], v[184:187], v[200:203], v[88:91]
	v_mfma_f32_16x16x32_bf16 v[92:95], v[172:175], v[200:203], v[92:95]
	v_mfma_f32_16x16x32_bf16 v[76:79], v[172:175], v[208:211], v[76:79]
	v_mfma_f32_16x16x32_bf16 v[72:75], v[184:187], v[208:211], v[72:75]
	v_mfma_f32_16x16x32_bf16 v[64:67], v[184:187], v[216:219], v[64:67]
	v_mfma_f32_16x16x32_bf16 v[68:71], v[172:175], v[216:219], v[68:71]
	v_mfma_f32_16x16x32_bf16 v[108:111], v[180:183], v[196:199], v[108:111]
	v_mfma_f32_16x16x32_bf16 v[104:107], v[188:191], v[196:199], v[104:107]
	v_mfma_f32_16x16x32_bf16 v[88:91], v[188:191], v[204:207], v[88:91]
	v_mfma_f32_16x16x32_bf16 v[92:95], v[180:183], v[204:207], v[92:95]
	v_mfma_f32_16x16x32_bf16 v[76:79], v[180:183], v[212:215], v[76:79]
	v_mfma_f32_16x16x32_bf16 v[72:75], v[188:191], v[212:215], v[72:75]
	v_mfma_f32_16x16x32_bf16 v[64:67], v[188:191], v[220:223], v[64:67]
	v_mfma_f32_16x16x32_bf16 v[68:71], v[180:183], v[220:223], v[68:71]
	s_setprio 0
	s_barrier
	s_add_i32 s27, s77, s3
	v_lshl_add_u64 v[224:225], s[78:79], 0, v[176:177]
	s_mov_b32 m0, s27
	ds_read_b128 v[192:195], v139 offset:16384
	ds_read_b128 v[196:199], v139 offset:17408
	ds_read_b128 v[200:203], v139 offset:18432
	ds_read_b128 v[204:207], v139 offset:19456
	ds_read_b128 v[208:211], v139 offset:20480
	ds_read_b128 v[212:215], v139 offset:21504
	ds_read_b128 v[216:219], v139 offset:22528
	ds_read_b128 v[220:223], v139 offset:23552
	global_load_lds_dwordx4 v[224:225], off
	s_add_i32 m0, s27, 0x2000
	v_lshl_add_u64 v[226:227], s[78:79], 0, v[132:133]
	s_add_u32 s78, s78, s10
	s_addc_u32 s79, s79, s11
	s_add_i32 s17, s17, s3
	global_load_lds_dwordx4 v[226:227], off
	v_lshl_add_u64 v[228:229], s[78:79], 0, v[176:177]
	s_mov_b32 m0, s17
	v_lshl_add_u64 v[230:231], s[78:79], 0, v[132:133]
	global_load_lds_dwordx4 v[228:229], off
	s_add_i32 m0, s17, 0x2000
	v_lshl_add_u64 v[232:233], s[48:49], 0, v[128:129]
	global_load_lds_dwordx4 v[230:231], off
	s_mov_b32 m0, s16
	v_lshl_add_u64 v[234:235], s[48:49], 0, v[130:131]
	global_load_lds_dwordx4 v[232:233], off
	s_mov_b32 m0, s14
	s_nop 0
	global_load_lds_dwordx4 v[234:235], off
	s_waitcnt vmcnt(8)
	s_waitcnt lgkmcnt(0)
	s_barrier
; #define PG8_STAGE(bufoff, gbase, voff) do { _Pragma("unroll") for (int _i = 0; _i < 2; ++_i) \
;         __builtin_amdgcn_global_load_lds((const unsigned*)((const char*)(gbase) + (voff)[_i]), (LAS unsigned*)(lds + (bufoff) + ldsw + _i * 8192), 16, 0, 0); } while (0)
; #define PG8_LDA(dst, b, h) do { _Pragma("unroll") for (int m = 0; m < 4; ++m) _Pragma("unroll") for (int k = 0; k < 2; ++k) dst[m][k] = *(const LAS bf16x8*)(lds + PG8_SA(b, h) + aoff + m * 2048 + k * 1024); } while (0)
; #define PG8_LDB(dst, b, h) do { _Pragma("unroll") for (int n = 0; n < 2; ++n) _Pragma("unroll") for (int k = 0; k < 2; ++k) dst[n][k] = *(const LAS bf16x8*)(lds + PG8_SB(b, h) + boff + n * 2048 + k * 1024); } while (0)
; #define PG8_MMA(ai, bj, At, Bt) do { __builtin_amdgcn_s_setprio(1); _Pragma("unroll") for (int m = 0; m < 4; ++m) _Pragma("unroll") for (int n = 0; n < 2; ++n) _Pragma("unroll") for (int k = 0; k < 2; ++k) \
;         acc[ai][bj][m][n] = __builtin_amdgcn_mfma_f32_16x16x32_bf16(Bt[n][k], At[m][k], acc[ai][bj][m][n], 0, 0, 0); __builtin_amdgcn_s_setprio(0); } while (0)
; #define PG8_WAIT_V(n) asm volatile("s_waitcnt vmcnt(" #n ")" ::: "memory")
; #define PG8_WAIT_L(n) asm volatile("s_waitcnt lgkmcnt(" #n ")" ::: "memory")
; #define PG8_BAR __builtin_amdgcn_s_barrier()
; #define PG8_SCHED __builtin_amdgcn_sched_barrier(0)
; template <class Epi, class Sched, bool ALIGN_EPI>
; __device__ __forceinline__ void gemm_phase(LAS unsigned char* lds, const int wid, const int lda_, const int ldb_, const int K_, const Sched& S, const Epi& E) {
;     ...
;             PG8_WAIT_V(8); PG8_WAIT_L(0); PG8_BAR; PG8_MMA(1, 0, At, B0); PG8_MMA(1, 1, At, B1); PG8_BAR; PG8_SCHED;
;             PG8_LDB(B0, 1, 0); PG8_LDB(B1, 1, 1); PG8_SCHED; PG8_LDA(At, 1, 0); PG8_STAGE(PG8_SA(0, 1), a2 + hstepA, voffA);
;             PG8_WAIT_V(8); PG8_WAIT_L(0); PG8_BAR; PG8_MMA(0, 0, At, B0); PG8_MMA(0, 1, At, B1); PG8_BAR; PG8_SCHED;
	s_setprio 1
	s_waitcnt lgkmcnt(0)
	v_mfma_f32_16x16x32_bf16 v[60:63], v[156:159], v[192:195], v[60:63]
	v_mfma_f32_16x16x32_bf16 v[56:59], v[164:167], v[192:195], v[56:59]
	v_mfma_f32_16x16x32_bf16 v[48:51], v[164:167], v[200:203], v[48:51]
	v_mfma_f32_16x16x32_bf16 v[52:55], v[156:159], v[200:203], v[52:55]
	v_mfma_f32_16x16x32_bf16 v[36:39], v[156:159], v[208:211], v[36:39]
	v_mfma_f32_16x16x32_bf16 v[32:35], v[164:167], v[208:211], v[32:35]
	v_mfma_f32_16x16x32_bf16 v[16:19], v[164:167], v[216:219], v[16:19]
	v_mfma_f32_16x16x32_bf16 v[20:23], v[156:159], v[216:219], v[20:23]
	v_mfma_f32_16x16x32_bf16 v[60:63], v[160:163], v[196:199], v[60:63]
	v_mfma_f32_16x16x32_bf16 v[56:59], v[168:171], v[196:199], v[56:59]
	v_mfma_f32_16x16x32_bf16 v[48:51], v[168:171], v[204:207], v[48:51]
	v_mfma_f32_16x16x32_bf16 v[52:55], v[160:163], v[204:207], v[52:55]
	v_mfma_f32_16x16x32_bf16 v[36:39], v[160:163], v[212:215], v[36:39]
	v_mfma_f32_16x16x32_bf16 v[32:35], v[168:171], v[212:215], v[32:35]
	v_mfma_f32_16x16x32_bf16 v[16:19], v[168:171], v[220:223], v[16:19]
	v_mfma_f32_16x16x32_bf16 v[20:23], v[160:163], v[220:223], v[20:23]
	s_setprio 0
	s_setprio 1
	v_mfma_f32_16x16x32_bf16 v[44:47], v[172:175], v[192:195], v[44:47]
	v_mfma_f32_16x16x32_bf16 v[40:43], v[184:187], v[192:195], v[40:43]
	v_mfma_f32_16x16x32_bf16 v[24:27], v[184:187], v[200:203], v[24:27]
	v_mfma_f32_16x16x32_bf16 v[28:31], v[172:175], v[200:203], v[28:31]
	v_mfma_f32_16x16x32_bf16 v[12:15], v[172:175], v[208:211], v[12:15]
	v_mfma_f32_16x16x32_bf16 v[8:11], v[184:187], v[208:211], v[8:11]
	v_mfma_f32_16x16x32_bf16 v[0:3], v[184:187], v[216:219], v[0:3]
	v_mfma_f32_16x16x32_bf16 v[4:7], v[172:175], v[216:219], v[4:7]
	v_mfma_f32_16x16x32_bf16 v[44:47], v[180:183], v[196:199], v[44:47]
	v_mfma_f32_16x16x32_bf16 v[40:43], v[188:191], v[196:199], v[40:43]
	v_mfma_f32_16x16x32_bf16 v[24:27], v[188:191], v[204:207], v[24:27]
	v_mfma_f32_16x16x32_bf16 v[28:31], v[180:183], v[204:207], v[28:31]
	v_mfma_f32_16x16x32_bf16 v[12:15], v[180:183], v[212:215], v[12:15]
	v_mfma_f32_16x16x32_bf16 v[8:11], v[188:191], v[212:215], v[8:11]
	v_mfma_f32_16x16x32_bf16 v[0:3], v[188:191], v[220:223], v[0:3]
	v_mfma_f32_16x16x32_bf16 v[4:7], v[180:183], v[220:223], v[4:7]
	s_setprio 0
	s_barrier
	s_add_i32 s17, 0, 0x18000
	v_add_u32_e32 v141, s17, v135
	s_add_i32 s27, 0, 0x1c000
	ds_read_b128 v[156:159], v141
	ds_read_b128 v[160:163], v141 offset:1024
	ds_read_b128 v[164:167], v141 offset:2048
	ds_read_b128 v[168:171], v141 offset:3072
	v_add_u32_e32 v141, s27, v135
	ds_read_b128 v[172:175], v141
	ds_read_b128 v[180:183], v141 offset:1024
	ds_read_b128 v[184:187], v141 offset:2048
	ds_read_b128 v[188:191], v141 offset:3072
	s_add_u32 s48, s48, s0
	s_addc_u32 s49, s49, s1
	s_mov_b32 m0, s15
	v_lshl_add_u64 v[236:237], s[48:49], 0, v[128:129]
	ds_read_b128 v[192:195], v139 offset:32768
	ds_read_b128 v[196:199], v139 offset:33792
	ds_read_b128 v[200:203], v139 offset:34816
	ds_read_b128 v[204:207], v139 offset:35840
	ds_read_b128 v[208:211], v139 offset:36864
	ds_read_b128 v[212:215], v139 offset:37888
	ds_read_b128 v[216:219], v139 offset:38912
	ds_read_b128 v[220:223], v139 offset:39936
	global_load_lds_dwordx4 v[236:237], off
	v_lshl_add_u64 v[236:237], s[48:49], 0, v[130:131]
	s_mov_b32 m0, s26
	s_nop 0
	global_load_lds_dwordx4 v[236:237], off
	s_waitcnt vmcnt(8)
	s_waitcnt lgkmcnt(0)
	s_barrier
	s_setprio 1
	s_waitcnt lgkmcnt(0)
	v_mfma_f32_16x16x32_bf16 v[124:127], v[156:159], v[192:195], v[124:127]
	v_mfma_f32_16x16x32_bf16 v[120:123], v[164:167], v[192:195], v[120:123]
	v_mfma_f32_16x16x32_bf16 v[112:115], v[164:167], v[200:203], v[112:115]
	v_mfma_f32_16x16x32_bf16 v[116:119], v[156:159], v[200:203], v[116:119]
	v_mfma_f32_16x16x32_bf16 v[100:103], v[156:159], v[208:211], v[100:103]
	v_mfma_f32_16x16x32_bf16 v[96:99], v[164:167], v[208:211], v[96:99]
	v_mfma_f32_16x16x32_bf16 v[80:83], v[164:167], v[216:219], v[80:83]
	v_mfma_f32_16x16x32_bf16 v[84:87], v[156:159], v[216:219], v[84:87]
	v_mfma_f32_16x16x32_bf16 v[124:127], v[160:163], v[196:199], v[124:127]
	v_mfma_f32_16x16x32_bf16 v[120:123], v[168:171], v[196:199], v[120:123]
	v_mfma_f32_16x16x32_bf16 v[112:115], v[168:171], v[204:207], v[112:115]
	v_mfma_f32_16x16x32_bf16 v[116:119], v[160:163], v[204:207], v[116:119]
	v_mfma_f32_16x16x32_bf16 v[100:103], v[160:163], v[212:215], v[100:103]
	v_mfma_f32_16x16x32_bf16 v[96:99], v[168:171], v[212:215], v[96:99]
	v_mfma_f32_16x16x32_bf16 v[80:83], v[168:171], v[220:223], v[80:83]
	v_mfma_f32_16x16x32_bf16 v[84:87], v[160:163], v[220:223], v[84:87]
	s_setprio 0
	s_setprio 1
	v_mfma_f32_16x16x32_bf16 v[108:111], v[172:175], v[192:195], v[108:111]
	v_mfma_f32_16x16x32_bf16 v[104:107], v[184:187], v[192:195], v[104:107]
	v_mfma_f32_16x16x32_bf16 v[88:91], v[184:187], v[200:203], v[88:91]
	v_mfma_f32_16x16x32_bf16 v[92:95], v[172:175], v[200:203], v[92:95]
	v_mfma_f32_16x16x32_bf16 v[76:79], v[172:175], v[208:211], v[76:79]
	v_mfma_f32_16x16x32_bf16 v[72:75], v[184:187], v[208:211], v[72:75]
	v_mfma_f32_16x16x32_bf16 v[64:67], v[184:187], v[216:219], v[64:67]
	v_mfma_f32_16x16x32_bf16 v[68:71], v[172:175], v[216:219], v[68:71]
	v_mfma_f32_16x16x32_bf16 v[108:111], v[180:183], v[196:199], v[108:111]
	v_mfma_f32_16x16x32_bf16 v[104:107], v[188:191], v[196:199], v[104:107]
	v_mfma_f32_16x16x32_bf16 v[88:91], v[188:191], v[204:207], v[88:91]
	v_mfma_f32_16x16x32_bf16 v[92:95], v[180:183], v[204:207], v[92:95]
	v_mfma_f32_16x16x32_bf16 v[76:79], v[180:183], v[212:215], v[76:79]
	v_mfma_f32_16x16x32_bf16 v[72:75], v[188:191], v[212:215], v[72:75]
	v_mfma_f32_16x16x32_bf16 v[64:67], v[188:191], v[220:223], v[64:67]
	v_mfma_f32_16x16x32_bf16 v[68:71], v[180:183], v[220:223], v[68:71]
	s_setprio 0
	s_barrier
; #define PG8_STAGE(bufoff, gbase, voff) do { _Pragma("unroll") for (int _i = 0; _i < 2; ++_i) \
;         __builtin_amdgcn_global_load_lds((const unsigned*)((const char*)(gbase) + (voff)[_i]), (LAS unsigned*)(lds + (bufoff) + ldsw + _i * 8192), 16, 0, 0); } while (0)
; #define PG8_LDA(dst, b, h) do { _Pragma("unroll") for (int m = 0; m < 4; ++m) _Pragma("unroll") for (int k = 0; k < 2; ++k) dst[m][k] = *(const LAS bf16x8*)(lds + PG8_SA(b, h) + aoff + m * 2048 + k * 1024); } while (0)
; #define PG8_MMA(ai, bj, At, Bt) do { __builtin_amdgcn_s_setprio(1); _Pragma("unroll") for (int m = 0; m < 4; ++m) _Pragma("unroll") for (int n = 0; n < 2; ++n) _Pragma("unroll") for (int k = 0; k < 2; ++k) \
;         acc[ai][bj][m][n] = __builtin_amdgcn_mfma_f32_16x16x32_bf16(Bt[n][k], At[m][k], acc[ai][bj][m][n], 0, 0, 0); __builtin_amdgcn_s_setprio(0); } while (0)
; #define PG8_WAIT_V(n) asm volatile("s_waitcnt vmcnt(" #n ")" ::: "memory")
; #define PG8_WAIT_L(n) asm volatile("s_waitcnt lgkmcnt(" #n ")" ::: "memory")
; #define PG8_BAR __builtin_amdgcn_s_barrier()
; #define PG8_SCHED __builtin_amdgcn_sched_barrier(0)
; template <class Epi, class Sched, bool ALIGN_EPI>
; __device__ __forceinline__ void gemm_phase(LAS unsigned char* lds, const int wid, const int lda_, const int ldb_, const int K_, const Sched& S, const Epi& E) {
;     ...
;             PG8_LDA(At, 1, 1); PG8_STAGE(PG8_SB(1, 0), b3, voffB); PG8_STAGE(PG8_SB(1, 1), b3 + hstepB, voffB); PG8_STAGE(PG8_SA(1, 0), a3, voffA);
;             PG8_WAIT_V(8); PG8_WAIT_L(0); PG8_BAR; PG8_MMA(1, 0, At, B0); PG8_MMA(1, 1, At, B1); PG8_BAR; PG8_SCHED;
;         }
;     __device__ __forceinline__ void out(const pg8::Unit& u, char*& o, int& ldo, int& kind) const { ldo = D;
;     ...
;         else { o = (char*)ws + WS_PART + (((size_t)u.kq * MCTX + (size_t)(u.pm - 64) * 256) * D + (size_t)u.pn * 256) * 2; kind = 0; } }
	s_add_i32 s17, s17, s3
	v_lshl_add_u64 v[224:225], v[224:225], 0, s[24:25]
	s_mov_b32 m0, s17
	ds_read_b128 v[192:195], v139 offset:49152
	ds_read_b128 v[196:199], v139 offset:50176
	ds_read_b128 v[200:203], v139 offset:51200
	ds_read_b128 v[204:207], v139 offset:52224
	ds_read_b128 v[208:211], v139 offset:53248
	ds_read_b128 v[212:215], v139 offset:54272
	ds_read_b128 v[216:219], v139 offset:55296
	ds_read_b128 v[220:223], v139 offset:56320
	global_load_lds_dwordx4 v[224:225], off
	v_lshl_add_u64 v[224:225], v[226:227], 0, s[24:25]
	s_add_i32 m0, s17, 0x2000
	s_add_i32 s17, s27, s3
	global_load_lds_dwordx4 v[224:225], off
	v_lshl_add_u64 v[224:225], v[228:229], 0, s[24:25]
	s_mov_b32 m0, s17
	s_nop 0
	global_load_lds_dwordx4 v[224:225], off
	v_lshl_add_u64 v[224:225], v[230:231], 0, s[24:25]
	s_add_i32 m0, s17, 0x2000
	s_nop 0
	global_load_lds_dwordx4 v[224:225], off
	v_lshl_add_u64 v[224:225], v[232:233], 0, s[24:25]
	s_mov_b32 m0, s50
	s_nop 0
	global_load_lds_dwordx4 v[224:225], off
	v_lshl_add_u64 v[224:225], v[234:235], 0, s[24:25]
	s_mov_b32 m0, s51
	s_nop 0
	global_load_lds_dwordx4 v[224:225], off
	s_waitcnt vmcnt(8)
	s_waitcnt lgkmcnt(0)
	s_barrier
	s_setprio 1
	s_waitcnt lgkmcnt(0)
	v_mfma_f32_16x16x32_bf16 v[60:63], v[156:159], v[192:195], v[60:63]
	v_mfma_f32_16x16x32_bf16 v[56:59], v[164:167], v[192:195], v[56:59]
	v_mfma_f32_16x16x32_bf16 v[48:51], v[164:167], v[200:203], v[48:51]
	v_mfma_f32_16x16x32_bf16 v[52:55], v[156:159], v[200:203], v[52:55]
	v_mfma_f32_16x16x32_bf16 v[36:39], v[156:159], v[208:211], v[36:39]
	v_mfma_f32_16x16x32_bf16 v[32:35], v[164:167], v[208:211], v[32:35]
	v_mfma_f32_16x16x32_bf16 v[16:19], v[164:167], v[216:219], v[16:19]
	v_mfma_f32_16x16x32_bf16 v[20:23], v[156:159], v[216:219], v[20:23]
	v_mfma_f32_16x16x32_bf16 v[60:63], v[160:163], v[196:199], v[60:63]
	v_mfma_f32_16x16x32_bf16 v[56:59], v[168:171], v[196:199], v[56:59]
	v_mfma_f32_16x16x32_bf16 v[48:51], v[168:171], v[204:207], v[48:51]
	v_mfma_f32_16x16x32_bf16 v[52:55], v[160:163], v[204:207], v[52:55]
	v_mfma_f32_16x16x32_bf16 v[36:39], v[160:163], v[212:215], v[36:39]
	v_mfma_f32_16x16x32_bf16 v[32:35], v[168:171], v[212:215], v[32:35]
	v_mfma_f32_16x16x32_bf16 v[16:19], v[168:171], v[220:223], v[16:19]
	v_mfma_f32_16x16x32_bf16 v[20:23], v[160:163], v[220:223], v[20:23]
	s_setprio 0
	s_setprio 1
	v_mfma_f32_16x16x32_bf16 v[44:47], v[172:175], v[192:195], v[44:47]
	v_mfma_f32_16x16x32_bf16 v[40:43], v[184:187], v[192:195], v[40:43]
	v_mfma_f32_16x16x32_bf16 v[24:27], v[184:187], v[200:203], v[24:27]
	v_mfma_f32_16x16x32_bf16 v[28:31], v[172:175], v[200:203], v[28:31]
	v_mfma_f32_16x16x32_bf16 v[12:15], v[172:175], v[208:211], v[12:15]
	v_mfma_f32_16x16x32_bf16 v[8:11], v[184:187], v[208:211], v[8:11]
	v_mfma_f32_16x16x32_bf16 v[0:3], v[184:187], v[216:219], v[0:3]
	v_mfma_f32_16x16x32_bf16 v[4:7], v[172:175], v[216:219], v[4:7]
	v_mfma_f32_16x16x32_bf16 v[44:47], v[180:183], v[196:199], v[44:47]
	v_mfma_f32_16x16x32_bf16 v[40:43], v[188:191], v[196:199], v[40:43]
	v_mfma_f32_16x16x32_bf16 v[24:27], v[188:191], v[204:207], v[24:27]
	v_mfma_f32_16x16x32_bf16 v[28:31], v[180:183], v[204:207], v[28:31]
	v_mfma_f32_16x16x32_bf16 v[12:15], v[180:183], v[212:215], v[12:15]
	v_mfma_f32_16x16x32_bf16 v[8:11], v[188:191], v[212:215], v[8:11]
	v_mfma_f32_16x16x32_bf16 v[0:3], v[188:191], v[220:223], v[0:3]
	v_mfma_f32_16x16x32_bf16 v[4:7], v[180:183], v[220:223], v[4:7]
	s_setprio 0
	s_barrier
	s_add_u32 s46, s46, 0x100
	s_addc_u32 s47, s47, 0
	s_add_u32 s31, s31, 0x100
	s_addc_u32 s35, s35, 0
	s_cmp_ge_u32 s76, s4
	s_mov_b32 s39, s76
	s_cbranch_scc0 .LBB0_1341
	s_mov_b64 s[46:47], -1
	s_and_b64 vcc, exec, s[44:45]
	s_cbranch_vccz .LBB0_1344
	s_mov_b32 s39, s92
	s_ashr_i32 s31, s30, 31
	s_ashr_i32 s35, s34, 31
	s_lshl_b64 s[4:5], s[30:31], 20
	s_lshl_b64 s[44:45], s[34:35], 9
	s_lshl_b64 s[38:39], s[38:39], 23
	v_readlane_b32 s46, v251, 28
	v_readlane_b32 s47, v251, 29
	s_add_u32 s17, s46, s44
	s_addc_u32 s27, s47, s45
	s_add_u32 s17, s17, s38
	s_addc_u32 s27, s27, s39
	s_add_u32 s4, s17, s4
	s_addc_u32 s5, s27, s5
	s_add_u32 s4, s4, 0xfc000000
	s_addc_u32 s5, s5, -1
	s_mov_b64 s[46:47], 0
